# wt2_einv + DFT stage-1 and stage-2 output stores write-through (sc1): M1->M2 and M2->G2 seams
# speedup vs baseline: 1.0055x; 1.0010x over previous
.LBB0_488:
	s_add_i32 s0, s10, 0xfffff800
	s_lshr_b32 s0, s0, 9
	s_add_i32 s0, s0, 2
	s_ashr_i32 s1, s10, 10
	s_cmpk_lt_i32 s10, 0x800
	s_cselect_b32 s4, 0x7f, 63
	s_cselect_b32 s0, s1, s0
	s_lshr_b32 s1, s10, 3
	s_and_b32 s48, s4, s1
	s_cmp_lt_i32 s0, 2
	s_cselect_b64 s[14:15], -1, 0
	s_lshl_b32 s4, s0, 13
	s_lshl_b32 s0, s0, 12
	s_add_i32 s5, s0, 0x2000
	s_and_b64 s[0:1], s[14:15], exec
	s_cselect_b32 s0, s4, s5
	s_or_b32 s1, s0, s48
	s_mul_hi_i32 s4, s1, 0xc00
	s_mulk_i32 s1, 0xc00
	s_and_b32 s5, s11, 0x1c0
	s_add_u32 s1, s24, s1
	s_addc_u32 s4, s25, s4
	s_lshl_b32 s13, s5, 1
	v_mov_b32_e32 v42, v180
	s_add_u32 s20, s1, s13
	s_addc_u32 s21, s4, 0
	v_ashrrev_i32_e32 v181, 4, v42
	v_and_b32_e32 v94, 15, v42
	v_lshlrev_b32_e32 v156, 3, v181
	s_and_b64 s[14:15], s[14:15], exec
	v_lshlrev_b32_e32 v98, 3, v94
	s_cselect_b32 s12, 7, 6
	v_add_u32_e32 v170, 32, v156
	v_ashrrev_i32_e32 v157, 31, v156
	s_waitcnt vmcnt(0)
	v_or_b32_e32 v8, 1, v156
	v_add_u32_e32 v10, 33, v156
	v_lshl_add_u64 v[2:3], s[20:21], 0, v[98:99]
	v_lshlrev_b64 v[174:175], s12, v[156:157]
	v_ashrrev_i32_e32 v171, 31, v170
	v_ashrrev_i32_e32 v9, 31, v8
	v_ashrrev_i32_e32 v11, 31, v10
	v_mad_u64_u32 v[4:5], s[14:15], v174, s86, v[2:3]
	v_lshlrev_b64 v[172:173], s12, v[170:171]
	v_lshlrev_b64 v[176:177], s12, v[8:9]
	v_lshlrev_b64 v[10:11], s12, v[10:11]
	v_mad_i32_i24 v5, v175, s86, v5
	v_mad_u64_u32 v[6:7], s[14:15], v172, s86, v[2:3]
	v_mad_u64_u32 v[8:9], s[14:15], v176, s86, v[2:3]
	v_mad_u64_u32 v[12:13], s[14:15], v10, s86, v[2:3]
	v_mad_i32_i24 v7, v173, s86, v7
	v_mad_i32_i24 v9, v177, s86, v9
	v_mad_i32_i24 v13, v11, s86, v13
	global_load_dwordx2 v[18:19], v[4:5], off
	global_load_dwordx2 v[20:21], v[6:7], off
	global_load_dwordx2 v[22:23], v[8:9], off
	global_load_dwordx2 v[24:25], v[12:13], off
	v_or_b32_e32 v8, 3, v156
	v_ashrrev_i32_e32 v9, 31, v8
	v_lshlrev_b64 v[8:9], s12, v[8:9]
	v_mad_u64_u32 v[10:11], s[14:15], v8, s86, v[2:3]
	v_add_u32_e32 v8, 35, v156
	v_or_b32_e32 v4, 2, v156
	v_mad_i32_i24 v11, v9, s86, v11
	v_ashrrev_i32_e32 v9, 31, v8
	v_ashrrev_i32_e32 v5, 31, v4
	v_add_u32_e32 v166, 34, v156
	v_lshlrev_b64 v[8:9], s12, v[8:9]
	v_lshlrev_b64 v[4:5], s12, v[4:5]
	v_ashrrev_i32_e32 v167, 31, v166
	v_mad_u64_u32 v[12:13], s[14:15], v8, s86, v[2:3]
	v_or_b32_e32 v8, 5, v156
	v_mad_u64_u32 v[6:7], s[14:15], v4, s86, v[2:3]
	v_lshlrev_b64 v[168:169], s12, v[166:167]
	v_mad_i32_i24 v13, v9, s86, v13
	v_ashrrev_i32_e32 v9, 31, v8
	v_mad_i32_i24 v7, v5, s86, v7
	v_mad_u64_u32 v[4:5], s[14:15], v168, s86, v[2:3]
	v_lshlrev_b64 v[8:9], s12, v[8:9]
	v_mad_i32_i24 v5, v169, s86, v5
	global_load_dwordx2 v[30:31], v[6:7], off
	global_load_dwordx2 v[32:33], v[4:5], off
	global_load_dwordx2 v[34:35], v[10:11], off
	global_load_dwordx2 v[36:37], v[12:13], off
	v_or_b32_e32 v4, 4, v156
	v_mad_u64_u32 v[10:11], s[14:15], v8, s86, v[2:3]
	v_add_u32_e32 v8, 37, v156
	v_ashrrev_i32_e32 v5, 31, v4
	v_add_u32_e32 v162, 36, v156
	v_mad_i32_i24 v11, v9, s86, v11
	v_ashrrev_i32_e32 v9, 31, v8
	v_lshlrev_b64 v[4:5], s12, v[4:5]
	v_ashrrev_i32_e32 v163, 31, v162
	v_lshlrev_b64 v[8:9], s12, v[8:9]
	v_mad_u64_u32 v[6:7], s[14:15], v4, s86, v[2:3]
	v_lshlrev_b64 v[164:165], s12, v[162:163]
	v_mad_u64_u32 v[12:13], s[14:15], v8, s86, v[2:3]
	v_or_b32_e32 v8, 7, v156
	v_mad_i32_i24 v7, v5, s86, v7
	v_mad_u64_u32 v[4:5], s[14:15], v164, s86, v[2:3]
	v_mad_i32_i24 v13, v9, s86, v13
	v_ashrrev_i32_e32 v9, 31, v8
	v_mad_i32_i24 v5, v165, s86, v5
	global_load_dwordx2 v[50:51], v[6:7], off
	global_load_dwordx2 v[52:53], v[4:5], off
	global_load_dwordx2 v[58:59], v[10:11], off
	global_load_dwordx2 v[54:55], v[12:13], off
	v_or_b32_e32 v4, 6, v156
	v_lshlrev_b64 v[8:9], s12, v[8:9]
	v_ashrrev_i32_e32 v5, 31, v4
	v_add_u32_e32 v158, 38, v156
	v_mad_u64_u32 v[10:11], s[14:15], v8, s86, v[2:3]
	v_add_u32_e32 v8, 39, v156
	v_lshlrev_b64 v[4:5], s12, v[4:5]
	v_ashrrev_i32_e32 v159, 31, v158
	v_mad_i32_i24 v11, v9, s86, v11
	v_ashrrev_i32_e32 v9, 31, v8
	s_cselect_b32 s1, 0, 0x10000
	v_mad_u64_u32 v[6:7], s[14:15], v4, s86, v[2:3]
	v_lshlrev_b64 v[160:161], s12, v[158:159]
	v_lshlrev_b64 v[8:9], s12, v[8:9]
	s_add_u32 s1, s6, s1
	v_mad_i32_i24 v7, v5, s86, v7
	v_mad_u64_u32 v[4:5], s[14:15], v160, s86, v[2:3]
	v_mad_u64_u32 v[2:3], s[14:15], v8, s86, v[2:3]
	s_addc_u32 s4, s7, 0
	s_lshl_b32 s5, s48, 9
	s_add_u32 s14, s1, s5
	v_lshlrev_b32_e32 v178, 2, v181
	s_addc_u32 s15, s4, 0
	v_ashrrev_i32_e32 v179, 31, v178
	v_mad_i32_i24 v5, v161, s86, v5
	v_mad_i32_i24 v3, v9, s86, v3
	global_load_dwordx2 v[60:61], v[6:7], off
	global_load_dwordx2 v[56:57], v[4:5], off
	global_load_dwordx2 v[62:63], v[10:11], off
	global_load_dwordx2 v[64:65], v[2:3], off
	v_lshl_add_u64 v[6:7], v[178:179], 3, s[14:15]
	global_load_dwordx4 v[26:29], v[6:7], off offset:16
	global_load_dwordx4 v[38:41], v[6:7], off
	global_load_dwordx4 v[10:13], v[6:7], off offset:144
	global_load_dwordx4 v[14:17], v[6:7], off offset:128
	global_load_dwordx4 v[2:5], v[6:7], off offset:272
	s_nop 0
	global_load_dwordx4 v[6:9], v[6:7], off offset:256
	v_and_b32_e32 v42, -16, v42
	v_add_u32_e32 v157, 0, v42
	v_mad_u32_u24 v159, v94, s50, v157
	s_waitcnt vmcnt(18)
	v_perm_b32 v42, v24, v20, s87
	s_waitcnt vmcnt(10)
	v_perm_b32 v44, v54, v52, s87
	v_perm_b32 v46, v24, v20, s55
	v_perm_b32 v48, v54, v52, s55
	v_perm_b32 v74, v25, v21, s87
	v_perm_b32 v78, v25, v21, s55
	v_perm_b32 v54, v22, v18, s87
	v_perm_b32 v66, v22, v18, s55
	v_perm_b32 v70, v23, v19, s87
	v_perm_b32 v82, v23, v19, s55
	ds_read_b128 v[18:21], v159 offset:59392
	s_waitcnt vmcnt(6)
	v_perm_b32 v45, v64, v56, s87
	v_perm_b32 v49, v64, v56, s55
	v_perm_b32 v76, v55, v53, s87
	v_perm_b32 v77, v65, v57, s87
	v_perm_b32 v80, v55, v53, s55
	v_perm_b32 v81, v65, v57, s55
	v_perm_b32 v55, v34, v30, s87
	v_perm_b32 v56, v58, v50, s87
	v_perm_b32 v57, v62, v60, s87
	v_perm_b32 v67, v34, v30, s55
	v_perm_b32 v68, v58, v50, s55
	v_perm_b32 v69, v62, v60, s55
	v_perm_b32 v71, v35, v31, s87
	v_perm_b32 v72, v59, v51, s87
	v_perm_b32 v73, v63, v61, s87
	v_perm_b32 v83, v35, v31, s55
	v_perm_b32 v84, v59, v51, s55
	v_perm_b32 v85, v63, v61, s55
	ds_read_b128 v[58:61], v159 offset:64000
	s_waitcnt lgkmcnt(1)
	v_mfma_f32_16x16x32_bf16 v[86:89], v[18:21], v[54:57], 0
	v_add_u32_e32 v95, 0xe800, v157
	v_mad_u32_u24 v163, v94, s50, v248
	v_perm_b32 v43, v36, v32, s87
	v_mfma_f32_16x16x32_bf16 v[90:93], v[18:21], v[66:69], 0
	v_perm_b32 v47, v36, v32, s55
	v_perm_b32 v75, v37, v33, s87
	v_perm_b32 v79, v37, v33, s55
	v_mfma_f32_16x16x32_bf16 v[152:155], v[18:21], v[70:73], 0
	v_mad_u32_u24 v167, v94, s50, v228
	v_mad_u32_u24 v171, v94, s50, v196
	v_add_u32_e32 v157, 0xe840, v157
	v_mfma_f32_16x16x32_bf16 v[182:185], v[18:21], v[82:85], 0
	ds_read_b128 v[18:21], v159 offset:61696
	s_ashr_i32 s1, s0, 31
	s_lshl_b64 s[0:1], s[0:1], 11
	s_waitcnt lgkmcnt(0)
	v_mfma_f32_16x16x32_bf16 v[30:33], v[18:21], v[54:57], 0
	s_add_u32 s0, s16, s0
	s_addc_u32 s1, s17, s1
	s_add_u32 s0, s0, s13
	v_mfma_f32_16x16x32_bf16 v[34:37], v[18:21], v[66:69], 0
	s_addc_u32 s1, s1, 0
	v_cmp_gt_i32_e32 vcc, 9, v181
	v_mfma_f32_16x16x32_bf16 v[50:53], v[18:21], v[70:73], 0
	v_mfma_f32_16x16x32_bf16 v[148:151], v[18:21], v[82:85], 0
	v_mfma_f32_16x16x32_bf16 v[18:21], v[58:61], v[54:57], 0
	v_mfma_f32_16x16x32_bf16 v[22:25], v[58:61], v[66:69], 0
	v_mfma_f32_16x16x32_bf16 v[140:143], v[58:61], v[70:73], 0
	v_mfma_f32_16x16x32_bf16 v[144:147], v[58:61], v[82:85], 0
	v_add_u32_e32 v58, v95, v163
	ds_read_b128 v[58:61], v58
	s_waitcnt lgkmcnt(0)
	v_mfma_f32_16x16x32_bf16 v[62:65], v[58:61], v[54:57], 0
	v_mfma_f32_16x16x32_bf16 v[100:103], v[58:61], v[66:69], 0
	v_mfma_f32_16x16x32_bf16 v[104:107], v[58:61], v[70:73], 0
	v_mfma_f32_16x16x32_bf16 v[108:111], v[58:61], v[82:85], 0
	v_add_u32_e32 v58, v95, v167
	ds_read_b128 v[58:61], v58
	s_waitcnt lgkmcnt(0)
	v_mfma_f32_16x16x32_bf16 v[112:115], v[58:61], v[54:57], 0
	v_mfma_f32_16x16x32_bf16 v[128:131], v[58:61], v[66:69], 0
	v_mfma_f32_16x16x32_bf16 v[132:135], v[58:61], v[70:73], 0
	v_mfma_f32_16x16x32_bf16 v[136:139], v[58:61], v[82:85], 0
	v_add_u32_e32 v58, v95, v171
	ds_read_b128 v[94:97], v58
	s_waitcnt lgkmcnt(0)
	v_mfma_f32_16x16x32_bf16 v[58:61], v[94:97], v[54:57], 0
	ds_read_b128 v[54:57], v159 offset:59456
	v_mfma_f32_16x16x32_bf16 v[116:119], v[94:97], v[66:69], 0
	v_mfma_f32_16x16x32_bf16 v[120:123], v[94:97], v[70:73], 0
	v_mfma_f32_16x16x32_bf16 v[124:127], v[94:97], v[82:85], 0
	s_waitcnt lgkmcnt(0)
	v_mfma_f32_16x16x32_bf16 v[94:97], v[54:57], v[42:45], v[86:89]
	v_mfma_f32_16x16x32_bf16 v[86:89], v[54:57], v[74:77], v[152:155]
	s_nop 2
	ds_read_b128 v[152:155], v159 offset:61760
	v_mfma_f32_16x16x32_bf16 v[90:93], v[54:57], v[46:49], v[90:93]
	v_mfma_f32_16x16x32_bf16 v[82:85], v[54:57], v[78:81], v[182:185]
	s_waitcnt lgkmcnt(0)
	v_mfma_f32_16x16x32_bf16 v[54:57], v[152:155], v[74:77], v[50:53]
	v_mfma_f32_16x16x32_bf16 v[50:53], v[152:155], v[78:81], v[148:151]
	s_nop 2
	ds_read_b128 v[148:151], v159 offset:64064
	v_mfma_f32_16x16x32_bf16 v[70:73], v[152:155], v[42:45], v[30:33]
	s_waitcnt lgkmcnt(0)
	v_mfma_f32_16x16x32_bf16 v[30:33], v[148:151], v[46:49], v[22:25]
	v_mfma_f32_16x16x32_bf16 v[22:25], v[148:151], v[74:77], v[140:143]
	s_nop 2
	v_add_u32_e32 v140, v157, v163
	ds_read_b128 v[140:143], v140
	v_mfma_f32_16x16x32_bf16 v[66:69], v[152:155], v[46:49], v[34:37]
	s_waitcnt lgkmcnt(0)
	v_mfma_f32_16x16x32_bf16 v[152:155], v[140:143], v[42:45], v[62:65]
	s_nop 2
	v_add_u32_e32 v62, v157, v167
	ds_read_b128 v[62:65], v62
	v_mfma_f32_16x16x32_bf16 v[34:37], v[148:151], v[42:45], v[18:21]
	v_mfma_f32_16x16x32_bf16 v[18:21], v[148:151], v[78:81], v[144:147]
	v_mfma_f32_16x16x32_bf16 v[148:151], v[140:143], v[46:49], v[100:103]
	v_mfma_f32_16x16x32_bf16 v[144:147], v[140:143], v[74:77], v[104:107]
	v_mfma_f32_16x16x32_bf16 v[140:143], v[140:143], v[78:81], v[108:111]
	s_waitcnt lgkmcnt(0)
	v_mfma_f32_16x16x32_bf16 v[112:115], v[62:65], v[42:45], v[112:115]
	v_mfma_f32_16x16x32_bf16 v[108:111], v[62:65], v[46:49], v[128:131]
	v_mfma_f32_16x16x32_bf16 v[104:107], v[62:65], v[74:77], v[132:135]
	v_mfma_f32_16x16x32_bf16 v[100:103], v[62:65], v[78:81], v[136:139]
	v_add_u32_e32 v62, v157, v171
	ds_read_b128 v[128:131], v62
	s_waitcnt lgkmcnt(0)
	v_mfma_f32_16x16x32_bf16 v[62:65], v[128:131], v[42:45], v[58:61]
	v_mfma_f32_16x16x32_bf16 v[58:61], v[128:131], v[46:49], v[116:119]
	v_mfma_f32_16x16x32_bf16 v[46:49], v[128:131], v[74:77], v[120:123]
	v_lshl_add_u64 v[74:75], s[0:1], 0, v[98:99]
	v_mfma_f32_16x16x32_bf16 v[42:45], v[128:131], v[78:81], v[124:127]
	s_and_saveexec_b64 s[0:1], vcc
	s_cbranch_execz .LBB0_490
	v_mov_b32_e32 v78, v94
	v_mov_b32_e32 v79, v148
	v_mov_b32_e32 v76, v152
	v_mov_b32_e32 v77, v90
	s_waitcnt vmcnt(4)
	v_pk_mul_f32 v[78:79], v[38:39], v[78:79]
	v_mov_b32_e32 v80, v94
	v_mov_b32_e32 v81, v90
	v_pk_fma_f32 v[76:77], v[38:39], v[76:77], v[78:79] op_sel:[1,0,0] op_sel_hi:[0,1,1]
	v_mov_b32_e32 v78, v152
	v_mov_b32_e32 v79, v148
	v_pk_mul_f32 v[80:81], v[38:39], v[80:81] op_sel:[1,0]
	v_mov_b32_e32 v116, v86
	v_mov_b32_e32 v117, v140
	v_pk_fma_f32 v[78:79], v[38:39], v[78:79], v[80:81] op_sel_hi:[0,1,1] neg_lo:[0,0,1] neg_hi:[0,0,1]
	v_mov_b32_e32 v80, v144
	v_mov_b32_e32 v81, v82
	v_pk_mul_f32 v[116:117], v[38:39], v[116:117]
	v_mov_b32_e32 v118, v86
	v_pk_fma_f32 v[80:81], v[38:39], v[80:81], v[116:117] op_sel:[1,0,0] op_sel_hi:[0,1,1]
	v_mov_b32_e32 v119, v82
	v_or_b32_e32 v174, s48, v174
	v_mov_b32_e32 v116, v144
	v_mov_b32_e32 v117, v140
	v_pk_mul_f32 v[118:119], v[38:39], v[118:119] op_sel:[1,0]
	v_cvt_pk_bf16_f32 v76, v76, v77
	v_cvt_pk_bf16_f32 v77, v80, v81
	v_lshlrev_b64 v[80:81], 10, v[174:175]
	v_pk_fma_f32 v[38:39], v[38:39], v[116:117], v[118:119] op_sel_hi:[0,1,1] neg_lo:[0,0,1] neg_hi:[0,0,1]
	v_lshl_add_u64 v[80:81], v[74:75], 0, v[80:81]
	global_store_dwordx2 v[80:81], v[76:77], off sc1
	v_cvt_pk_bf16_f32 v77, v38, v39
	v_lshl_add_u64 v[38:39], v[176:177], 0, s[48:49]
	v_lshlrev_b64 v[38:39], 10, v[38:39]
	v_cvt_pk_bf16_f32 v76, v78, v79
	v_lshl_add_u64 v[38:39], v[74:75], 0, v[38:39]
	global_store_dwordx2 v[38:39], v[76:77], off sc1
.LBB0_490:
	s_or_b64 exec, exec, s[0:1]
	s_waitcnt vmcnt(4)
	v_or_b32_e32 v38, 1, v178
	v_cmp_gt_i32_e32 vcc, 33, v38
	s_and_saveexec_b64 s[0:1], vcc
	s_cbranch_execz .LBB0_492
	v_mov_b32_e32 v148, v95
	v_mov_b32_e32 v90, v153
	v_pk_mul_f32 v[76:77], v[40:41], v[148:149]
	v_mov_b32_e32 v78, v41
	v_pk_fma_f32 v[76:77], v[40:41], v[90:91], v[76:77] op_sel:[1,0,0] op_sel_hi:[0,1,1]
	v_mov_b32_e32 v90, v95
	v_mov_b32_e32 v140, v87
	v_pk_mul_f32 v[80:81], v[78:79], v[90:91] op_sel_hi:[0,1]
	v_mov_b32_e32 v82, v145
	v_pk_mul_f32 v[90:91], v[40:41], v[140:141]
	v_lshlrev_b32_e32 v38, 1, v38
	v_pk_fma_f32 v[90:91], v[40:41], v[82:83], v[90:91] op_sel:[1,0,0] op_sel_hi:[0,1,1]
	v_mov_b32_e32 v82, v87
	v_mov_b32_e32 v148, v153
	v_mov_b32_e32 v140, v145
	v_pk_mul_f32 v[78:79], v[78:79], v[82:83] op_sel_hi:[0,1]
	v_ashrrev_i32_e32 v39, 31, v38
	v_pk_fma_f32 v[80:81], v[40:41], v[148:149], v[80:81] op_sel_hi:[0,1,1] neg_lo:[0,0,1] neg_hi:[0,0,1]
	v_pk_fma_f32 v[40:41], v[40:41], v[140:141], v[78:79] op_sel_hi:[0,1,1] neg_lo:[0,0,1] neg_hi:[0,0,1]
	v_lshlrev_b64 v[78:79], s12, v[38:39]
	v_or_b32_e32 v38, 1, v38
	v_ashrrev_i32_e32 v39, 31, v38
	v_or_b32_e32 v78, s48, v78
	v_lshlrev_b64 v[38:39], s12, v[38:39]
	v_lshlrev_b64 v[78:79], 10, v[78:79]
	v_lshl_add_u64 v[38:39], v[38:39], 0, s[48:49]
	v_cvt_pk_bf16_f32 v76, v76, v77
	v_cvt_pk_bf16_f32 v77, v90, v91
	v_lshl_add_u64 v[78:79], v[74:75], 0, v[78:79]
	v_lshlrev_b64 v[38:39], 10, v[38:39]
	global_store_dwordx2 v[78:79], v[76:77], off sc1
	v_cvt_pk_bf16_f32 v76, v80, v81
	v_cvt_pk_bf16_f32 v77, v40, v41
	v_lshl_add_u64 v[38:39], v[74:75], 0, v[38:39]
	global_store_dwordx2 v[38:39], v[76:77], off sc1
.LBB0_492:
	s_or_b64 exec, exec, s[0:1]
	v_or_b32_e32 v38, 2, v178
	v_cmp_gt_i32_e32 vcc, 33, v38
	s_and_saveexec_b64 s[0:1], vcc
	s_cbranch_execz .LBB0_494
	v_mov_b32_e32 v76, v96
	v_mov_b32_e32 v77, v150
	v_mov_b32_e32 v40, v154
	v_mov_b32_e32 v41, v92
	v_pk_mul_f32 v[76:77], v[26:27], v[76:77]
	v_mov_b32_e32 v78, v96
	v_mov_b32_e32 v79, v92
	v_pk_fma_f32 v[40:41], v[26:27], v[40:41], v[76:77] op_sel:[1,0,0] op_sel_hi:[0,1,1]
	v_mov_b32_e32 v76, v154
	v_mov_b32_e32 v77, v150
	v_pk_mul_f32 v[78:79], v[26:27], v[78:79] op_sel:[1,0]
	v_mov_b32_e32 v80, v88
	v_mov_b32_e32 v81, v142
	v_pk_fma_f32 v[76:77], v[26:27], v[76:77], v[78:79] op_sel_hi:[0,1,1] neg_lo:[0,0,1] neg_hi:[0,0,1]
	v_mov_b32_e32 v78, v146
	v_mov_b32_e32 v79, v84
	v_pk_mul_f32 v[80:81], v[26:27], v[80:81]
	v_lshlrev_b32_e32 v38, 1, v38
	v_pk_fma_f32 v[78:79], v[26:27], v[78:79], v[80:81] op_sel:[1,0,0] op_sel_hi:[0,1,1]
	v_ashrrev_i32_e32 v39, 31, v38
	v_cvt_pk_bf16_f32 v40, v40, v41
	v_cvt_pk_bf16_f32 v41, v78, v79
	v_lshlrev_b64 v[78:79], s12, v[38:39]
	v_mov_b32_e32 v82, v88
	v_mov_b32_e32 v83, v84
	v_or_b32_e32 v78, s48, v78
	v_mov_b32_e32 v80, v146
	v_mov_b32_e32 v81, v142
	v_pk_mul_f32 v[82:83], v[26:27], v[82:83] op_sel:[1,0]
	v_lshlrev_b64 v[78:79], 10, v[78:79]
	v_pk_fma_f32 v[26:27], v[26:27], v[80:81], v[82:83] op_sel_hi:[0,1,1] neg_lo:[0,0,1] neg_hi:[0,0,1]
	v_lshl_add_u64 v[78:79], v[74:75], 0, v[78:79]
	global_store_dwordx2 v[78:79], v[40:41], off sc1
	v_cvt_pk_bf16_f32 v41, v26, v27
	v_or_b32_e32 v26, 1, v38
	v_ashrrev_i32_e32 v27, 31, v26
	v_lshlrev_b64 v[26:27], s12, v[26:27]
	v_lshl_add_u64 v[26:27], v[26:27], 0, s[48:49]
	v_lshlrev_b64 v[26:27], 10, v[26:27]
	v_cvt_pk_bf16_f32 v40, v76, v77
	v_lshl_add_u64 v[26:27], v[74:75], 0, v[26:27]
	global_store_dwordx2 v[26:27], v[40:41], off sc1
.LBB0_494:
	s_or_b64 exec, exec, s[0:1]
	v_or_b32_e32 v26, 3, v178
	v_cmp_gt_i32_e32 vcc, 33, v26
	s_and_saveexec_b64 s[0:1], vcc
	s_cbranch_execz .LBB0_499
	v_mov_b32_e32 v150, v97
	v_mov_b32_e32 v142, v89
	v_mov_b32_e32 v92, v155
	v_pk_mul_f32 v[38:39], v[28:29], v[150:151]
	v_mov_b32_e32 v84, v147
	v_pk_mul_f32 v[78:79], v[28:29], v[142:143]
	v_pk_fma_f32 v[38:39], v[28:29], v[92:93], v[38:39] op_sel:[1,0,0] op_sel_hi:[0,1,1]
	v_mov_b32_e32 v40, v29
	v_mov_b32_e32 v92, v97
	v_pk_fma_f32 v[78:79], v[28:29], v[84:85], v[78:79] op_sel:[1,0,0] op_sel_hi:[0,1,1]
	v_mov_b32_e32 v84, v89
	v_lshlrev_b32_e32 v26, 1, v26
	v_mov_b32_e32 v150, v155
	v_pk_mul_f32 v[76:77], v[40:41], v[92:93] op_sel_hi:[0,1]
	v_mov_b32_e32 v142, v147
	v_pk_mul_f32 v[40:41], v[40:41], v[84:85] op_sel_hi:[0,1]
	v_ashrrev_i32_e32 v27, 31, v26
	v_pk_fma_f32 v[76:77], v[28:29], v[150:151], v[76:77] op_sel_hi:[0,1,1] neg_lo:[0,0,1] neg_hi:[0,0,1]
	v_pk_fma_f32 v[28:29], v[28:29], v[142:143], v[40:41] op_sel_hi:[0,1,1] neg_lo:[0,0,1] neg_hi:[0,0,1]
	v_lshlrev_b64 v[40:41], s12, v[26:27]
	v_or_b32_e32 v26, 1, v26
	v_ashrrev_i32_e32 v27, 31, v26
	v_or_b32_e32 v40, s48, v40
	v_lshlrev_b64 v[26:27], s12, v[26:27]
	v_lshlrev_b64 v[40:41], 10, v[40:41]
	v_lshl_add_u64 v[26:27], v[26:27], 0, s[48:49]
	v_cvt_pk_bf16_f32 v38, v38, v39
	v_cvt_pk_bf16_f32 v39, v78, v79
	v_lshl_add_u64 v[40:41], v[74:75], 0, v[40:41]
	v_lshlrev_b64 v[26:27], 10, v[26:27]
	global_store_dwordx2 v[40:41], v[38:39], off sc1
	v_cvt_pk_bf16_f32 v38, v76, v77
	v_cvt_pk_bf16_f32 v39, v28, v29
	v_lshl_add_u64 v[26:27], v[74:75], 0, v[26:27]
	global_store_dwordx2 v[26:27], v[38:39], off sc1
	s_or_b64 exec, exec, s[0:1]
	v_cmp_gt_i32_e32 vcc, 5, v181
	s_and_saveexec_b64 s[0:1], vcc
	s_cbranch_execnz .LBB0_500

.LBB0_497:
	v_mov_b32_e32 v108, v71
	v_mov_b32_e32 v100, v55
	v_mov_b32_e32 v66, v113
	s_waitcnt vmcnt(2)
	v_pk_mul_f32 v[14:15], v[16:17], v[108:109]
	v_mov_b32_e32 v50, v105
	v_pk_mul_f32 v[38:39], v[16:17], v[100:101]
	v_pk_fma_f32 v[14:15], v[16:17], v[66:67], v[14:15] op_sel:[1,0,0] op_sel_hi:[0,1,1]
	v_mov_b32_e32 v26, v17
	v_mov_b32_e32 v66, v71
	v_pk_fma_f32 v[38:39], v[16:17], v[50:51], v[38:39] op_sel:[1,0,0] op_sel_hi:[0,1,1]
	v_mov_b32_e32 v50, v55
	v_mov_b32_e32 v108, v113
	v_pk_mul_f32 v[28:29], v[26:27], v[66:67] op_sel_hi:[0,1]
	v_mov_b32_e32 v100, v105
	v_pk_mul_f32 v[26:27], v[26:27], v[50:51] op_sel_hi:[0,1]
	v_or_b32_e32 v168, s48, v168
	v_pk_fma_f32 v[28:29], v[16:17], v[108:109], v[28:29] op_sel_hi:[0,1,1] neg_lo:[0,0,1] neg_hi:[0,0,1]
	v_pk_fma_f32 v[16:17], v[16:17], v[100:101], v[26:27] op_sel_hi:[0,1,1] neg_lo:[0,0,1] neg_hi:[0,0,1]
	v_lshlrev_b64 v[26:27], 10, v[168:169]
	v_cvt_pk_bf16_f32 v14, v14, v15
	v_cvt_pk_bf16_f32 v15, v38, v39
	v_lshl_add_u64 v[26:27], v[74:75], 0, v[26:27]
	global_store_dwordx2 v[26:27], v[14:15], off sc1
	v_cvt_pk_bf16_f32 v15, v16, v17
	v_or_b32_e32 v16, 1, v166
	v_ashrrev_i32_e32 v17, 31, v16
	v_lshlrev_b64 v[16:17], s12, v[16:17]
	v_lshl_add_u64 v[16:17], v[16:17], 0, s[48:49]
	v_lshlrev_b64 v[16:17], 10, v[16:17]
	v_cvt_pk_bf16_f32 v14, v28, v29
	v_lshl_add_u64 v[16:17], v[74:75], 0, v[16:17]
	global_store_dwordx2 v[16:17], v[14:15], off sc1
	v_mov_b32_e32 v16, v72
	v_mov_b32_e32 v17, v110
	v_mov_b32_e32 v14, v114
	v_mov_b32_e32 v15, v68
	v_pk_mul_f32 v[16:17], v[10:11], v[16:17]
	v_mov_b32_e32 v26, v11
	v_mov_b32_e32 v28, v72
	v_mov_b32_e32 v29, v68
	v_pk_fma_f32 v[14:15], v[10:11], v[14:15], v[16:17] op_sel:[1,0,0] op_sel_hi:[0,1,1]
	v_mov_b32_e32 v16, v114
	v_mov_b32_e32 v17, v110
	v_pk_mul_f32 v[28:29], v[26:27], v[28:29] op_sel_hi:[0,1]
	v_mov_b32_e32 v38, v56
	v_mov_b32_e32 v39, v102
	v_pk_fma_f32 v[16:17], v[10:11], v[16:17], v[28:29] op_sel_hi:[0,1,1] neg_lo:[0,0,1] neg_hi:[0,0,1]
	v_mov_b32_e32 v28, v106
	v_mov_b32_e32 v29, v52
	v_pk_mul_f32 v[38:39], v[10:11], v[38:39]
	v_mov_b32_e32 v40, v56
	v_mov_b32_e32 v41, v52
	v_pk_fma_f32 v[28:29], v[10:11], v[28:29], v[38:39] op_sel:[1,0,0] op_sel_hi:[0,1,1]
	v_mov_b32_e32 v38, v106
	v_mov_b32_e32 v39, v102
	v_pk_mul_f32 v[26:27], v[26:27], v[40:41] op_sel_hi:[0,1]
	v_or_b32_e32 v164, s48, v164
	v_pk_fma_f32 v[10:11], v[10:11], v[38:39], v[26:27] op_sel_hi:[0,1,1] neg_lo:[0,0,1] neg_hi:[0,0,1]
	v_lshlrev_b64 v[26:27], 10, v[164:165]
	v_cvt_pk_bf16_f32 v14, v14, v15
	v_cvt_pk_bf16_f32 v15, v28, v29
	v_lshl_add_u64 v[26:27], v[74:75], 0, v[26:27]
	global_store_dwordx2 v[26:27], v[14:15], off sc1
	v_cvt_pk_bf16_f32 v15, v10, v11
	v_or_b32_e32 v10, 1, v162
	v_ashrrev_i32_e32 v11, 31, v10
	v_lshlrev_b64 v[10:11], s12, v[10:11]
	v_lshl_add_u64 v[10:11], v[10:11], 0, s[48:49]
	v_lshlrev_b64 v[10:11], 10, v[10:11]
	v_cvt_pk_bf16_f32 v14, v16, v17
	v_lshl_add_u64 v[10:11], v[74:75], 0, v[10:11]
	v_mov_b32_e32 v110, v73
	v_mov_b32_e32 v102, v57
	global_store_dwordx2 v[10:11], v[14:15], off sc1
	v_mov_b32_e32 v68, v115
	v_pk_mul_f32 v[10:11], v[12:13], v[110:111]
	v_mov_b32_e32 v52, v107
	v_pk_mul_f32 v[26:27], v[12:13], v[102:103]
	v_pk_fma_f32 v[10:11], v[12:13], v[68:69], v[10:11] op_sel:[1,0,0] op_sel_hi:[0,1,1]
	v_mov_b32_e32 v14, v13
	v_mov_b32_e32 v68, v73
	v_pk_fma_f32 v[26:27], v[12:13], v[52:53], v[26:27] op_sel:[1,0,0] op_sel_hi:[0,1,1]
	v_mov_b32_e32 v52, v57
	v_mov_b32_e32 v110, v115
	v_pk_mul_f32 v[16:17], v[14:15], v[68:69] op_sel_hi:[0,1]
	v_mov_b32_e32 v102, v107
	v_pk_mul_f32 v[14:15], v[14:15], v[52:53] op_sel_hi:[0,1]
	v_or_b32_e32 v160, s48, v160
	v_pk_fma_f32 v[16:17], v[12:13], v[110:111], v[16:17] op_sel_hi:[0,1,1] neg_lo:[0,0,1] neg_hi:[0,0,1]
	v_pk_fma_f32 v[12:13], v[12:13], v[102:103], v[14:15] op_sel_hi:[0,1,1] neg_lo:[0,0,1] neg_hi:[0,0,1]
	v_lshlrev_b64 v[14:15], 10, v[160:161]
	v_cvt_pk_bf16_f32 v10, v10, v11
	v_cvt_pk_bf16_f32 v11, v26, v27
	v_lshl_add_u64 v[14:15], v[74:75], 0, v[14:15]
	global_store_dwordx2 v[14:15], v[10:11], off sc1
	v_cvt_pk_bf16_f32 v11, v12, v13
	v_or_b32_e32 v12, 1, v158
	v_ashrrev_i32_e32 v13, 31, v12
	v_lshlrev_b64 v[12:13], s12, v[12:13]
	v_lshl_add_u64 v[12:13], v[12:13], 0, s[48:49]
	v_lshlrev_b64 v[12:13], 10, v[12:13]
	v_cvt_pk_bf16_f32 v10, v16, v17
	v_lshl_add_u64 v[12:13], v[74:75], 0, v[12:13]
	global_store_dwordx2 v[12:13], v[10:11], off sc1
	s_or_b64 exec, exec, s[0:1]
	v_cmp_gt_i32_e32 vcc, 1, v181
	s_and_saveexec_b64 s[0:1], vcc
	s_cbranch_execnz .LBB0_502

.LBB0_500:
	v_mov_b32_e32 v28, v70
	v_mov_b32_e32 v29, v108
	v_mov_b32_e32 v26, v112
	v_mov_b32_e32 v27, v66
	s_waitcnt vmcnt(2)
	v_pk_mul_f32 v[28:29], v[14:15], v[28:29]
	v_mov_b32_e32 v38, v70
	v_mov_b32_e32 v39, v66
	v_pk_fma_f32 v[26:27], v[14:15], v[26:27], v[28:29] op_sel:[1,0,0] op_sel_hi:[0,1,1]
	v_mov_b32_e32 v28, v112
	v_mov_b32_e32 v29, v108
	v_pk_mul_f32 v[38:39], v[14:15], v[38:39] op_sel:[1,0]
	v_mov_b32_e32 v40, v54
	v_mov_b32_e32 v41, v100
	v_pk_fma_f32 v[28:29], v[14:15], v[28:29], v[38:39] op_sel_hi:[0,1,1] neg_lo:[0,0,1] neg_hi:[0,0,1]
	v_mov_b32_e32 v38, v104
	v_mov_b32_e32 v39, v50
	v_pk_mul_f32 v[40:41], v[14:15], v[40:41]
	v_mov_b32_e32 v76, v54
	v_pk_fma_f32 v[38:39], v[14:15], v[38:39], v[40:41] op_sel:[1,0,0] op_sel_hi:[0,1,1]
	v_mov_b32_e32 v77, v50
	v_or_b32_e32 v172, s48, v172
	v_mov_b32_e32 v40, v104
	v_mov_b32_e32 v41, v100
	v_pk_mul_f32 v[76:77], v[14:15], v[76:77] op_sel:[1,0]
	v_cvt_pk_bf16_f32 v26, v26, v27
	v_cvt_pk_bf16_f32 v27, v38, v39
	v_lshlrev_b64 v[38:39], 10, v[172:173]
	v_pk_fma_f32 v[14:15], v[14:15], v[40:41], v[76:77] op_sel_hi:[0,1,1] neg_lo:[0,0,1] neg_hi:[0,0,1]
	v_lshl_add_u64 v[38:39], v[74:75], 0, v[38:39]
	global_store_dwordx2 v[38:39], v[26:27], off sc1
	v_cvt_pk_bf16_f32 v27, v14, v15
	v_or_b32_e32 v14, 1, v170
	v_ashrrev_i32_e32 v15, 31, v14
	v_lshlrev_b64 v[14:15], s12, v[14:15]
	v_lshl_add_u64 v[14:15], v[14:15], 0, s[48:49]
	v_lshlrev_b64 v[14:15], 10, v[14:15]
	v_cvt_pk_bf16_f32 v26, v28, v29
	v_lshl_add_u64 v[14:15], v[74:75], 0, v[14:15]
	global_store_dwordx2 v[14:15], v[26:27], off sc1
	s_or_b64 exec, exec, s[0:1]
	v_cmp_gt_i32_e32 vcc, 4, v181
	s_and_saveexec_b64 s[0:1], vcc
	s_cbranch_execnz .LBB0_497

.LBB0_502:
	s_waitcnt vmcnt(3)
	v_mov_b32_e32 v12, v34
	v_mov_b32_e32 v13, v58
	v_mov_b32_e32 v10, v62
	v_mov_b32_e32 v11, v30
	s_waitcnt vmcnt(0)
	v_pk_mul_f32 v[12:13], v[6:7], v[12:13]
	v_mov_b32_e32 v14, v34
	v_mov_b32_e32 v15, v30
	v_pk_fma_f32 v[10:11], v[6:7], v[10:11], v[12:13] op_sel:[1,0,0] op_sel_hi:[0,1,1]
	v_mov_b32_e32 v12, v62
	v_mov_b32_e32 v13, v58
	v_pk_mul_f32 v[14:15], v[6:7], v[14:15] op_sel:[1,0]
	v_mov_b32_e32 v16, v22
	v_mov_b32_e32 v17, v42
	v_pk_fma_f32 v[12:13], v[6:7], v[12:13], v[14:15] op_sel_hi:[0,1,1] neg_lo:[0,0,1] neg_hi:[0,0,1]
	v_mov_b32_e32 v14, v46
	v_mov_b32_e32 v15, v18
	v_pk_mul_f32 v[16:17], v[6:7], v[16:17]
	v_cvt_pk_bf16_f32 v10, v10, v11
	v_pk_fma_f32 v[14:15], v[6:7], v[14:15], v[16:17] op_sel:[1,0,0] op_sel_hi:[0,1,1]
	v_cvt_pk_bf16_f32 v11, v14, v15
	v_add_u32_e32 v14, 64, v156
	v_ashrrev_i32_e32 v15, 31, v14
	v_lshlrev_b64 v[14:15], s12, v[14:15]
	v_mov_b32_e32 v26, v22
	v_mov_b32_e32 v27, v18
	v_or_b32_e32 v14, s48, v14
	v_mov_b32_e32 v16, v46
	v_mov_b32_e32 v17, v42
	v_pk_mul_f32 v[26:27], v[6:7], v[26:27] op_sel:[1,0]
	v_lshlrev_b64 v[14:15], 10, v[14:15]
	v_pk_fma_f32 v[6:7], v[6:7], v[16:17], v[26:27] op_sel_hi:[0,1,1] neg_lo:[0,0,1] neg_hi:[0,0,1]
	v_lshl_add_u64 v[14:15], v[74:75], 0, v[14:15]
	global_store_dwordx2 v[14:15], v[10:11], off sc1
	v_cvt_pk_bf16_f32 v11, v6, v7
	v_add_u32_e32 v6, 0x41, v156
	v_ashrrev_i32_e32 v7, 31, v6
	v_lshlrev_b64 v[6:7], s12, v[6:7]
	v_lshl_add_u64 v[6:7], v[6:7], 0, s[48:49]
	v_lshlrev_b64 v[6:7], 10, v[6:7]
	v_cvt_pk_bf16_f32 v10, v12, v13
	v_lshl_add_u64 v[6:7], v[74:75], 0, v[6:7]
	global_store_dwordx2 v[6:7], v[10:11], off sc1
	s_or_b64 exec, exec, s[0:1]
	v_cmp_gt_i32_e32 vcc, 0, v181
	s_and_saveexec_b64 s[0:1], vcc
	s_cbranch_execz .LBB0_487
.LBB0_503:
	v_mov_b32_e32 v58, v35
	v_mov_b32_e32 v42, v23
	v_mov_b32_e32 v30, v63
	s_waitcnt vmcnt(0)
	v_pk_mul_f32 v[6:7], v[8:9], v[58:59]
	v_mov_b32_e32 v18, v47
	v_pk_mul_f32 v[14:15], v[8:9], v[42:43]
	v_pk_fma_f32 v[6:7], v[8:9], v[30:31], v[6:7] op_sel:[1,0,0] op_sel_hi:[0,1,1]
	v_mov_b32_e32 v10, v9
	v_mov_b32_e32 v30, v35
	v_pk_fma_f32 v[14:15], v[8:9], v[18:19], v[14:15] op_sel:[1,0,0] op_sel_hi:[0,1,1]
	v_mov_b32_e32 v18, v23
	v_mov_b32_e32 v58, v63
	v_pk_mul_f32 v[12:13], v[10:11], v[30:31] op_sel_hi:[0,1]
	v_mov_b32_e32 v42, v47
	v_pk_mul_f32 v[10:11], v[10:11], v[18:19] op_sel_hi:[0,1]
	v_pk_fma_f32 v[12:13], v[8:9], v[58:59], v[12:13] op_sel_hi:[0,1,1] neg_lo:[0,0,1] neg_hi:[0,0,1]
	v_pk_fma_f32 v[8:9], v[8:9], v[42:43], v[10:11] op_sel_hi:[0,1,1] neg_lo:[0,0,1] neg_hi:[0,0,1]
	v_add_u32_e32 v10, 0x42, v156
	v_ashrrev_i32_e32 v11, 31, v10
	v_lshlrev_b64 v[10:11], s12, v[10:11]
	v_or_b32_e32 v10, s48, v10
	v_lshlrev_b64 v[10:11], 10, v[10:11]
	v_cvt_pk_bf16_f32 v6, v6, v7
	v_cvt_pk_bf16_f32 v7, v14, v15
	v_lshl_add_u64 v[10:11], v[74:75], 0, v[10:11]
	global_store_dwordx2 v[10:11], v[6:7], off sc1
	v_cvt_pk_bf16_f32 v7, v8, v9
	v_add_u32_e32 v8, 0x43, v156
	v_ashrrev_i32_e32 v9, 31, v8
	v_lshlrev_b64 v[8:9], s12, v[8:9]
	v_lshl_add_u64 v[8:9], v[8:9], 0, s[48:49]
	v_lshlrev_b64 v[8:9], 10, v[8:9]
	v_cvt_pk_bf16_f32 v6, v12, v13
	v_lshl_add_u64 v[8:9], v[74:75], 0, v[8:9]
	global_store_dwordx2 v[8:9], v[6:7], off sc1
	v_mov_b32_e32 v8, v36
	v_mov_b32_e32 v9, v60
	v_mov_b32_e32 v6, v64
	v_mov_b32_e32 v7, v32
	v_pk_mul_f32 v[8:9], v[2:3], v[8:9]
	v_mov_b32_e32 v10, v3
	v_mov_b32_e32 v12, v36
	v_mov_b32_e32 v13, v32
	v_pk_fma_f32 v[6:7], v[2:3], v[6:7], v[8:9] op_sel:[1,0,0] op_sel_hi:[0,1,1]
	v_mov_b32_e32 v8, v64
	v_mov_b32_e32 v9, v60
	v_pk_mul_f32 v[12:13], v[10:11], v[12:13] op_sel_hi:[0,1]
	v_mov_b32_e32 v14, v24
	v_mov_b32_e32 v15, v44
	v_pk_fma_f32 v[8:9], v[2:3], v[8:9], v[12:13] op_sel_hi:[0,1,1] neg_lo:[0,0,1] neg_hi:[0,0,1]
	v_mov_b32_e32 v12, v48
	v_mov_b32_e32 v13, v20
	v_pk_mul_f32 v[14:15], v[2:3], v[14:15]
	v_mov_b32_e32 v16, v24
	v_mov_b32_e32 v17, v20
	v_pk_fma_f32 v[12:13], v[2:3], v[12:13], v[14:15] op_sel:[1,0,0] op_sel_hi:[0,1,1]
	v_mov_b32_e32 v14, v48
	v_mov_b32_e32 v15, v44
	v_pk_mul_f32 v[10:11], v[10:11], v[16:17] op_sel_hi:[0,1]
	v_pk_fma_f32 v[2:3], v[2:3], v[14:15], v[10:11] op_sel_hi:[0,1,1] neg_lo:[0,0,1] neg_hi:[0,0,1]
	v_add_u32_e32 v10, 0x44, v156
	v_ashrrev_i32_e32 v11, 31, v10
	v_lshlrev_b64 v[10:11], s12, v[10:11]
	v_or_b32_e32 v10, s48, v10
	v_lshlrev_b64 v[10:11], 10, v[10:11]
	v_cvt_pk_bf16_f32 v6, v6, v7
	v_cvt_pk_bf16_f32 v7, v12, v13
	v_lshl_add_u64 v[10:11], v[74:75], 0, v[10:11]
	global_store_dwordx2 v[10:11], v[6:7], off sc1
	v_cvt_pk_bf16_f32 v7, v2, v3
	v_add_u32_e32 v2, 0x45, v156
	v_ashrrev_i32_e32 v3, 31, v2
	v_lshlrev_b64 v[2:3], s12, v[2:3]
	v_lshl_add_u64 v[2:3], v[2:3], 0, s[48:49]
	v_lshlrev_b64 v[2:3], 10, v[2:3]
	v_cvt_pk_bf16_f32 v6, v8, v9
	v_lshl_add_u64 v[2:3], v[74:75], 0, v[2:3]
	v_mov_b32_e32 v60, v37
	v_mov_b32_e32 v44, v25
	global_store_dwordx2 v[2:3], v[6:7], off sc1
	v_mov_b32_e32 v32, v65
	v_pk_mul_f32 v[2:3], v[4:5], v[60:61]
	v_mov_b32_e32 v20, v49
	v_pk_mul_f32 v[10:11], v[4:5], v[44:45]
	v_pk_fma_f32 v[2:3], v[4:5], v[32:33], v[2:3] op_sel:[1,0,0] op_sel_hi:[0,1,1]
	v_mov_b32_e32 v6, v5
	v_mov_b32_e32 v32, v37
	v_pk_fma_f32 v[10:11], v[4:5], v[20:21], v[10:11] op_sel:[1,0,0] op_sel_hi:[0,1,1]
	v_mov_b32_e32 v20, v25
	v_mov_b32_e32 v60, v65
	v_pk_mul_f32 v[8:9], v[6:7], v[32:33] op_sel_hi:[0,1]
	v_mov_b32_e32 v44, v49
	v_pk_mul_f32 v[6:7], v[6:7], v[20:21] op_sel_hi:[0,1]
	v_pk_fma_f32 v[8:9], v[4:5], v[60:61], v[8:9] op_sel_hi:[0,1,1] neg_lo:[0,0,1] neg_hi:[0,0,1]
	v_pk_fma_f32 v[4:5], v[4:5], v[44:45], v[6:7] op_sel_hi:[0,1,1] neg_lo:[0,0,1] neg_hi:[0,0,1]
	v_add_u32_e32 v6, 0x46, v156
	v_ashrrev_i32_e32 v7, 31, v6
	v_lshlrev_b64 v[6:7], s12, v[6:7]
	v_or_b32_e32 v6, s48, v6
	v_lshlrev_b64 v[6:7], 10, v[6:7]
	v_cvt_pk_bf16_f32 v2, v2, v3
	v_cvt_pk_bf16_f32 v3, v10, v11
	v_lshl_add_u64 v[6:7], v[74:75], 0, v[6:7]
	global_store_dwordx2 v[6:7], v[2:3], off sc1
	v_cvt_pk_bf16_f32 v3, v4, v5
	v_add_u32_e32 v4, 0x47, v156
	v_ashrrev_i32_e32 v5, 31, v4
	v_lshlrev_b64 v[4:5], s12, v[4:5]
	v_lshl_add_u64 v[4:5], v[4:5], 0, s[48:49]
	v_lshlrev_b64 v[4:5], 10, v[4:5]
	v_cvt_pk_bf16_f32 v2, v8, v9
	v_lshl_add_u64 v[4:5], v[74:75], 0, v[4:5]
	global_store_dwordx2 v[4:5], v[2:3], off
	s_branch .LBB0_487

.LBB0_597:
	s_or_b32 s0, s20, s14
	s_lshl_b32 s0, s0, 11
	s_add_u32 s0, s68, s0
	s_addc_u32 s1, s69, 0
	v_lshlrev_b32_e32 v98, 1, v150
	v_lshl_add_u64 v[132:133], s[0:1], 0, v[98:99]
	v_lshl_add_u32 v98, v151, 3, s57
	v_and_b32_e32 v134, -16, v212
	v_cvt_pk_bf16_f32 v137, v120, v116
	v_mul_lo_u32 v116, v211, s16
	v_add_u32_e32 v147, s57, v134
	v_lshl_add_u64 v[134:135], v[148:149], 1, s[12:13]
	v_add_u32_e32 v148, v98, v116
	v_cvt_pk_bf16_f32 v116, v129, v125
	v_cvt_pk_bf16_f32 v117, v121, v117
	v_cvt_pk_bf16_f32 v121, v122, v118
	v_cvt_pk_bf16_f32 v122, v82, v86
	v_cvt_pk_bf16_f32 v82, v83, v87
	v_cvt_pk_bf16_f32 v83, v91, v95
	v_cvt_pk_bf16_f32 v120, v130, v126
	ds_write2_b64 v148, v[116:117], v[82:83] offset0:34 offset1:50
	v_cvt_pk_bf16_f32 v82, v84, v88
	v_cvt_pk_bf16_f32 v83, v92, v96
	v_cvt_pk_bf16_f32 v119, v123, v119
	v_cvt_pk_bf16_f32 v123, v90, v94
	ds_write2_b64 v148, v[120:121], v[82:83] offset0:68 offset1:84
	v_cvt_pk_bf16_f32 v82, v85, v89
	v_cvt_pk_bf16_f32 v84, v113, v109
	v_cvt_pk_bf16_f32 v85, v105, v101
	v_cvt_pk_bf16_f32 v90, v66, v70
	v_add_u32_e32 v149, 0x1000, v148
	v_cvt_pk_bf16_f32 v66, v67, v71
	v_cvt_pk_bf16_f32 v67, v75, v79
	v_cvt_pk_bf16_f32 v118, v131, v127
	v_cvt_pk_bf16_f32 v83, v93, v97
	v_cvt_pk_bf16_f32 v86, v114, v110
	v_cvt_pk_bf16_f32 v87, v106, v102
	ds_write2_b64 v149, v[84:85], v[66:67] offset0:66 offset1:82
	v_cvt_pk_bf16_f32 v66, v68, v72
	v_cvt_pk_bf16_f32 v67, v76, v80
	v_cvt_pk_bf16_f32 v136, v128, v124
	ds_write2_b64 v148, v[118:119], v[82:83] offset0:102 offset1:118
	v_cvt_pk_bf16_f32 v82, v112, v108
	v_cvt_pk_bf16_f32 v83, v104, v100
	v_cvt_pk_bf16_f32 v88, v115, v111
	v_cvt_pk_bf16_f32 v89, v107, v103
	v_cvt_pk_bf16_f32 v91, v74, v78
	ds_write2_b64 v149, v[86:87], v[66:67] offset0:100 offset1:116
	v_cvt_pk_bf16_f32 v66, v69, v73
	v_cvt_pk_bf16_f32 v67, v77, v81
	ds_write2_b64 v148, v[136:137], v[122:123] offset1:16
	ds_write2_b64 v149, v[82:83], v[90:91] offset0:32 offset1:48
	ds_write2_b64 v149, v[88:89], v[66:67] offset0:134 offset1:150
	s_waitcnt lgkmcnt(0)
	v_lshlrev_b32_e32 v98, 10, v151
	v_mad_u32_u24 v150, v151, s6, v147
	v_lshl_add_u64 v[136:137], v[134:135], 0, v[98:99]
	ds_read_b128 v[66:69], v150
	ds_read_b128 v[70:73], v150 offset:4352
	global_load_dwordx4 v[74:77], v[136:137], off
	global_load_dwordx4 v[78:81], v[136:137], off offset:256
	global_load_dwordx4 v[82:85], v[136:137], off offset:512
	global_load_dwordx4 v[86:89], v[136:137], off offset:768
	s_add_i32 s15, s15, -1
	s_and_b32 s0, s15, 0xff
	s_cmp_lt_u32 s0, 31
	s_cselect_b64 s[0:1], -1, 0
	v_lshlrev_b32_e32 v146, 2, v211
	s_lshl_b32 s20, s14, 12
	s_and_b64 vcc, exec, s[0:1]
	s_waitcnt vmcnt(3) lgkmcnt(1)
	v_mfma_f32_16x16x32_bf16 v[90:93], v[66:69], v[74:77], 0
	s_waitcnt vmcnt(2)
	v_mfma_f32_16x16x32_bf16 v[94:97], v[66:69], v[78:81], 0
	s_waitcnt lgkmcnt(0)
	v_mfma_f32_16x16x32_bf16 v[108:111], v[70:73], v[78:81], 0
	ds_read_b128 v[78:81], v150 offset:64
	ds_read_b128 v[116:119], v150 offset:4416
	global_load_dwordx4 v[120:123], v[136:137], off offset:64
	global_load_dwordx4 v[124:127], v[136:137], off offset:320
	global_load_dwordx4 v[128:131], v[136:137], off offset:576
	global_load_dwordx4 v[138:141], v[136:137], off offset:832
	s_waitcnt vmcnt(5)
	v_mfma_f32_16x16x32_bf16 v[100:103], v[66:69], v[82:85], 0
	s_waitcnt vmcnt(4)
	v_mfma_f32_16x16x32_bf16 v[66:69], v[66:69], v[86:89], 0
	v_mfma_f32_16x16x32_bf16 v[74:77], v[70:73], v[74:77], 0
	v_mfma_f32_16x16x32_bf16 v[112:115], v[70:73], v[82:85], 0
	v_mfma_f32_16x16x32_bf16 v[70:73], v[70:73], v[86:89], 0
	s_waitcnt vmcnt(3) lgkmcnt(1)
	v_mfma_f32_16x16x32_bf16 v[104:107], v[78:81], v[120:123], v[90:93]
	s_waitcnt vmcnt(2)
	v_mfma_f32_16x16x32_bf16 v[82:85], v[78:81], v[124:127], v[94:97]
	s_nop 0
	ds_read_b128 v[90:93], v150 offset:128
	s_nop 0
	ds_read_b128 v[94:97], v150 offset:4480
	s_waitcnt vmcnt(1)
	v_mfma_f32_16x16x32_bf16 v[100:103], v[78:81], v[128:131], v[100:103]
	s_waitcnt vmcnt(0)
	v_mfma_f32_16x16x32_bf16 v[86:89], v[78:81], v[138:141], v[66:69]
	s_waitcnt lgkmcnt(2)
	v_mfma_f32_16x16x32_bf16 v[78:81], v[116:119], v[120:123], v[74:77]
	v_mfma_f32_16x16x32_bf16 v[66:69], v[116:119], v[124:127], v[108:111]
	v_mfma_f32_16x16x32_bf16 v[74:77], v[116:119], v[128:131], v[112:115]
	v_mfma_f32_16x16x32_bf16 v[70:73], v[116:119], v[138:141], v[70:73]
	s_nop 0
	global_load_dwordx4 v[108:111], v[136:137], off offset:128
	global_load_dwordx4 v[112:115], v[136:137], off offset:384
	global_load_dwordx4 v[116:119], v[136:137], off offset:640
	global_load_dwordx4 v[120:123], v[136:137], off offset:896
	s_waitcnt vmcnt(2) lgkmcnt(1)
	v_mfma_f32_16x16x32_bf16 v[138:141], v[90:93], v[112:115], 0
	s_waitcnt lgkmcnt(0)
	v_mfma_f32_16x16x32_bf16 v[152:155], v[94:97], v[112:115], 0
	ds_read_b128 v[112:115], v150 offset:192
	ds_read_b128 v[160:163], v150 offset:4544
	global_load_dwordx4 v[164:167], v[136:137], off offset:192
	global_load_dwordx4 v[168:171], v[136:137], off offset:448
	global_load_dwordx4 v[172:175], v[136:137], off offset:704
	global_load_dwordx4 v[176:179], v[136:137], off offset:960
	s_waitcnt lgkmcnt(0)
	v_mfma_f32_16x16x32_bf16 v[124:127], v[90:93], v[108:111], 0
	s_waitcnt vmcnt(5)
	v_mfma_f32_16x16x32_bf16 v[142:145], v[90:93], v[116:119], 0
	s_waitcnt vmcnt(4)
	v_mfma_f32_16x16x32_bf16 v[90:93], v[90:93], v[120:123], 0
	v_mfma_f32_16x16x32_bf16 v[156:159], v[94:97], v[116:119], 0
	s_waitcnt vmcnt(3) lgkmcnt(1)
	v_mfma_f32_16x16x32_bf16 v[128:131], v[112:115], v[164:167], v[124:127]
	s_waitcnt vmcnt(2)
	v_mfma_f32_16x16x32_bf16 v[116:119], v[112:115], v[168:171], v[138:141]
	v_mfma_f32_16x16x32_bf16 v[108:111], v[94:97], v[108:111], 0
	s_nop 1
	v_mov_b32_e32 v138, v104
	v_mov_b32_e32 v139, v82
	s_nop 0
	v_mov_b32_e32 v140, v128
	v_mfma_f32_16x16x32_bf16 v[94:97], v[94:97], v[120:123], 0
	v_mov_b32_e32 v141, v116
	v_pk_add_f32 v[134:135], v[138:139], v[140:141]
	s_waitcnt vmcnt(1)
	v_mfma_f32_16x16x32_bf16 v[124:127], v[112:115], v[172:175], v[142:145]
	s_waitcnt vmcnt(0)
	v_mfma_f32_16x16x32_bf16 v[120:123], v[112:115], v[176:179], v[90:93]
	s_nop 0
	v_mov_b32_e32 v142, v100
	v_mov_b32_e32 v143, v86
	s_nop 2
	v_mov_b32_e32 v144, v124
	s_waitcnt lgkmcnt(0)
	v_mfma_f32_16x16x32_bf16 v[90:93], v[160:163], v[168:171], v[152:155]
	s_nop 2
	v_cvt_pk_bf16_f32 v152, v134, v135
	v_mov_b32_e32 v145, v120
	v_pk_add_f32 v[134:135], v[142:143], v[144:145]
	v_mfma_f32_16x16x32_bf16 v[112:115], v[160:163], v[164:167], v[108:111]
	v_cvt_pk_bf16_f32 v153, v134, v135
	v_lshlrev_b32_e32 v134, 8, v211
	v_ashrrev_i32_e32 v135, 31, v134
	v_mfma_f32_16x16x32_bf16 v[108:111], v[160:163], v[172:175], v[156:159]
	v_lshlrev_b64 v[154:155], 11, v[134:135]
	v_lshl_add_u64 v[154:155], v[132:133], 0, v[154:155]
	global_store_dwordx2 v[154:155], v[152:153], off sc1
	v_mfma_f32_16x16x32_bf16 v[94:97], v[160:163], v[176:179], v[94:97]
	s_cbranch_vccz .LBB0_599
	v_pk_add_f32 v[138:139], v[138:139], v[140:141] neg_lo:[0,1] neg_hi:[0,1]
	v_pk_add_f32 v[140:141], v[142:143], v[144:145] neg_lo:[0,1] neg_hi:[0,1]
	v_cvt_pk_bf16_f32 v138, v138, v139
	v_cvt_pk_bf16_f32 v139, v140, v141
	v_sub_u32_e32 v140, 63, v146
	v_ashrrev_i32_e32 v141, 31, v140
	v_lshlrev_b64 v[140:141], 17, v[140:141]
	v_subrev_co_u32_e32 v140, vcc, s20, v140
	s_nop 1
	v_subbrev_co_u32_e32 v141, vcc, 0, v141, vcc
	v_lshl_add_u64 v[140:141], v[132:133], 0, v[140:141]
	v_add_co_u32_e32 v140, vcc, 0x20000, v140
	s_nop 1
	v_addc_co_u32_e32 v141, vcc, 0, v141, vcc
	global_store_dwordx2 v[140:141], v[138:139], off sc1
.LBB0_599:
	v_mov_b32_e32 v82, v105
	v_mov_b32_e32 v116, v129
	v_pk_add_f32 v[104:105], v[82:83], v[116:117]
	v_mov_b32_e32 v86, v101
	v_mov_b32_e32 v120, v125
	v_cvt_pk_bf16_f32 v100, v104, v105
	v_pk_add_f32 v[104:105], v[86:87], v[120:121]
	v_cndmask_b32_e64 v98, 0, 1, s[0:1]
	v_cvt_pk_bf16_f32 v101, v104, v105
	v_or_b32_e32 v104, 64, v134
	v_ashrrev_i32_e32 v105, 31, v104
	v_lshlrev_b64 v[104:105], 11, v[104:105]
	v_lshl_add_u64 v[104:105], v[132:133], 0, v[104:105]
	v_cmp_ne_u32_e64 s[36:37], 1, v98
	s_andn2_b64 vcc, exec, s[0:1]
	global_store_dwordx2 v[104:105], v[100:101], off sc1
	s_cbranch_vccnz .LBB0_601
	v_pk_add_f32 v[82:83], v[82:83], v[116:117] neg_lo:[0,1] neg_hi:[0,1]
	v_pk_add_f32 v[86:87], v[86:87], v[120:121] neg_lo:[0,1] neg_hi:[0,1]
	v_cvt_pk_bf16_f32 v82, v82, v83
	v_cvt_pk_bf16_f32 v83, v86, v87
	v_xor_b32_e32 v86, -2, v146
	v_ashrrev_i32_e32 v87, 31, v86
	v_lshlrev_b64 v[86:87], 17, v[86:87]
	v_subrev_co_u32_e32 v86, vcc, s20, v86
	s_nop 1
	v_subbrev_co_u32_e32 v87, vcc, 0, v87, vcc
	v_lshl_add_u64 v[86:87], v[132:133], 0, v[86:87]
	v_add_co_u32_e32 v86, vcc, 0x820000, v86
	s_nop 1
	v_addc_co_u32_e32 v87, vcc, 0, v87, vcc
	global_store_dwordx2 v[86:87], v[82:83], off sc1
.LBB0_601:
	v_mov_b32_e32 v82, v106
	v_mov_b32_e32 v83, v84
	v_mov_b32_e32 v86, v130
	v_mov_b32_e32 v87, v118
	v_pk_add_f32 v[100:101], v[82:83], v[86:87]
	v_mov_b32_e32 v104, v126
	v_cvt_pk_bf16_f32 v116, v100, v101
	v_mov_b32_e32 v100, v102
	v_mov_b32_e32 v101, v88
	v_mov_b32_e32 v105, v122
	v_pk_add_f32 v[120:121], v[100:101], v[104:105]
	s_and_b64 vcc, exec, s[36:37]
	v_cvt_pk_bf16_f32 v117, v120, v121
	v_or_b32_e32 v120, 0x80, v134
	v_ashrrev_i32_e32 v121, 31, v120
	v_lshlrev_b64 v[120:121], 11, v[120:121]
	v_lshl_add_u64 v[120:121], v[132:133], 0, v[120:121]
	global_store_dwordx2 v[120:121], v[116:117], off sc1
	s_cbranch_vccnz .LBB0_603
	v_pk_add_f32 v[82:83], v[82:83], v[86:87] neg_lo:[0,1] neg_hi:[0,1]
	v_pk_add_f32 v[86:87], v[100:101], v[104:105] neg_lo:[0,1] neg_hi:[0,1]
	v_cvt_pk_bf16_f32 v82, v82, v83
	v_cvt_pk_bf16_f32 v83, v86, v87
	v_xor_b32_e32 v86, -3, v146
	v_ashrrev_i32_e32 v87, 31, v86
	v_lshlrev_b64 v[86:87], 17, v[86:87]
	v_subrev_co_u32_e32 v86, vcc, s20, v86
	s_nop 1
	v_subbrev_co_u32_e32 v87, vcc, 0, v87, vcc
	v_lshl_add_u64 v[86:87], v[132:133], 0, v[86:87]
	v_add_co_u32_e32 v86, vcc, 0x820000, v86
	s_nop 1
	v_addc_co_u32_e32 v87, vcc, 0, v87, vcc
	global_store_dwordx2 v[86:87], v[82:83], off sc1
.LBB0_603:
	v_mov_b32_e32 v84, v107
	v_mov_b32_e32 v118, v131
	v_mov_b32_e32 v88, v103
	v_mov_b32_e32 v122, v127
	v_pk_add_f32 v[82:83], v[84:85], v[118:119]
	v_pk_add_f32 v[86:87], v[88:89], v[122:123]
	v_cvt_pk_bf16_f32 v82, v82, v83
	v_cvt_pk_bf16_f32 v83, v86, v87
	v_or_b32_e32 v86, 0xc0, v134
	v_ashrrev_i32_e32 v87, 31, v86
	v_lshlrev_b64 v[86:87], 11, v[86:87]
	v_lshl_add_u64 v[86:87], v[132:133], 0, v[86:87]
	s_and_b64 vcc, exec, s[36:37]
	global_store_dwordx2 v[86:87], v[82:83], off sc1
	s_cbranch_vccnz .LBB0_605
	v_pk_add_f32 v[82:83], v[84:85], v[118:119] neg_lo:[0,1] neg_hi:[0,1]
	v_pk_add_f32 v[84:85], v[88:89], v[122:123] neg_lo:[0,1] neg_hi:[0,1]
	v_cvt_pk_bf16_f32 v82, v82, v83
	v_cvt_pk_bf16_f32 v83, v84, v85
	v_xor_b32_e32 v84, -4, v146
	v_ashrrev_i32_e32 v85, 31, v84
	v_lshlrev_b64 v[84:85], 17, v[84:85]
	v_subrev_co_u32_e32 v84, vcc, s20, v84
	s_nop 1
	v_subbrev_co_u32_e32 v85, vcc, 0, v85, vcc
	v_lshl_add_u64 v[84:85], v[132:133], 0, v[84:85]
	v_add_co_u32_e32 v84, vcc, 0x820000, v84
	s_nop 1
	v_addc_co_u32_e32 v85, vcc, 0, v85, vcc
	global_store_dwordx2 v[84:85], v[82:83], off sc1
.LBB0_605:
	v_mov_b32_e32 v82, v78
	v_mov_b32_e32 v83, v66
	v_mov_b32_e32 v84, v112
	v_mov_b32_e32 v85, v90
	v_pk_add_f32 v[86:87], v[82:83], v[84:85]
	v_mov_b32_e32 v88, v108
	v_cvt_pk_bf16_f32 v100, v86, v87
	v_mov_b32_e32 v86, v74
	v_mov_b32_e32 v87, v70
	v_mov_b32_e32 v89, v94
	v_pk_add_f32 v[102:103], v[86:87], v[88:89]
	s_and_b64 vcc, exec, s[36:37]
	v_cvt_pk_bf16_f32 v101, v102, v103
	v_add_u32_e32 v102, 0x400, v134
	v_ashrrev_i32_e32 v103, 31, v102
	v_lshlrev_b64 v[102:103], 11, v[102:103]
	v_lshl_add_u64 v[102:103], v[132:133], 0, v[102:103]
	global_store_dwordx2 v[102:103], v[100:101], off sc1
	s_cbranch_vccnz .LBB0_607
	v_pk_add_f32 v[82:83], v[82:83], v[84:85] neg_lo:[0,1] neg_hi:[0,1]
	v_pk_add_f32 v[84:85], v[86:87], v[88:89] neg_lo:[0,1] neg_hi:[0,1]
	v_cvt_pk_bf16_f32 v82, v82, v83
	v_cvt_pk_bf16_f32 v83, v84, v85
	v_sub_u32_e32 v84, 47, v146
	v_ashrrev_i32_e32 v85, 31, v84
	v_lshlrev_b64 v[84:85], 17, v[84:85]
	v_subrev_co_u32_e32 v84, vcc, s20, v84
	s_nop 1
	v_subbrev_co_u32_e32 v85, vcc, 0, v85, vcc
	v_lshl_add_u64 v[84:85], v[132:133], 0, v[84:85]
	v_add_co_u32_e32 v84, vcc, 0x20000, v84
	s_nop 1
	v_addc_co_u32_e32 v85, vcc, 0, v85, vcc
	global_store_dwordx2 v[84:85], v[82:83], off sc1
.LBB0_607:
	v_mov_b32_e32 v66, v79
	v_mov_b32_e32 v90, v113
	v_pk_add_f32 v[78:79], v[66:67], v[90:91]
	v_mov_b32_e32 v70, v75
	v_mov_b32_e32 v94, v109
	v_cvt_pk_bf16_f32 v74, v78, v79
	v_pk_add_f32 v[78:79], v[70:71], v[94:95]
	s_and_b64 vcc, exec, s[36:37]
	v_cvt_pk_bf16_f32 v75, v78, v79
	v_add_u32_e32 v78, 0x440, v134
	v_ashrrev_i32_e32 v79, 31, v78
	v_lshlrev_b64 v[78:79], 11, v[78:79]
	v_lshl_add_u64 v[78:79], v[132:133], 0, v[78:79]
	global_store_dwordx2 v[78:79], v[74:75], off sc1
	s_cbranch_vccnz .LBB0_609
	v_pk_add_f32 v[66:67], v[66:67], v[90:91] neg_lo:[0,1] neg_hi:[0,1]
	v_pk_add_f32 v[70:71], v[70:71], v[94:95] neg_lo:[0,1] neg_hi:[0,1]
	v_cvt_pk_bf16_f32 v66, v66, v67
	v_cvt_pk_bf16_f32 v67, v70, v71
	v_sub_u32_e32 v70, 46, v146
	v_ashrrev_i32_e32 v71, 31, v70
	v_lshlrev_b64 v[70:71], 17, v[70:71]
	v_subrev_co_u32_e32 v70, vcc, s20, v70
	s_nop 1
	v_subbrev_co_u32_e32 v71, vcc, 0, v71, vcc
	v_lshl_add_u64 v[70:71], v[132:133], 0, v[70:71]
	v_add_co_u32_e32 v70, vcc, 0x20000, v70
	s_nop 1
	v_addc_co_u32_e32 v71, vcc, 0, v71, vcc
	global_store_dwordx2 v[70:71], v[66:67], off sc1
.LBB0_609:
	v_mov_b32_e32 v66, v80
	v_mov_b32_e32 v67, v68
	v_mov_b32_e32 v70, v114
	v_mov_b32_e32 v71, v92
	v_pk_add_f32 v[74:75], v[66:67], v[70:71]
	v_mov_b32_e32 v78, v110
	v_cvt_pk_bf16_f32 v82, v74, v75
	v_mov_b32_e32 v74, v76
	v_mov_b32_e32 v75, v72
	v_mov_b32_e32 v79, v96
	v_pk_add_f32 v[84:85], v[74:75], v[78:79]
	s_and_b64 vcc, exec, s[36:37]
	v_cvt_pk_bf16_f32 v83, v84, v85
	v_add_u32_e32 v84, 0x480, v134
	v_ashrrev_i32_e32 v85, 31, v84
	v_lshlrev_b64 v[84:85], 11, v[84:85]
	v_lshl_add_u64 v[84:85], v[132:133], 0, v[84:85]
	global_store_dwordx2 v[84:85], v[82:83], off sc1
	s_cbranch_vccnz .LBB0_611
	v_pk_add_f32 v[66:67], v[66:67], v[70:71] neg_lo:[0,1] neg_hi:[0,1]
	v_pk_add_f32 v[70:71], v[74:75], v[78:79] neg_lo:[0,1] neg_hi:[0,1]
	v_cvt_pk_bf16_f32 v66, v66, v67
	v_cvt_pk_bf16_f32 v67, v70, v71
	v_sub_u32_e32 v70, 45, v146
	v_ashrrev_i32_e32 v71, 31, v70
	v_lshlrev_b64 v[70:71], 17, v[70:71]
	v_subrev_co_u32_e32 v70, vcc, s20, v70
	s_nop 1
	v_subbrev_co_u32_e32 v71, vcc, 0, v71, vcc
	v_lshl_add_u64 v[70:71], v[132:133], 0, v[70:71]
	v_add_co_u32_e32 v70, vcc, 0x20000, v70
	s_nop 1
	v_addc_co_u32_e32 v71, vcc, 0, v71, vcc
	global_store_dwordx2 v[70:71], v[66:67], off sc1
.LBB0_611:
	v_mov_b32_e32 v68, v81
	v_mov_b32_e32 v92, v115
	v_mov_b32_e32 v72, v77
	v_mov_b32_e32 v96, v111
	v_pk_add_f32 v[66:67], v[68:69], v[92:93]
	v_pk_add_f32 v[70:71], v[72:73], v[96:97]
	v_cvt_pk_bf16_f32 v66, v66, v67
	v_cvt_pk_bf16_f32 v67, v70, v71
	v_add_u32_e32 v70, 0x4c0, v134
	v_ashrrev_i32_e32 v71, 31, v70
	v_lshlrev_b64 v[70:71], 11, v[70:71]
	v_lshl_add_u64 v[70:71], v[132:133], 0, v[70:71]
	s_and_b64 vcc, exec, s[36:37]
	global_store_dwordx2 v[70:71], v[66:67], off sc1
	s_cbranch_vccnz .LBB0_613
	v_pk_add_f32 v[66:67], v[68:69], v[92:93] neg_lo:[0,1] neg_hi:[0,1]
	v_pk_add_f32 v[68:69], v[72:73], v[96:97] neg_lo:[0,1] neg_hi:[0,1]
	v_cvt_pk_bf16_f32 v66, v66, v67
	v_cvt_pk_bf16_f32 v67, v68, v69
	v_sub_u32_e32 v68, 44, v146
	v_ashrrev_i32_e32 v69, 31, v68
	v_lshlrev_b64 v[68:69], 17, v[68:69]
	v_subrev_co_u32_e32 v68, vcc, s20, v68
	s_nop 1
	v_subbrev_co_u32_e32 v69, vcc, 0, v69, vcc
	v_lshl_add_u64 v[68:69], v[132:133], 0, v[68:69]
	v_add_co_u32_e32 v68, vcc, 0x20000, v68
	s_nop 1
	v_addc_co_u32_e32 v69, vcc, 0, v69, vcc
	global_store_dwordx2 v[68:69], v[66:67], off sc1
.LBB0_613:
	v_cvt_pk_bf16_f32 v66, v46, v54
	v_cvt_pk_bf16_f32 v46, v47, v55
	v_cvt_pk_bf16_f32 v47, v59, v63
	v_cvt_pk_bf16_f32 v54, v48, v56
	v_cvt_pk_bf16_f32 v56, v18, v22
	v_cvt_pk_bf16_f32 v18, v19, v23
	v_cvt_pk_bf16_f32 v19, v27, v31
	v_cvt_pk_bf16_f32 v55, v60, v64
	ds_write2_b64 v148, v[46:47], v[18:19] offset0:34 offset1:50
	v_cvt_pk_bf16_f32 v18, v20, v24
	v_cvt_pk_bf16_f32 v19, v28, v32
	ds_write2_b64 v148, v[54:55], v[18:19] offset0:68 offset1:84
	v_cvt_pk_bf16_f32 v18, v21, v25
	v_cvt_pk_bf16_f32 v20, v35, v39
	v_cvt_pk_bf16_f32 v21, v43, v51
	v_cvt_pk_bf16_f32 v27, v6, v2
	v_cvt_pk_bf16_f32 v2, v15, v11
	v_cvt_pk_bf16_f32 v3, v7, v3
	v_cvt_pk_bf16_f32 v48, v49, v57
	v_cvt_pk_bf16_f32 v49, v61, v65
	v_cvt_pk_bf16_f32 v19, v29, v33
	v_cvt_pk_bf16_f32 v22, v36, v40
	v_cvt_pk_bf16_f32 v23, v44, v52
	ds_write2_b64 v149, v[20:21], v[2:3] offset0:66 offset1:82
	v_cvt_pk_bf16_f32 v2, v16, v12
	v_cvt_pk_bf16_f32 v3, v8, v4
	v_cvt_pk_bf16_f32 v67, v58, v62
	v_cvt_pk_bf16_f32 v57, v26, v30
	ds_write2_b64 v148, v[48:49], v[18:19] offset0:102 offset1:118
	v_cvt_pk_bf16_f32 v18, v34, v38
	v_cvt_pk_bf16_f32 v19, v42, v50
	v_cvt_pk_bf16_f32 v24, v37, v41
	v_cvt_pk_bf16_f32 v25, v45, v53
	v_cvt_pk_bf16_f32 v26, v14, v10
	ds_write2_b64 v149, v[22:23], v[2:3] offset0:100 offset1:116
	v_cvt_pk_bf16_f32 v2, v17, v13
	v_cvt_pk_bf16_f32 v3, v9, v5
	ds_write2_b64 v148, v[66:67], v[56:57] offset1:16
	ds_write2_b64 v149, v[18:19], v[26:27] offset0:32 offset1:48
	ds_write2_b64 v149, v[24:25], v[2:3] offset0:134 offset1:150
	v_mul_u32_u24_e32 v68, 0x110, v151
	s_waitcnt lgkmcnt(0)
	v_add_u32_e32 v82, v147, v68
	ds_read_b128 v[2:5], v82
	ds_read_b128 v[6:9], v82 offset:4352
	global_load_dwordx4 v[10:13], v[136:137], off
	global_load_dwordx4 v[14:17], v[136:137], off offset:256
	global_load_dwordx4 v[18:21], v[136:137], off offset:512
	global_load_dwordx4 v[22:25], v[136:137], off offset:768
	s_and_b64 vcc, exec, s[36:37]
	s_waitcnt vmcnt(3) lgkmcnt(1)
	v_mfma_f32_16x16x32_bf16 v[26:29], v[2:5], v[10:13], 0
	s_waitcnt vmcnt(2)
	v_mfma_f32_16x16x32_bf16 v[30:33], v[2:5], v[14:17], 0
	s_waitcnt lgkmcnt(0)
	v_mfma_f32_16x16x32_bf16 v[42:45], v[6:9], v[14:17], 0
	ds_read_b128 v[14:17], v82 offset:64
	ds_read_b128 v[50:53], v82 offset:4416
	global_load_dwordx4 v[54:57], v[136:137], off offset:64
	global_load_dwordx4 v[58:61], v[136:137], off offset:320
	global_load_dwordx4 v[62:65], v[136:137], off offset:576
	global_load_dwordx4 v[66:69], v[136:137], off offset:832
	s_waitcnt vmcnt(5)
	v_mfma_f32_16x16x32_bf16 v[34:37], v[2:5], v[18:21], 0
	s_waitcnt vmcnt(4)
	v_mfma_f32_16x16x32_bf16 v[2:5], v[2:5], v[22:25], 0
	v_mfma_f32_16x16x32_bf16 v[10:13], v[6:9], v[10:13], 0
	v_mfma_f32_16x16x32_bf16 v[46:49], v[6:9], v[18:21], 0
	v_mfma_f32_16x16x32_bf16 v[6:9], v[6:9], v[22:25], 0
	s_waitcnt vmcnt(3) lgkmcnt(1)
	v_mfma_f32_16x16x32_bf16 v[38:41], v[14:17], v[54:57], v[26:29]
	s_waitcnt vmcnt(2)
	v_mfma_f32_16x16x32_bf16 v[18:21], v[14:17], v[58:61], v[30:33]
	s_waitcnt vmcnt(1)
	v_mfma_f32_16x16x32_bf16 v[26:29], v[14:17], v[62:65], v[34:37]
	s_nop 0
	ds_read_b128 v[30:33], v82 offset:128
	s_nop 0
	ds_read_b128 v[34:37], v82 offset:4480
	s_waitcnt vmcnt(0)
	v_mfma_f32_16x16x32_bf16 v[22:25], v[14:17], v[66:69], v[2:5]
	s_waitcnt lgkmcnt(2)
	v_mfma_f32_16x16x32_bf16 v[14:17], v[50:53], v[54:57], v[10:13]
	v_mfma_f32_16x16x32_bf16 v[2:5], v[50:53], v[58:61], v[42:45]
	v_mfma_f32_16x16x32_bf16 v[10:13], v[50:53], v[62:65], v[46:49]
	v_mfma_f32_16x16x32_bf16 v[6:9], v[50:53], v[66:69], v[6:9]
	s_nop 0
	global_load_dwordx4 v[42:45], v[136:137], off offset:128
	global_load_dwordx4 v[46:49], v[136:137], off offset:384
	global_load_dwordx4 v[50:53], v[136:137], off offset:640
	global_load_dwordx4 v[54:57], v[136:137], off offset:896
	s_waitcnt vmcnt(3) lgkmcnt(1)
	v_mfma_f32_16x16x32_bf16 v[58:61], v[30:33], v[42:45], 0
	s_waitcnt vmcnt(2)
	v_mfma_f32_16x16x32_bf16 v[66:69], v[30:33], v[46:49], 0
	s_waitcnt lgkmcnt(0)
	v_mfma_f32_16x16x32_bf16 v[74:77], v[34:37], v[46:49], 0
	ds_read_b128 v[46:49], v82 offset:192
	ds_read_b128 v[82:85], v82 offset:4544
	global_load_dwordx4 v[86:89], v[136:137], off offset:192
	global_load_dwordx4 v[90:93], v[136:137], off offset:448
	global_load_dwordx4 v[94:97], v[136:137], off offset:704
	global_load_dwordx4 v[100:103], v[136:137], off offset:960
	s_waitcnt lgkmcnt(0)
	s_waitcnt vmcnt(5)
	v_mfma_f32_16x16x32_bf16 v[70:73], v[30:33], v[50:53], 0
	s_waitcnt vmcnt(4)
	v_mfma_f32_16x16x32_bf16 v[30:33], v[30:33], v[54:57], 0
	v_mfma_f32_16x16x32_bf16 v[78:81], v[34:37], v[50:53], 0
	s_waitcnt vmcnt(3) lgkmcnt(1)
	v_mfma_f32_16x16x32_bf16 v[62:65], v[46:49], v[86:89], v[58:61]
	s_waitcnt vmcnt(2)
	v_mfma_f32_16x16x32_bf16 v[50:53], v[46:49], v[90:93], v[66:69]
	v_mfma_f32_16x16x32_bf16 v[42:45], v[34:37], v[42:45], 0
	s_nop 1
	v_mov_b32_e32 v66, v38
	v_mov_b32_e32 v67, v18
	s_nop 0
	v_mov_b32_e32 v68, v62
	v_mfma_f32_16x16x32_bf16 v[34:37], v[34:37], v[54:57], 0
	v_mov_b32_e32 v69, v50
	s_waitcnt vmcnt(1)
	v_mfma_f32_16x16x32_bf16 v[58:61], v[46:49], v[94:97], v[70:73]
	s_waitcnt vmcnt(0)
	v_mfma_f32_16x16x32_bf16 v[54:57], v[46:49], v[100:103], v[30:33]
	s_nop 0
	v_add_f32_e64 v70, v66, v68
	v_add_f32_e64 v71, v67, v69
	s_nop 2
	v_mov_b32_e32 v72, v58
	s_waitcnt lgkmcnt(0)
	v_mfma_f32_16x16x32_bf16 v[30:33], v[82:85], v[90:93], v[74:77]
	s_nop 2
	v_cvt_pk_bf16_f32 v74, v70, v71
	v_mov_b32_e32 v70, v26
	v_mov_b32_e32 v71, v22
	v_mov_b32_e32 v73, v54
	v_pk_add_f32 v[76:77], v[70:71], v[72:73]
	v_mfma_f32_16x16x32_bf16 v[46:49], v[82:85], v[86:89], v[42:45]
	v_cvt_pk_bf16_f32 v75, v76, v77
	v_add_u32_e32 v76, 0x800, v134
	v_ashrrev_i32_e32 v77, 31, v76
	v_mfma_f32_16x16x32_bf16 v[42:45], v[82:85], v[94:97], v[78:81]
	v_lshlrev_b64 v[76:77], 11, v[76:77]
	v_lshl_add_u64 v[76:77], v[132:133], 0, v[76:77]
	global_store_dwordx2 v[76:77], v[74:75], off sc1
	v_mfma_f32_16x16x32_bf16 v[34:37], v[82:85], v[100:103], v[34:37]
	s_cbranch_vccnz .LBB0_615
	v_pk_add_f32 v[66:67], v[66:67], v[68:69] neg_lo:[0,1] neg_hi:[0,1]
	v_pk_add_f32 v[68:69], v[70:71], v[72:73] neg_lo:[0,1] neg_hi:[0,1]
	v_cvt_pk_bf16_f32 v66, v66, v67
	v_cvt_pk_bf16_f32 v67, v68, v69
	v_sub_u32_e32 v68, 31, v146
	v_ashrrev_i32_e32 v69, 31, v68
	v_lshlrev_b64 v[68:69], 17, v[68:69]
	v_subrev_co_u32_e32 v68, vcc, s20, v68
	s_nop 1
	v_subbrev_co_u32_e32 v69, vcc, 0, v69, vcc
	v_lshl_add_u64 v[68:69], v[132:133], 0, v[68:69]
	v_add_co_u32_e32 v68, vcc, 0x20000, v68
	s_nop 1
	v_addc_co_u32_e32 v69, vcc, 0, v69, vcc
	global_store_dwordx2 v[68:69], v[66:67], off sc1
.LBB0_615:
	v_mov_b32_e32 v18, v39
	v_mov_b32_e32 v50, v63
	v_pk_add_f32 v[38:39], v[18:19], v[50:51]
	v_mov_b32_e32 v22, v27
	v_mov_b32_e32 v54, v59
	v_cvt_pk_bf16_f32 v26, v38, v39
	v_pk_add_f32 v[38:39], v[22:23], v[54:55]
	s_and_b64 vcc, exec, s[36:37]
	v_cvt_pk_bf16_f32 v27, v38, v39
	v_add_u32_e32 v38, 0x840, v134
	v_ashrrev_i32_e32 v39, 31, v38
	v_lshlrev_b64 v[38:39], 11, v[38:39]
	v_lshl_add_u64 v[38:39], v[132:133], 0, v[38:39]
	global_store_dwordx2 v[38:39], v[26:27], off sc1
	s_cbranch_vccnz .LBB0_617
	v_pk_add_f32 v[18:19], v[18:19], v[50:51] neg_lo:[0,1] neg_hi:[0,1]
	v_pk_add_f32 v[22:23], v[22:23], v[54:55] neg_lo:[0,1] neg_hi:[0,1]
	v_cvt_pk_bf16_f32 v18, v18, v19
	v_cvt_pk_bf16_f32 v19, v22, v23
	v_sub_u32_e32 v22, 30, v146
	v_ashrrev_i32_e32 v23, 31, v22
	v_lshlrev_b64 v[22:23], 17, v[22:23]
	v_subrev_co_u32_e32 v22, vcc, s20, v22
	s_nop 1
	v_subbrev_co_u32_e32 v23, vcc, 0, v23, vcc
	v_lshl_add_u64 v[22:23], v[132:133], 0, v[22:23]
	v_add_co_u32_e32 v22, vcc, 0x20000, v22
	s_nop 1
	v_addc_co_u32_e32 v23, vcc, 0, v23, vcc
	global_store_dwordx2 v[22:23], v[18:19], off sc1
.LBB0_617:
	v_mov_b32_e32 v18, v40
	v_mov_b32_e32 v19, v20
	v_mov_b32_e32 v22, v64
	v_mov_b32_e32 v23, v52
	v_pk_add_f32 v[26:27], v[18:19], v[22:23]
	v_mov_b32_e32 v38, v60
	v_cvt_pk_bf16_f32 v50, v26, v27
	v_mov_b32_e32 v26, v28
	v_mov_b32_e32 v27, v24
	v_mov_b32_e32 v39, v56
	v_pk_add_f32 v[54:55], v[26:27], v[38:39]
	s_and_b64 vcc, exec, s[36:37]
	v_cvt_pk_bf16_f32 v51, v54, v55
	v_add_u32_e32 v54, 0x880, v134
	v_ashrrev_i32_e32 v55, 31, v54
	v_lshlrev_b64 v[54:55], 11, v[54:55]
	v_lshl_add_u64 v[54:55], v[132:133], 0, v[54:55]
	global_store_dwordx2 v[54:55], v[50:51], off sc1
	s_cbranch_vccnz .LBB0_619
	v_pk_add_f32 v[18:19], v[18:19], v[22:23] neg_lo:[0,1] neg_hi:[0,1]
	v_pk_add_f32 v[22:23], v[26:27], v[38:39] neg_lo:[0,1] neg_hi:[0,1]
	v_cvt_pk_bf16_f32 v18, v18, v19
	v_cvt_pk_bf16_f32 v19, v22, v23
	v_sub_u32_e32 v22, 29, v146
	v_ashrrev_i32_e32 v23, 31, v22
	v_lshlrev_b64 v[22:23], 17, v[22:23]
	v_subrev_co_u32_e32 v22, vcc, s20, v22
	s_nop 1
	v_subbrev_co_u32_e32 v23, vcc, 0, v23, vcc
	v_lshl_add_u64 v[22:23], v[132:133], 0, v[22:23]
	v_add_co_u32_e32 v22, vcc, 0x20000, v22
	s_nop 1
	v_addc_co_u32_e32 v23, vcc, 0, v23, vcc
	global_store_dwordx2 v[22:23], v[18:19], off sc1
.LBB0_619:
	v_mov_b32_e32 v20, v41
	v_mov_b32_e32 v52, v65
	v_mov_b32_e32 v24, v29
	v_mov_b32_e32 v56, v61
	v_pk_add_f32 v[18:19], v[20:21], v[52:53]
	v_pk_add_f32 v[22:23], v[24:25], v[56:57]
	v_cvt_pk_bf16_f32 v18, v18, v19
	v_cvt_pk_bf16_f32 v19, v22, v23
	v_add_u32_e32 v22, 0x8c0, v134
	v_ashrrev_i32_e32 v23, 31, v22
	v_lshlrev_b64 v[22:23], 11, v[22:23]
	v_lshl_add_u64 v[22:23], v[132:133], 0, v[22:23]
	s_and_b64 vcc, exec, s[36:37]
	global_store_dwordx2 v[22:23], v[18:19], off sc1
	s_cbranch_vccnz .LBB0_621
	v_pk_add_f32 v[18:19], v[20:21], v[52:53] neg_lo:[0,1] neg_hi:[0,1]
	v_pk_add_f32 v[20:21], v[24:25], v[56:57] neg_lo:[0,1] neg_hi:[0,1]
	v_cvt_pk_bf16_f32 v18, v18, v19
	v_cvt_pk_bf16_f32 v19, v20, v21
	v_sub_u32_e32 v20, 28, v146
	v_ashrrev_i32_e32 v21, 31, v20
	v_lshlrev_b64 v[20:21], 17, v[20:21]
	v_subrev_co_u32_e32 v20, vcc, s20, v20
	s_nop 1
	v_subbrev_co_u32_e32 v21, vcc, 0, v21, vcc
	v_lshl_add_u64 v[20:21], v[132:133], 0, v[20:21]
	v_add_co_u32_e32 v20, vcc, 0x20000, v20
	s_nop 1
	v_addc_co_u32_e32 v21, vcc, 0, v21, vcc
	global_store_dwordx2 v[20:21], v[18:19], off sc1
.LBB0_621:
	v_mov_b32_e32 v18, v14
	v_mov_b32_e32 v19, v2
	v_mov_b32_e32 v20, v46
	v_mov_b32_e32 v21, v30
	v_pk_add_f32 v[22:23], v[18:19], v[20:21]
	v_mov_b32_e32 v24, v42
	v_cvt_pk_bf16_f32 v26, v22, v23
	v_mov_b32_e32 v22, v10
	v_mov_b32_e32 v23, v6
	v_mov_b32_e32 v25, v34
	v_pk_add_f32 v[28:29], v[22:23], v[24:25]
	s_and_b64 vcc, exec, s[36:37]
	v_cvt_pk_bf16_f32 v27, v28, v29
	v_add_u32_e32 v28, 0xc00, v134
	v_ashrrev_i32_e32 v29, 31, v28
	v_lshlrev_b64 v[28:29], 11, v[28:29]
	v_lshl_add_u64 v[28:29], v[132:133], 0, v[28:29]
	global_store_dwordx2 v[28:29], v[26:27], off sc1
	s_cbranch_vccnz .LBB0_623
	v_pk_add_f32 v[18:19], v[18:19], v[20:21] neg_lo:[0,1] neg_hi:[0,1]
	v_pk_add_f32 v[20:21], v[22:23], v[24:25] neg_lo:[0,1] neg_hi:[0,1]
	v_cvt_pk_bf16_f32 v18, v18, v19
	v_cvt_pk_bf16_f32 v19, v20, v21
	v_sub_u32_e32 v20, 15, v146
	v_ashrrev_i32_e32 v21, 31, v20
	v_lshlrev_b64 v[20:21], 17, v[20:21]
	v_subrev_co_u32_e32 v20, vcc, s20, v20
	s_nop 1
	v_subbrev_co_u32_e32 v21, vcc, 0, v21, vcc
	v_lshl_add_u64 v[20:21], v[132:133], 0, v[20:21]
	v_add_co_u32_e32 v20, vcc, 0x20000, v20
	s_nop 1
	v_addc_co_u32_e32 v21, vcc, 0, v21, vcc
	global_store_dwordx2 v[20:21], v[18:19], off sc1
.LBB0_623:
	v_mov_b32_e32 v2, v15
	v_mov_b32_e32 v30, v47
	v_pk_add_f32 v[14:15], v[2:3], v[30:31]
	v_mov_b32_e32 v6, v11
	v_mov_b32_e32 v34, v43
	v_cvt_pk_bf16_f32 v10, v14, v15
	v_pk_add_f32 v[14:15], v[6:7], v[34:35]
	s_and_b64 vcc, exec, s[36:37]
	v_cvt_pk_bf16_f32 v11, v14, v15
	v_add_u32_e32 v14, 0xc40, v134
	v_ashrrev_i32_e32 v15, 31, v14
	v_lshlrev_b64 v[14:15], 11, v[14:15]
	v_lshl_add_u64 v[14:15], v[132:133], 0, v[14:15]
	global_store_dwordx2 v[14:15], v[10:11], off sc1
	s_cbranch_vccnz .LBB0_625
	v_pk_add_f32 v[2:3], v[2:3], v[30:31] neg_lo:[0,1] neg_hi:[0,1]
	v_pk_add_f32 v[6:7], v[6:7], v[34:35] neg_lo:[0,1] neg_hi:[0,1]
	v_cvt_pk_bf16_f32 v2, v2, v3
	v_cvt_pk_bf16_f32 v3, v6, v7
	v_sub_u32_e32 v6, 14, v146
	v_ashrrev_i32_e32 v7, 31, v6
	v_lshlrev_b64 v[6:7], 17, v[6:7]
	v_subrev_co_u32_e32 v6, vcc, s20, v6
	s_nop 1
	v_subbrev_co_u32_e32 v7, vcc, 0, v7, vcc
	v_lshl_add_u64 v[6:7], v[132:133], 0, v[6:7]
	v_add_co_u32_e32 v6, vcc, 0x20000, v6
	s_nop 1
	v_addc_co_u32_e32 v7, vcc, 0, v7, vcc
	global_store_dwordx2 v[6:7], v[2:3], off sc1
.LBB0_625:
	v_mov_b32_e32 v2, v16
	v_mov_b32_e32 v3, v4
	v_mov_b32_e32 v6, v48
	v_mov_b32_e32 v7, v32
	v_pk_add_f32 v[10:11], v[2:3], v[6:7]
	v_mov_b32_e32 v14, v44
	v_cvt_pk_bf16_f32 v18, v10, v11
	v_mov_b32_e32 v10, v12
	v_mov_b32_e32 v11, v8
	v_mov_b32_e32 v15, v36
	v_pk_add_f32 v[20:21], v[10:11], v[14:15]
	s_and_b64 vcc, exec, s[36:37]
	v_cvt_pk_bf16_f32 v19, v20, v21
	v_add_u32_e32 v20, 0xc80, v134
	v_ashrrev_i32_e32 v21, 31, v20
	v_lshlrev_b64 v[20:21], 11, v[20:21]
	v_lshl_add_u64 v[20:21], v[132:133], 0, v[20:21]
	global_store_dwordx2 v[20:21], v[18:19], off sc1
	s_cbranch_vccnz .LBB0_627
	v_pk_add_f32 v[2:3], v[2:3], v[6:7] neg_lo:[0,1] neg_hi:[0,1]
	v_pk_add_f32 v[6:7], v[10:11], v[14:15] neg_lo:[0,1] neg_hi:[0,1]
	v_cvt_pk_bf16_f32 v2, v2, v3
	v_cvt_pk_bf16_f32 v3, v6, v7
	v_sub_u32_e32 v6, 13, v146
	v_ashrrev_i32_e32 v7, 31, v6
	v_lshlrev_b64 v[6:7], 17, v[6:7]
	v_subrev_co_u32_e32 v6, vcc, s20, v6
	s_nop 1
	v_subbrev_co_u32_e32 v7, vcc, 0, v7, vcc
	v_lshl_add_u64 v[6:7], v[132:133], 0, v[6:7]
	v_add_co_u32_e32 v6, vcc, 0x20000, v6
	s_nop 1
	v_addc_co_u32_e32 v7, vcc, 0, v7, vcc
	global_store_dwordx2 v[6:7], v[2:3], off sc1
.LBB0_627:
	v_mov_b32_e32 v4, v17
	v_mov_b32_e32 v32, v49
	v_mov_b32_e32 v8, v13
	v_mov_b32_e32 v36, v45
	v_pk_add_f32 v[2:3], v[4:5], v[32:33]
	v_pk_add_f32 v[6:7], v[8:9], v[36:37]
	v_cvt_pk_bf16_f32 v2, v2, v3
	v_cvt_pk_bf16_f32 v3, v6, v7
	v_add_u32_e32 v6, 0xcc0, v134
	v_ashrrev_i32_e32 v7, 31, v6
	v_lshlrev_b64 v[6:7], 11, v[6:7]
	v_lshl_add_u64 v[6:7], v[132:133], 0, v[6:7]
	s_mov_b64 s[0:1], 0
	s_and_b64 vcc, exec, s[36:37]
	s_mov_b64 s[10:11], 0
	global_store_dwordx2 v[6:7], v[2:3], off sc1
	s_cbranch_vccnz .LBB0_629
	v_pk_add_f32 v[2:3], v[4:5], v[32:33] neg_lo:[0,1] neg_hi:[0,1]
	v_pk_add_f32 v[4:5], v[8:9], v[36:37] neg_lo:[0,1] neg_hi:[0,1]
	v_cvt_pk_bf16_f32 v2, v2, v3
	v_cvt_pk_bf16_f32 v3, v4, v5
	v_sub_u32_e32 v6, 12, v146
	s_mov_b64 s[10:11], -1

.LBB0_634:
	s_add_i32 s14, s14, s0
	s_ashr_i32 s15, s14, 31
	s_lshl_b64 s[14:15], s[14:15], 11
	s_add_u32 s14, s68, s14
	s_addc_u32 s15, s69, s15
	v_lshlrev_b32_e32 v98, 1, v148
	v_lshl_add_u64 v[132:133], s[14:15], 0, v[98:99]
	v_lshl_add_u32 v98, v149, 3, s57
	v_cvt_pk_bf16_f32 v137, v120, v116
	v_mul_lo_u32 v116, v186, s16
	v_add_u32_e32 v148, v98, v116
	v_cvt_pk_bf16_f32 v116, v129, v125
	v_cvt_pk_bf16_f32 v117, v121, v117
	v_cvt_pk_bf16_f32 v121, v122, v118
	v_cvt_pk_bf16_f32 v122, v82, v86
	v_cvt_pk_bf16_f32 v82, v83, v87
	v_cvt_pk_bf16_f32 v83, v91, v95
	v_and_b32_e32 v134, -16, v187
	v_cvt_pk_bf16_f32 v120, v130, v126
	ds_write2_b64 v148, v[116:117], v[82:83] offset0:34 offset1:50
	v_cvt_pk_bf16_f32 v82, v84, v88
	v_cvt_pk_bf16_f32 v83, v92, v96
	v_add_u32_e32 v147, s57, v134
	v_lshl_add_u64 v[134:135], v[150:151], 1, s[12:13]
	v_cvt_pk_bf16_f32 v119, v123, v119
	v_cvt_pk_bf16_f32 v123, v90, v94
	ds_write2_b64 v148, v[120:121], v[82:83] offset0:68 offset1:84
	v_cvt_pk_bf16_f32 v82, v85, v89
	v_cvt_pk_bf16_f32 v84, v113, v109
	v_cvt_pk_bf16_f32 v85, v105, v101
	v_cvt_pk_bf16_f32 v90, v66, v70
	v_add_u32_e32 v150, 0x1000, v148
	v_cvt_pk_bf16_f32 v66, v67, v71
	v_cvt_pk_bf16_f32 v67, v75, v79
	v_cvt_pk_bf16_f32 v118, v131, v127
	v_cvt_pk_bf16_f32 v83, v93, v97
	v_cvt_pk_bf16_f32 v86, v114, v110
	v_cvt_pk_bf16_f32 v87, v106, v102
	ds_write2_b64 v150, v[84:85], v[66:67] offset0:66 offset1:82
	v_cvt_pk_bf16_f32 v66, v68, v72
	v_cvt_pk_bf16_f32 v67, v76, v80
	v_cvt_pk_bf16_f32 v136, v128, v124
	ds_write2_b64 v148, v[118:119], v[82:83] offset0:102 offset1:118
	v_cvt_pk_bf16_f32 v82, v112, v108
	v_cvt_pk_bf16_f32 v83, v104, v100
	v_cvt_pk_bf16_f32 v88, v115, v111
	v_cvt_pk_bf16_f32 v89, v107, v103
	v_cvt_pk_bf16_f32 v91, v74, v78
	ds_write2_b64 v150, v[86:87], v[66:67] offset0:100 offset1:116
	v_cvt_pk_bf16_f32 v66, v69, v73
	v_cvt_pk_bf16_f32 v67, v77, v81
	ds_write2_b64 v148, v[136:137], v[122:123] offset1:16
	ds_write2_b64 v150, v[82:83], v[90:91] offset0:32 offset1:48
	ds_write2_b64 v150, v[88:89], v[66:67] offset0:134 offset1:150
	s_waitcnt lgkmcnt(0)
	v_lshlrev_b32_e32 v98, 10, v149
	v_mad_u32_u24 v151, v149, s6, v147
	v_lshl_add_u64 v[136:137], v[134:135], 0, v[98:99]
	ds_read_b128 v[66:69], v151
	ds_read_b128 v[70:73], v151 offset:4352
	global_load_dwordx4 v[74:77], v[136:137], off
	global_load_dwordx4 v[78:81], v[136:137], off offset:256
	global_load_dwordx4 v[82:85], v[136:137], off offset:512
	global_load_dwordx4 v[86:89], v[136:137], off offset:768
	v_lshl_add_u32 v146, v186, 2, s1
	s_add_i32 s4, s0, -1
	s_cmp_lt_u32 s4, 31
	s_cselect_b64 s[14:15], -1, 0
	s_lshl_b32 s20, s0, 12
	s_and_b64 vcc, exec, s[14:15]
	s_waitcnt vmcnt(3) lgkmcnt(1)
	v_mfma_f32_16x16x32_bf16 v[90:93], v[66:69], v[74:77], 0
	s_waitcnt vmcnt(2)
	v_mfma_f32_16x16x32_bf16 v[94:97], v[66:69], v[78:81], 0
	s_waitcnt lgkmcnt(0)
	v_mfma_f32_16x16x32_bf16 v[104:107], v[70:73], v[78:81], 0
	ds_read_b128 v[78:81], v151 offset:64
	ds_read_b128 v[116:119], v151 offset:4416
	global_load_dwordx4 v[120:123], v[136:137], off offset:64
	global_load_dwordx4 v[124:127], v[136:137], off offset:320
	global_load_dwordx4 v[128:131], v[136:137], off offset:576
	global_load_dwordx4 v[138:141], v[136:137], off offset:832
	s_waitcnt vmcnt(5)
	v_mfma_f32_16x16x32_bf16 v[100:103], v[66:69], v[82:85], 0
	s_waitcnt vmcnt(4)
	v_mfma_f32_16x16x32_bf16 v[66:69], v[66:69], v[86:89], 0
	v_mfma_f32_16x16x32_bf16 v[74:77], v[70:73], v[74:77], 0
	v_mfma_f32_16x16x32_bf16 v[112:115], v[70:73], v[82:85], 0
	v_mfma_f32_16x16x32_bf16 v[70:73], v[70:73], v[86:89], 0
	s_waitcnt vmcnt(3) lgkmcnt(1)
	v_mfma_f32_16x16x32_bf16 v[108:111], v[78:81], v[120:123], v[90:93]
	s_waitcnt vmcnt(2)
	v_mfma_f32_16x16x32_bf16 v[82:85], v[78:81], v[124:127], v[94:97]
	s_nop 0
	ds_read_b128 v[90:93], v151 offset:128
	s_nop 0
	ds_read_b128 v[94:97], v151 offset:4480
	s_waitcnt vmcnt(1)
	v_mfma_f32_16x16x32_bf16 v[100:103], v[78:81], v[128:131], v[100:103]
	s_waitcnt vmcnt(0)
	v_mfma_f32_16x16x32_bf16 v[86:89], v[78:81], v[138:141], v[66:69]
	s_waitcnt lgkmcnt(2)
	v_mfma_f32_16x16x32_bf16 v[78:81], v[116:119], v[120:123], v[74:77]
	v_mfma_f32_16x16x32_bf16 v[66:69], v[116:119], v[124:127], v[104:107]
	v_mfma_f32_16x16x32_bf16 v[74:77], v[116:119], v[128:131], v[112:115]
	v_mfma_f32_16x16x32_bf16 v[70:73], v[116:119], v[138:141], v[70:73]
	s_nop 0
	global_load_dwordx4 v[104:107], v[136:137], off offset:128
	global_load_dwordx4 v[112:115], v[136:137], off offset:384
	global_load_dwordx4 v[116:119], v[136:137], off offset:640
	global_load_dwordx4 v[120:123], v[136:137], off offset:896
	s_waitcnt vmcnt(2) lgkmcnt(1)
	v_mfma_f32_16x16x32_bf16 v[138:141], v[90:93], v[112:115], 0
	s_waitcnt lgkmcnt(0)
	v_mfma_f32_16x16x32_bf16 v[152:155], v[94:97], v[112:115], 0
	ds_read_b128 v[112:115], v151 offset:192
	ds_read_b128 v[160:163], v151 offset:4544
	global_load_dwordx4 v[164:167], v[136:137], off offset:192
	global_load_dwordx4 v[168:171], v[136:137], off offset:448
	global_load_dwordx4 v[172:175], v[136:137], off offset:704
	global_load_dwordx4 v[176:179], v[136:137], off offset:960
	s_waitcnt lgkmcnt(0)
	v_mfma_f32_16x16x32_bf16 v[124:127], v[90:93], v[104:107], 0
	s_waitcnt vmcnt(5)
	v_mfma_f32_16x16x32_bf16 v[142:145], v[90:93], v[116:119], 0
	s_waitcnt vmcnt(4)
	v_mfma_f32_16x16x32_bf16 v[90:93], v[90:93], v[120:123], 0
	v_mfma_f32_16x16x32_bf16 v[156:159], v[94:97], v[116:119], 0
	s_waitcnt vmcnt(3) lgkmcnt(1)
	v_mfma_f32_16x16x32_bf16 v[128:131], v[112:115], v[164:167], v[124:127]
	s_waitcnt vmcnt(2)
	v_mfma_f32_16x16x32_bf16 v[116:119], v[112:115], v[168:171], v[138:141]
	v_mfma_f32_16x16x32_bf16 v[104:107], v[94:97], v[104:107], 0
	s_nop 1
	v_mov_b32_e32 v138, v108
	v_mov_b32_e32 v139, v82
	s_nop 0
	v_mov_b32_e32 v140, v128
	v_mfma_f32_16x16x32_bf16 v[94:97], v[94:97], v[120:123], 0
	v_mov_b32_e32 v141, v116
	v_pk_add_f32 v[134:135], v[138:139], v[140:141]
	s_waitcnt vmcnt(1)
	v_mfma_f32_16x16x32_bf16 v[124:127], v[112:115], v[172:175], v[142:145]
	s_waitcnt vmcnt(0)
	v_mfma_f32_16x16x32_bf16 v[120:123], v[112:115], v[176:179], v[90:93]
	s_nop 0
	v_mov_b32_e32 v142, v100
	v_mov_b32_e32 v143, v86
	s_nop 2
	v_mov_b32_e32 v144, v124
	s_waitcnt lgkmcnt(0)
	v_mfma_f32_16x16x32_bf16 v[90:93], v[160:163], v[168:171], v[152:155]
	s_nop 2
	v_cvt_pk_bf16_f32 v152, v134, v135
	v_mov_b32_e32 v145, v120
	v_pk_add_f32 v[134:135], v[142:143], v[144:145]
	v_mfma_f32_16x16x32_bf16 v[112:115], v[160:163], v[164:167], v[104:107]
	v_cvt_pk_bf16_f32 v153, v134, v135
	v_lshlrev_b32_e32 v134, 6, v146
	v_ashrrev_i32_e32 v135, 31, v134
	v_mfma_f32_16x16x32_bf16 v[104:107], v[160:163], v[172:175], v[156:159]
	v_lshlrev_b64 v[154:155], 11, v[134:135]
	v_lshl_add_u64 v[154:155], v[132:133], 0, v[154:155]
	global_store_dwordx2 v[154:155], v[152:153], off sc1
	v_mfma_f32_16x16x32_bf16 v[94:97], v[160:163], v[176:179], v[94:97]
	s_cbranch_vccz .LBB0_636
	v_pk_add_f32 v[138:139], v[138:139], v[140:141] neg_lo:[0,1] neg_hi:[0,1]
	v_pk_add_f32 v[140:141], v[142:143], v[144:145] neg_lo:[0,1] neg_hi:[0,1]
	v_cvt_pk_bf16_f32 v138, v138, v139
	v_cvt_pk_bf16_f32 v139, v140, v141
	v_sub_u32_e32 v140, 0x7f, v146
	v_ashrrev_i32_e32 v141, 31, v140
	v_lshlrev_b64 v[140:141], 17, v[140:141]
	v_subrev_co_u32_e32 v140, vcc, s20, v140
	s_nop 1
	v_subbrev_co_u32_e32 v141, vcc, 0, v141, vcc
	v_lshl_add_u64 v[140:141], v[132:133], 0, v[140:141]
	v_add_co_u32_e32 v140, vcc, 0x20000, v140
	s_nop 1
	v_addc_co_u32_e32 v141, vcc, 0, v141, vcc
	global_store_dwordx2 v[140:141], v[138:139], off sc1
.LBB0_636:
	v_mov_b32_e32 v82, v109
	v_mov_b32_e32 v116, v129
	v_pk_add_f32 v[108:109], v[82:83], v[116:117]
	v_mov_b32_e32 v86, v101
	v_mov_b32_e32 v120, v125
	v_cvt_pk_bf16_f32 v100, v108, v109
	v_pk_add_f32 v[108:109], v[86:87], v[120:121]
	v_cndmask_b32_e64 v98, 0, 1, s[14:15]
	v_cvt_pk_bf16_f32 v101, v108, v109
	v_or_b32_e32 v108, 64, v134
	v_ashrrev_i32_e32 v109, 31, v108
	v_lshlrev_b64 v[108:109], 11, v[108:109]
	v_lshl_add_u64 v[108:109], v[132:133], 0, v[108:109]
	v_cmp_ne_u32_e64 s[36:37], 1, v98
	s_andn2_b64 vcc, exec, s[14:15]
	global_store_dwordx2 v[108:109], v[100:101], off sc1
	s_cbranch_vccnz .LBB0_638
	v_pk_add_f32 v[82:83], v[82:83], v[116:117] neg_lo:[0,1] neg_hi:[0,1]
	v_pk_add_f32 v[86:87], v[86:87], v[120:121] neg_lo:[0,1] neg_hi:[0,1]
	v_cvt_pk_bf16_f32 v82, v82, v83
	v_cvt_pk_bf16_f32 v83, v86, v87
	v_xor_b32_e32 v86, -2, v146
	v_ashrrev_i32_e32 v87, 31, v86
	v_lshlrev_b64 v[86:87], 17, v[86:87]
	v_subrev_co_u32_e32 v86, vcc, s20, v86
	s_nop 1
	v_subbrev_co_u32_e32 v87, vcc, 0, v87, vcc
	v_lshl_add_u64 v[86:87], v[132:133], 0, v[86:87]
	v_add_co_u32_e32 v86, vcc, 0x1020000, v86
	s_nop 1
	v_addc_co_u32_e32 v87, vcc, 0, v87, vcc
	global_store_dwordx2 v[86:87], v[82:83], off sc1
.LBB0_638:
	v_mov_b32_e32 v82, v110
	v_mov_b32_e32 v83, v84
	v_mov_b32_e32 v86, v130
	v_mov_b32_e32 v87, v118
	v_pk_add_f32 v[100:101], v[82:83], v[86:87]
	v_mov_b32_e32 v108, v126
	v_cvt_pk_bf16_f32 v116, v100, v101
	v_mov_b32_e32 v100, v102
	v_mov_b32_e32 v101, v88
	v_mov_b32_e32 v109, v122
	v_pk_add_f32 v[120:121], v[100:101], v[108:109]
	s_and_b64 vcc, exec, s[36:37]
	v_cvt_pk_bf16_f32 v117, v120, v121
	v_or_b32_e32 v120, 0x80, v134
	v_ashrrev_i32_e32 v121, 31, v120
	v_lshlrev_b64 v[120:121], 11, v[120:121]
	v_lshl_add_u64 v[120:121], v[132:133], 0, v[120:121]
	global_store_dwordx2 v[120:121], v[116:117], off sc1
	s_cbranch_vccnz .LBB0_640
	v_pk_add_f32 v[82:83], v[82:83], v[86:87] neg_lo:[0,1] neg_hi:[0,1]
	v_pk_add_f32 v[86:87], v[100:101], v[108:109] neg_lo:[0,1] neg_hi:[0,1]
	v_cvt_pk_bf16_f32 v82, v82, v83
	v_cvt_pk_bf16_f32 v83, v86, v87
	v_xor_b32_e32 v86, -3, v146
	v_ashrrev_i32_e32 v87, 31, v86
	v_lshlrev_b64 v[86:87], 17, v[86:87]
	v_subrev_co_u32_e32 v86, vcc, s20, v86
	s_nop 1
	v_subbrev_co_u32_e32 v87, vcc, 0, v87, vcc
	v_lshl_add_u64 v[86:87], v[132:133], 0, v[86:87]
	v_add_co_u32_e32 v86, vcc, 0x1020000, v86
	s_nop 1
	v_addc_co_u32_e32 v87, vcc, 0, v87, vcc
	global_store_dwordx2 v[86:87], v[82:83], off sc1
.LBB0_640:
	v_mov_b32_e32 v84, v111
	v_mov_b32_e32 v118, v131
	v_mov_b32_e32 v88, v103
	v_mov_b32_e32 v122, v127
	v_pk_add_f32 v[82:83], v[84:85], v[118:119]
	v_pk_add_f32 v[86:87], v[88:89], v[122:123]
	v_cvt_pk_bf16_f32 v82, v82, v83
	v_cvt_pk_bf16_f32 v83, v86, v87
	v_or_b32_e32 v86, 0xc0, v134
	v_ashrrev_i32_e32 v87, 31, v86
	v_lshlrev_b64 v[86:87], 11, v[86:87]
	v_lshl_add_u64 v[86:87], v[132:133], 0, v[86:87]
	s_and_b64 vcc, exec, s[36:37]
	global_store_dwordx2 v[86:87], v[82:83], off sc1
	s_cbranch_vccnz .LBB0_642
	v_pk_add_f32 v[82:83], v[84:85], v[118:119] neg_lo:[0,1] neg_hi:[0,1]
	v_pk_add_f32 v[84:85], v[88:89], v[122:123] neg_lo:[0,1] neg_hi:[0,1]
	v_cvt_pk_bf16_f32 v82, v82, v83
	v_cvt_pk_bf16_f32 v83, v84, v85
	v_xor_b32_e32 v84, -4, v146
	v_ashrrev_i32_e32 v85, 31, v84
	v_lshlrev_b64 v[84:85], 17, v[84:85]
	v_subrev_co_u32_e32 v84, vcc, s20, v84
	s_nop 1
	v_subbrev_co_u32_e32 v85, vcc, 0, v85, vcc
	v_lshl_add_u64 v[84:85], v[132:133], 0, v[84:85]
	v_add_co_u32_e32 v84, vcc, 0x1020000, v84
	s_nop 1
	v_addc_co_u32_e32 v85, vcc, 0, v85, vcc
	global_store_dwordx2 v[84:85], v[82:83], off sc1
.LBB0_642:
	v_mov_b32_e32 v82, v78
	v_mov_b32_e32 v83, v66
	v_mov_b32_e32 v84, v112
	v_mov_b32_e32 v85, v90
	v_pk_add_f32 v[86:87], v[82:83], v[84:85]
	v_mov_b32_e32 v88, v104
	v_cvt_pk_bf16_f32 v100, v86, v87
	v_mov_b32_e32 v86, v74
	v_mov_b32_e32 v87, v70
	v_mov_b32_e32 v89, v94
	v_pk_add_f32 v[102:103], v[86:87], v[88:89]
	s_and_b64 vcc, exec, s[36:37]
	v_cvt_pk_bf16_f32 v101, v102, v103
	v_add_u32_e32 v102, 0x400, v134
	v_ashrrev_i32_e32 v103, 31, v102
	v_lshlrev_b64 v[102:103], 11, v[102:103]
	v_lshl_add_u64 v[102:103], v[132:133], 0, v[102:103]
	global_store_dwordx2 v[102:103], v[100:101], off sc1
	s_cbranch_vccnz .LBB0_644
	v_pk_add_f32 v[82:83], v[82:83], v[84:85] neg_lo:[0,1] neg_hi:[0,1]
	v_pk_add_f32 v[84:85], v[86:87], v[88:89] neg_lo:[0,1] neg_hi:[0,1]
	v_cvt_pk_bf16_f32 v82, v82, v83
	v_cvt_pk_bf16_f32 v83, v84, v85
	v_sub_u32_e32 v84, 0x6f, v146
	v_ashrrev_i32_e32 v85, 31, v84
	v_lshlrev_b64 v[84:85], 17, v[84:85]
	v_subrev_co_u32_e32 v84, vcc, s20, v84
	s_nop 1
	v_subbrev_co_u32_e32 v85, vcc, 0, v85, vcc
	v_lshl_add_u64 v[84:85], v[132:133], 0, v[84:85]
	v_add_co_u32_e32 v84, vcc, 0x20000, v84
	s_nop 1
	v_addc_co_u32_e32 v85, vcc, 0, v85, vcc
	global_store_dwordx2 v[84:85], v[82:83], off sc1
.LBB0_644:
	v_mov_b32_e32 v66, v79
	v_mov_b32_e32 v90, v113
	v_pk_add_f32 v[78:79], v[66:67], v[90:91]
	v_mov_b32_e32 v70, v75
	v_mov_b32_e32 v94, v105
	v_cvt_pk_bf16_f32 v74, v78, v79
	v_pk_add_f32 v[78:79], v[70:71], v[94:95]
	s_and_b64 vcc, exec, s[36:37]
	v_cvt_pk_bf16_f32 v75, v78, v79
	v_add_u32_e32 v78, 0x440, v134
	v_ashrrev_i32_e32 v79, 31, v78
	v_lshlrev_b64 v[78:79], 11, v[78:79]
	v_lshl_add_u64 v[78:79], v[132:133], 0, v[78:79]
	global_store_dwordx2 v[78:79], v[74:75], off sc1
	s_cbranch_vccnz .LBB0_646
	v_pk_add_f32 v[66:67], v[66:67], v[90:91] neg_lo:[0,1] neg_hi:[0,1]
	v_pk_add_f32 v[70:71], v[70:71], v[94:95] neg_lo:[0,1] neg_hi:[0,1]
	v_cvt_pk_bf16_f32 v66, v66, v67
	v_cvt_pk_bf16_f32 v67, v70, v71
	v_sub_u32_e32 v70, 0x6e, v146
	v_ashrrev_i32_e32 v71, 31, v70
	v_lshlrev_b64 v[70:71], 17, v[70:71]
	v_subrev_co_u32_e32 v70, vcc, s20, v70
	s_nop 1
	v_subbrev_co_u32_e32 v71, vcc, 0, v71, vcc
	v_lshl_add_u64 v[70:71], v[132:133], 0, v[70:71]
	v_add_co_u32_e32 v70, vcc, 0x20000, v70
	s_nop 1
	v_addc_co_u32_e32 v71, vcc, 0, v71, vcc
	global_store_dwordx2 v[70:71], v[66:67], off sc1
.LBB0_646:
	v_mov_b32_e32 v66, v80
	v_mov_b32_e32 v67, v68
	v_mov_b32_e32 v70, v114
	v_mov_b32_e32 v71, v92
	v_pk_add_f32 v[74:75], v[66:67], v[70:71]
	v_mov_b32_e32 v78, v106
	v_cvt_pk_bf16_f32 v82, v74, v75
	v_mov_b32_e32 v74, v76
	v_mov_b32_e32 v75, v72
	v_mov_b32_e32 v79, v96
	v_pk_add_f32 v[84:85], v[74:75], v[78:79]
	s_and_b64 vcc, exec, s[36:37]
	v_cvt_pk_bf16_f32 v83, v84, v85
	v_add_u32_e32 v84, 0x480, v134
	v_ashrrev_i32_e32 v85, 31, v84
	v_lshlrev_b64 v[84:85], 11, v[84:85]
	v_lshl_add_u64 v[84:85], v[132:133], 0, v[84:85]
	global_store_dwordx2 v[84:85], v[82:83], off sc1
	s_cbranch_vccnz .LBB0_648
	v_pk_add_f32 v[66:67], v[66:67], v[70:71] neg_lo:[0,1] neg_hi:[0,1]
	v_pk_add_f32 v[70:71], v[74:75], v[78:79] neg_lo:[0,1] neg_hi:[0,1]
	v_cvt_pk_bf16_f32 v66, v66, v67
	v_cvt_pk_bf16_f32 v67, v70, v71
	v_sub_u32_e32 v70, 0x6d, v146
	v_ashrrev_i32_e32 v71, 31, v70
	v_lshlrev_b64 v[70:71], 17, v[70:71]
	v_subrev_co_u32_e32 v70, vcc, s20, v70
	s_nop 1
	v_subbrev_co_u32_e32 v71, vcc, 0, v71, vcc
	v_lshl_add_u64 v[70:71], v[132:133], 0, v[70:71]
	v_add_co_u32_e32 v70, vcc, 0x20000, v70
	s_nop 1
	v_addc_co_u32_e32 v71, vcc, 0, v71, vcc
	global_store_dwordx2 v[70:71], v[66:67], off sc1
.LBB0_648:
	v_mov_b32_e32 v68, v81
	v_mov_b32_e32 v92, v115
	v_mov_b32_e32 v72, v77
	v_mov_b32_e32 v96, v107
	v_pk_add_f32 v[66:67], v[68:69], v[92:93]
	v_pk_add_f32 v[70:71], v[72:73], v[96:97]
	v_cvt_pk_bf16_f32 v66, v66, v67
	v_cvt_pk_bf16_f32 v67, v70, v71
	v_add_u32_e32 v70, 0x4c0, v134
	v_ashrrev_i32_e32 v71, 31, v70
	v_lshlrev_b64 v[70:71], 11, v[70:71]
	v_lshl_add_u64 v[70:71], v[132:133], 0, v[70:71]
	s_and_b64 vcc, exec, s[36:37]
	global_store_dwordx2 v[70:71], v[66:67], off sc1
	s_cbranch_vccnz .LBB0_650
	v_pk_add_f32 v[66:67], v[68:69], v[92:93] neg_lo:[0,1] neg_hi:[0,1]
	v_pk_add_f32 v[68:69], v[72:73], v[96:97] neg_lo:[0,1] neg_hi:[0,1]
	v_cvt_pk_bf16_f32 v66, v66, v67
	v_cvt_pk_bf16_f32 v67, v68, v69
	v_sub_u32_e32 v68, 0x6c, v146
	v_ashrrev_i32_e32 v69, 31, v68
	v_lshlrev_b64 v[68:69], 17, v[68:69]
	v_subrev_co_u32_e32 v68, vcc, s20, v68
	s_nop 1
	v_subbrev_co_u32_e32 v69, vcc, 0, v69, vcc
	v_lshl_add_u64 v[68:69], v[132:133], 0, v[68:69]
	v_add_co_u32_e32 v68, vcc, 0x20000, v68
	s_nop 1
	v_addc_co_u32_e32 v69, vcc, 0, v69, vcc
	global_store_dwordx2 v[68:69], v[66:67], off sc1
.LBB0_650:
	v_cvt_pk_bf16_f32 v66, v34, v38
	v_cvt_pk_bf16_f32 v67, v42, v46
	v_cvt_pk_bf16_f32 v38, v36, v40
	v_cvt_pk_bf16_f32 v36, v37, v41
	v_cvt_pk_bf16_f32 v40, v50, v54
	v_cvt_pk_bf16_f32 v41, v58, v62
	v_cvt_pk_bf16_f32 v34, v35, v39
	v_cvt_pk_bf16_f32 v35, v43, v47
	ds_write2_b64 v148, v[66:67], v[40:41] offset1:16
	v_cvt_pk_bf16_f32 v40, v51, v55
	v_cvt_pk_bf16_f32 v41, v59, v63
	v_cvt_pk_bf16_f32 v39, v44, v48
	ds_write2_b64 v148, v[34:35], v[40:41] offset0:34 offset1:50
	v_cvt_pk_bf16_f32 v34, v52, v56
	v_cvt_pk_bf16_f32 v35, v60, v64
	v_cvt_pk_bf16_f32 v37, v45, v49
	ds_write2_b64 v148, v[38:39], v[34:35] offset0:68 offset1:84
	v_cvt_pk_bf16_f32 v34, v53, v57
	v_cvt_pk_bf16_f32 v35, v61, v65
	ds_write2_b64 v148, v[36:37], v[34:35] offset0:102 offset1:118
	v_cvt_pk_bf16_f32 v34, v18, v22
	v_cvt_pk_bf16_f32 v18, v19, v23
	v_cvt_pk_bf16_f32 v19, v27, v31
	v_cvt_pk_bf16_f32 v22, v20, v24
	v_cvt_pk_bf16_f32 v24, v14, v2
	v_cvt_pk_bf16_f32 v2, v15, v3
	v_cvt_pk_bf16_f32 v3, v7, v11
	v_cvt_pk_bf16_f32 v23, v28, v32
	ds_write2_b64 v150, v[18:19], v[2:3] offset0:66 offset1:82
	v_cvt_pk_bf16_f32 v2, v16, v4
	v_cvt_pk_bf16_f32 v3, v8, v12
	v_cvt_pk_bf16_f32 v35, v26, v30
	v_cvt_pk_bf16_f32 v20, v21, v25
	v_cvt_pk_bf16_f32 v21, v29, v33
	v_cvt_pk_bf16_f32 v25, v6, v10
	ds_write2_b64 v150, v[22:23], v[2:3] offset0:100 offset1:116
	v_cvt_pk_bf16_f32 v2, v17, v5
	v_cvt_pk_bf16_f32 v3, v9, v13
	ds_write2_b64 v150, v[34:35], v[24:25] offset0:32 offset1:48
	ds_write2_b64 v150, v[20:21], v[2:3] offset0:134 offset1:150
	v_mul_u32_u24_e32 v68, 0x110, v149
	s_waitcnt lgkmcnt(0)
	v_add_u32_e32 v82, v147, v68
	ds_read_b128 v[2:5], v82
	ds_read_b128 v[6:9], v82 offset:4352
	global_load_dwordx4 v[10:13], v[136:137], off
	global_load_dwordx4 v[14:17], v[136:137], off offset:256
	global_load_dwordx4 v[18:21], v[136:137], off offset:512
	global_load_dwordx4 v[22:25], v[136:137], off offset:768
	s_and_b64 vcc, exec, s[36:37]
	s_waitcnt vmcnt(3) lgkmcnt(1)
	v_mfma_f32_16x16x32_bf16 v[26:29], v[2:5], v[10:13], 0
	s_waitcnt vmcnt(2)
	v_mfma_f32_16x16x32_bf16 v[30:33], v[2:5], v[14:17], 0
	s_waitcnt lgkmcnt(0)
	v_mfma_f32_16x16x32_bf16 v[42:45], v[6:9], v[14:17], 0
	ds_read_b128 v[14:17], v82 offset:64
	ds_read_b128 v[50:53], v82 offset:4416
	global_load_dwordx4 v[54:57], v[136:137], off offset:64
	global_load_dwordx4 v[58:61], v[136:137], off offset:320
	global_load_dwordx4 v[62:65], v[136:137], off offset:576
	global_load_dwordx4 v[66:69], v[136:137], off offset:832
	s_waitcnt vmcnt(5)
	v_mfma_f32_16x16x32_bf16 v[34:37], v[2:5], v[18:21], 0
	s_waitcnt vmcnt(4)
	v_mfma_f32_16x16x32_bf16 v[2:5], v[2:5], v[22:25], 0
	v_mfma_f32_16x16x32_bf16 v[10:13], v[6:9], v[10:13], 0
	v_mfma_f32_16x16x32_bf16 v[46:49], v[6:9], v[18:21], 0
	v_mfma_f32_16x16x32_bf16 v[6:9], v[6:9], v[22:25], 0
	s_waitcnt vmcnt(3) lgkmcnt(1)
	v_mfma_f32_16x16x32_bf16 v[38:41], v[14:17], v[54:57], v[26:29]
	s_waitcnt vmcnt(2)
	v_mfma_f32_16x16x32_bf16 v[18:21], v[14:17], v[58:61], v[30:33]
	s_waitcnt vmcnt(1)
	v_mfma_f32_16x16x32_bf16 v[26:29], v[14:17], v[62:65], v[34:37]
	s_nop 0
	ds_read_b128 v[30:33], v82 offset:128
	s_nop 0
	ds_read_b128 v[34:37], v82 offset:4480
	s_waitcnt vmcnt(0)
	v_mfma_f32_16x16x32_bf16 v[22:25], v[14:17], v[66:69], v[2:5]
	s_waitcnt lgkmcnt(2)
	v_mfma_f32_16x16x32_bf16 v[14:17], v[50:53], v[54:57], v[10:13]
	v_mfma_f32_16x16x32_bf16 v[2:5], v[50:53], v[58:61], v[42:45]
	v_mfma_f32_16x16x32_bf16 v[10:13], v[50:53], v[62:65], v[46:49]
	v_mfma_f32_16x16x32_bf16 v[6:9], v[50:53], v[66:69], v[6:9]
	s_nop 0
	global_load_dwordx4 v[42:45], v[136:137], off offset:128
	global_load_dwordx4 v[46:49], v[136:137], off offset:384
	global_load_dwordx4 v[50:53], v[136:137], off offset:640
	global_load_dwordx4 v[54:57], v[136:137], off offset:896
	s_waitcnt vmcnt(3) lgkmcnt(1)
	v_mfma_f32_16x16x32_bf16 v[58:61], v[30:33], v[42:45], 0
	s_waitcnt vmcnt(2)
	v_mfma_f32_16x16x32_bf16 v[66:69], v[30:33], v[46:49], 0
	s_waitcnt lgkmcnt(0)
	v_mfma_f32_16x16x32_bf16 v[74:77], v[34:37], v[46:49], 0
	ds_read_b128 v[46:49], v82 offset:192
	ds_read_b128 v[82:85], v82 offset:4544
	global_load_dwordx4 v[86:89], v[136:137], off offset:192
	global_load_dwordx4 v[90:93], v[136:137], off offset:448
	global_load_dwordx4 v[94:97], v[136:137], off offset:704
	global_load_dwordx4 v[100:103], v[136:137], off offset:960
	s_waitcnt lgkmcnt(0)
	s_waitcnt vmcnt(5)
	v_mfma_f32_16x16x32_bf16 v[70:73], v[30:33], v[50:53], 0
	s_waitcnt vmcnt(4)
	v_mfma_f32_16x16x32_bf16 v[30:33], v[30:33], v[54:57], 0
	v_mfma_f32_16x16x32_bf16 v[78:81], v[34:37], v[50:53], 0
	s_waitcnt vmcnt(3) lgkmcnt(1)
	v_mfma_f32_16x16x32_bf16 v[62:65], v[46:49], v[86:89], v[58:61]
	s_waitcnt vmcnt(2)
	v_mfma_f32_16x16x32_bf16 v[50:53], v[46:49], v[90:93], v[66:69]
	v_mfma_f32_16x16x32_bf16 v[42:45], v[34:37], v[42:45], 0
	s_nop 1
	v_mov_b32_e32 v66, v38
	v_mov_b32_e32 v67, v18
	s_nop 0
	v_mov_b32_e32 v68, v62
	v_mfma_f32_16x16x32_bf16 v[34:37], v[34:37], v[54:57], 0
	v_mov_b32_e32 v69, v50
	s_waitcnt vmcnt(1)
	v_mfma_f32_16x16x32_bf16 v[58:61], v[46:49], v[94:97], v[70:73]
	s_waitcnt vmcnt(0)
	v_mfma_f32_16x16x32_bf16 v[54:57], v[46:49], v[100:103], v[30:33]
	s_nop 0
	v_add_f32_e64 v70, v66, v68
	v_add_f32_e64 v71, v67, v69
	s_nop 2
	v_mov_b32_e32 v72, v58
	s_waitcnt lgkmcnt(0)
	v_mfma_f32_16x16x32_bf16 v[30:33], v[82:85], v[90:93], v[74:77]
	s_nop 2
	v_cvt_pk_bf16_f32 v74, v70, v71
	v_mov_b32_e32 v70, v26
	v_mov_b32_e32 v71, v22
	v_mov_b32_e32 v73, v54
	v_pk_add_f32 v[76:77], v[70:71], v[72:73]
	v_mfma_f32_16x16x32_bf16 v[46:49], v[82:85], v[86:89], v[42:45]
	v_cvt_pk_bf16_f32 v75, v76, v77
	v_add_u32_e32 v76, 0x800, v134
	v_ashrrev_i32_e32 v77, 31, v76
	v_mfma_f32_16x16x32_bf16 v[42:45], v[82:85], v[94:97], v[78:81]
	v_lshlrev_b64 v[76:77], 11, v[76:77]
	v_lshl_add_u64 v[76:77], v[132:133], 0, v[76:77]
	global_store_dwordx2 v[76:77], v[74:75], off sc1
	v_mfma_f32_16x16x32_bf16 v[34:37], v[82:85], v[100:103], v[34:37]
	s_cbranch_vccnz .LBB0_652
	v_pk_add_f32 v[66:67], v[66:67], v[68:69] neg_lo:[0,1] neg_hi:[0,1]
	v_pk_add_f32 v[68:69], v[70:71], v[72:73] neg_lo:[0,1] neg_hi:[0,1]
	v_cvt_pk_bf16_f32 v66, v66, v67
	v_cvt_pk_bf16_f32 v67, v68, v69
	v_sub_u32_e32 v68, 0x5f, v146
	v_ashrrev_i32_e32 v69, 31, v68
	v_lshlrev_b64 v[68:69], 17, v[68:69]
	v_subrev_co_u32_e32 v68, vcc, s20, v68
	s_nop 1
	v_subbrev_co_u32_e32 v69, vcc, 0, v69, vcc
	v_lshl_add_u64 v[68:69], v[132:133], 0, v[68:69]
	v_add_co_u32_e32 v68, vcc, 0x20000, v68
	s_nop 1
	v_addc_co_u32_e32 v69, vcc, 0, v69, vcc
	global_store_dwordx2 v[68:69], v[66:67], off sc1
.LBB0_652:
	v_mov_b32_e32 v18, v39
	v_mov_b32_e32 v50, v63
	v_pk_add_f32 v[38:39], v[18:19], v[50:51]
	v_mov_b32_e32 v22, v27
	v_mov_b32_e32 v54, v59
	v_cvt_pk_bf16_f32 v26, v38, v39
	v_pk_add_f32 v[38:39], v[22:23], v[54:55]
	s_and_b64 vcc, exec, s[36:37]
	v_cvt_pk_bf16_f32 v27, v38, v39
	v_add_u32_e32 v38, 0x840, v134
	v_ashrrev_i32_e32 v39, 31, v38
	v_lshlrev_b64 v[38:39], 11, v[38:39]
	v_lshl_add_u64 v[38:39], v[132:133], 0, v[38:39]
	global_store_dwordx2 v[38:39], v[26:27], off sc1
	s_cbranch_vccnz .LBB0_654
	v_pk_add_f32 v[18:19], v[18:19], v[50:51] neg_lo:[0,1] neg_hi:[0,1]
	v_pk_add_f32 v[22:23], v[22:23], v[54:55] neg_lo:[0,1] neg_hi:[0,1]
	v_cvt_pk_bf16_f32 v18, v18, v19
	v_cvt_pk_bf16_f32 v19, v22, v23
	v_sub_u32_e32 v22, 0x5e, v146
	v_ashrrev_i32_e32 v23, 31, v22
	v_lshlrev_b64 v[22:23], 17, v[22:23]
	v_subrev_co_u32_e32 v22, vcc, s20, v22
	s_nop 1
	v_subbrev_co_u32_e32 v23, vcc, 0, v23, vcc
	v_lshl_add_u64 v[22:23], v[132:133], 0, v[22:23]
	v_add_co_u32_e32 v22, vcc, 0x20000, v22
	s_nop 1
	v_addc_co_u32_e32 v23, vcc, 0, v23, vcc
	global_store_dwordx2 v[22:23], v[18:19], off sc1
.LBB0_654:
	v_mov_b32_e32 v18, v40
	v_mov_b32_e32 v19, v20
	v_mov_b32_e32 v22, v64
	v_mov_b32_e32 v23, v52
	v_pk_add_f32 v[26:27], v[18:19], v[22:23]
	v_mov_b32_e32 v38, v60
	v_cvt_pk_bf16_f32 v50, v26, v27
	v_mov_b32_e32 v26, v28
	v_mov_b32_e32 v27, v24
	v_mov_b32_e32 v39, v56
	v_pk_add_f32 v[54:55], v[26:27], v[38:39]
	s_and_b64 vcc, exec, s[36:37]
	v_cvt_pk_bf16_f32 v51, v54, v55
	v_add_u32_e32 v54, 0x880, v134
	v_ashrrev_i32_e32 v55, 31, v54
	v_lshlrev_b64 v[54:55], 11, v[54:55]
	v_lshl_add_u64 v[54:55], v[132:133], 0, v[54:55]
	global_store_dwordx2 v[54:55], v[50:51], off sc1
	s_cbranch_vccnz .LBB0_656
	v_pk_add_f32 v[18:19], v[18:19], v[22:23] neg_lo:[0,1] neg_hi:[0,1]
	v_pk_add_f32 v[22:23], v[26:27], v[38:39] neg_lo:[0,1] neg_hi:[0,1]
	v_cvt_pk_bf16_f32 v18, v18, v19
	v_cvt_pk_bf16_f32 v19, v22, v23
	v_sub_u32_e32 v22, 0x5d, v146
	v_ashrrev_i32_e32 v23, 31, v22
	v_lshlrev_b64 v[22:23], 17, v[22:23]
	v_subrev_co_u32_e32 v22, vcc, s20, v22
	s_nop 1
	v_subbrev_co_u32_e32 v23, vcc, 0, v23, vcc
	v_lshl_add_u64 v[22:23], v[132:133], 0, v[22:23]
	v_add_co_u32_e32 v22, vcc, 0x20000, v22
	s_nop 1
	v_addc_co_u32_e32 v23, vcc, 0, v23, vcc
	global_store_dwordx2 v[22:23], v[18:19], off sc1
.LBB0_656:
	v_mov_b32_e32 v20, v41
	v_mov_b32_e32 v52, v65
	v_mov_b32_e32 v24, v29
	v_mov_b32_e32 v56, v61
	v_pk_add_f32 v[18:19], v[20:21], v[52:53]
	v_pk_add_f32 v[22:23], v[24:25], v[56:57]
	v_cvt_pk_bf16_f32 v18, v18, v19
	v_cvt_pk_bf16_f32 v19, v22, v23
	v_add_u32_e32 v22, 0x8c0, v134
	v_ashrrev_i32_e32 v23, 31, v22
	v_lshlrev_b64 v[22:23], 11, v[22:23]
	v_lshl_add_u64 v[22:23], v[132:133], 0, v[22:23]
	s_and_b64 vcc, exec, s[36:37]
	global_store_dwordx2 v[22:23], v[18:19], off sc1
	s_cbranch_vccnz .LBB0_658
	v_pk_add_f32 v[18:19], v[20:21], v[52:53] neg_lo:[0,1] neg_hi:[0,1]
	v_pk_add_f32 v[20:21], v[24:25], v[56:57] neg_lo:[0,1] neg_hi:[0,1]
	v_cvt_pk_bf16_f32 v18, v18, v19
	v_cvt_pk_bf16_f32 v19, v20, v21
	v_sub_u32_e32 v20, 0x5c, v146
	v_ashrrev_i32_e32 v21, 31, v20
	v_lshlrev_b64 v[20:21], 17, v[20:21]
	v_subrev_co_u32_e32 v20, vcc, s20, v20
	s_nop 1
	v_subbrev_co_u32_e32 v21, vcc, 0, v21, vcc
	v_lshl_add_u64 v[20:21], v[132:133], 0, v[20:21]
	v_add_co_u32_e32 v20, vcc, 0x20000, v20
	s_nop 1
	v_addc_co_u32_e32 v21, vcc, 0, v21, vcc
	global_store_dwordx2 v[20:21], v[18:19], off sc1
.LBB0_658:
	v_mov_b32_e32 v18, v14
	v_mov_b32_e32 v19, v2
	v_mov_b32_e32 v20, v46
	v_mov_b32_e32 v21, v30
	v_pk_add_f32 v[22:23], v[18:19], v[20:21]
	v_mov_b32_e32 v24, v42
	v_cvt_pk_bf16_f32 v26, v22, v23
	v_mov_b32_e32 v22, v10
	v_mov_b32_e32 v23, v6
	v_mov_b32_e32 v25, v34
	v_pk_add_f32 v[28:29], v[22:23], v[24:25]
	s_and_b64 vcc, exec, s[36:37]
	v_cvt_pk_bf16_f32 v27, v28, v29
	v_add_u32_e32 v28, 0xc00, v134
	v_ashrrev_i32_e32 v29, 31, v28
	v_lshlrev_b64 v[28:29], 11, v[28:29]
	v_lshl_add_u64 v[28:29], v[132:133], 0, v[28:29]
	global_store_dwordx2 v[28:29], v[26:27], off sc1
	s_cbranch_vccnz .LBB0_660
	v_pk_add_f32 v[18:19], v[18:19], v[20:21] neg_lo:[0,1] neg_hi:[0,1]
	v_pk_add_f32 v[20:21], v[22:23], v[24:25] neg_lo:[0,1] neg_hi:[0,1]
	v_cvt_pk_bf16_f32 v18, v18, v19
	v_cvt_pk_bf16_f32 v19, v20, v21
	v_sub_u32_e32 v20, 0x4f, v146
	v_ashrrev_i32_e32 v21, 31, v20
	v_lshlrev_b64 v[20:21], 17, v[20:21]
	v_subrev_co_u32_e32 v20, vcc, s20, v20
	s_nop 1
	v_subbrev_co_u32_e32 v21, vcc, 0, v21, vcc
	v_lshl_add_u64 v[20:21], v[132:133], 0, v[20:21]
	v_add_co_u32_e32 v20, vcc, 0x20000, v20
	s_nop 1
	v_addc_co_u32_e32 v21, vcc, 0, v21, vcc
	global_store_dwordx2 v[20:21], v[18:19], off sc1
.LBB0_660:
	v_mov_b32_e32 v2, v15
	v_mov_b32_e32 v30, v47
	v_pk_add_f32 v[14:15], v[2:3], v[30:31]
	v_mov_b32_e32 v6, v11
	v_mov_b32_e32 v34, v43
	v_cvt_pk_bf16_f32 v10, v14, v15
	v_pk_add_f32 v[14:15], v[6:7], v[34:35]
	s_and_b64 vcc, exec, s[36:37]
	v_cvt_pk_bf16_f32 v11, v14, v15
	v_add_u32_e32 v14, 0xc40, v134
	v_ashrrev_i32_e32 v15, 31, v14
	v_lshlrev_b64 v[14:15], 11, v[14:15]
	v_lshl_add_u64 v[14:15], v[132:133], 0, v[14:15]
	global_store_dwordx2 v[14:15], v[10:11], off sc1
	s_cbranch_vccnz .LBB0_662
	v_pk_add_f32 v[2:3], v[2:3], v[30:31] neg_lo:[0,1] neg_hi:[0,1]
	v_pk_add_f32 v[6:7], v[6:7], v[34:35] neg_lo:[0,1] neg_hi:[0,1]
	v_cvt_pk_bf16_f32 v2, v2, v3
	v_cvt_pk_bf16_f32 v3, v6, v7
	v_sub_u32_e32 v6, 0x4e, v146
	v_ashrrev_i32_e32 v7, 31, v6
	v_lshlrev_b64 v[6:7], 17, v[6:7]
	v_subrev_co_u32_e32 v6, vcc, s20, v6
	s_nop 1
	v_subbrev_co_u32_e32 v7, vcc, 0, v7, vcc
	v_lshl_add_u64 v[6:7], v[132:133], 0, v[6:7]
	v_add_co_u32_e32 v6, vcc, 0x20000, v6
	s_nop 1
	v_addc_co_u32_e32 v7, vcc, 0, v7, vcc
	global_store_dwordx2 v[6:7], v[2:3], off sc1
.LBB0_662:
	v_mov_b32_e32 v2, v16
	v_mov_b32_e32 v3, v4
	v_mov_b32_e32 v6, v48
	v_mov_b32_e32 v7, v32
	v_pk_add_f32 v[10:11], v[2:3], v[6:7]
	v_mov_b32_e32 v14, v44
	v_cvt_pk_bf16_f32 v18, v10, v11
	v_mov_b32_e32 v10, v12
	v_mov_b32_e32 v11, v8
	v_mov_b32_e32 v15, v36
	v_pk_add_f32 v[20:21], v[10:11], v[14:15]
	s_and_b64 vcc, exec, s[36:37]
	v_cvt_pk_bf16_f32 v19, v20, v21
	v_add_u32_e32 v20, 0xc80, v134
	v_ashrrev_i32_e32 v21, 31, v20
	v_lshlrev_b64 v[20:21], 11, v[20:21]
	v_lshl_add_u64 v[20:21], v[132:133], 0, v[20:21]
	global_store_dwordx2 v[20:21], v[18:19], off sc1
	s_cbranch_vccnz .LBB0_664
	v_pk_add_f32 v[2:3], v[2:3], v[6:7] neg_lo:[0,1] neg_hi:[0,1]
	v_pk_add_f32 v[6:7], v[10:11], v[14:15] neg_lo:[0,1] neg_hi:[0,1]
	v_cvt_pk_bf16_f32 v2, v2, v3
	v_cvt_pk_bf16_f32 v3, v6, v7
	v_sub_u32_e32 v6, 0x4d, v146
	v_ashrrev_i32_e32 v7, 31, v6
	v_lshlrev_b64 v[6:7], 17, v[6:7]
	v_subrev_co_u32_e32 v6, vcc, s20, v6
	s_nop 1
	v_subbrev_co_u32_e32 v7, vcc, 0, v7, vcc
	v_lshl_add_u64 v[6:7], v[132:133], 0, v[6:7]
	v_add_co_u32_e32 v6, vcc, 0x20000, v6
	s_nop 1
	v_addc_co_u32_e32 v7, vcc, 0, v7, vcc
	global_store_dwordx2 v[6:7], v[2:3], off sc1
.LBB0_664:
	v_mov_b32_e32 v4, v17
	v_mov_b32_e32 v32, v49
	v_mov_b32_e32 v8, v13
	v_mov_b32_e32 v36, v45
	v_pk_add_f32 v[2:3], v[4:5], v[32:33]
	v_pk_add_f32 v[6:7], v[8:9], v[36:37]
	v_cvt_pk_bf16_f32 v2, v2, v3
	v_cvt_pk_bf16_f32 v3, v6, v7
	v_add_u32_e32 v6, 0xcc0, v134
	v_ashrrev_i32_e32 v7, 31, v6
	v_lshlrev_b64 v[6:7], 11, v[6:7]
	v_lshl_add_u64 v[6:7], v[132:133], 0, v[6:7]
	s_and_b64 vcc, exec, s[36:37]
	global_store_dwordx2 v[6:7], v[2:3], off sc1
	s_cbranch_vccnz .LBB0_666
	v_pk_add_f32 v[2:3], v[4:5], v[32:33] neg_lo:[0,1] neg_hi:[0,1]
	v_pk_add_f32 v[4:5], v[8:9], v[36:37] neg_lo:[0,1] neg_hi:[0,1]
	v_cvt_pk_bf16_f32 v2, v2, v3
	v_cvt_pk_bf16_f32 v3, v4, v5
	v_sub_u32_e32 v6, 0x4c, v146
	s_mov_b64 s[10:11], -1
.LBB0_666:
	s_and_b64 vcc, exec, s[10:11]
	s_cbranch_vccz .LBB0_590
	s_waitcnt vmcnt(0)
	v_ashrrev_i32_e32 v7, 31, v6
	v_lshlrev_b64 v[4:5], 17, v[6:7]
	v_subrev_co_u32_e32 v4, vcc, s20, v4
	s_nop 1
	v_subbrev_co_u32_e32 v5, vcc, 0, v5, vcc
	v_lshl_add_u64 v[4:5], v[132:133], 0, v[4:5]
	v_add_co_u32_e32 v4, vcc, 0x20000, v4
	s_nop 1
	v_addc_co_u32_e32 v5, vcc, 0, v5, vcc
	global_store_dwordx2 v[4:5], v[2:3], off sc1
	s_branch .LBB0_590

.LBB0_676:
	s_lshl_b32 s4, s15, 14
	s_add_i32 s20, s41, 0
	s_or_b32 s4, s4, s27
	v_readlane_b32 s5, v254, 21
	s_add_u32 s12, s5, s4
	v_readlane_b32 s4, v254, 22
	s_addc_u32 s13, s4, 0
	s_or_b32 s10, s0, s14
	s_ashr_i32 s11, s10, 31
	s_lshl_b64 s[10:11], s[10:11], 11
	v_readlane_b32 s0, v254, 23
	s_add_u32 s0, s0, s10
	v_readlane_b32 s4, v254, 24
	s_addc_u32 s4, s4, s11
	s_lshl_b32 s21, s1, 1
	s_add_u32 s0, s0, s21
	s_addc_u32 s1, s4, 0
	v_lshlrev_b32_e32 v98, 1, v148
	v_lshl_add_u64 v[132:133], s[0:1], 0, v[98:99]
	s_movk_i32 s0, 0x440
	v_lshl_add_u32 v98, v149, 3, s20
	v_cvt_pk_bf16_f32 v137, v120, v116
	v_mul_lo_u32 v116, v211, s0
	v_add_u32_e32 v146, v98, v116
	v_cvt_pk_bf16_f32 v116, v129, v125
	v_cvt_pk_bf16_f32 v117, v121, v117
	v_cvt_pk_bf16_f32 v121, v122, v118
	v_cvt_pk_bf16_f32 v122, v82, v86
	v_cvt_pk_bf16_f32 v82, v83, v87
	v_cvt_pk_bf16_f32 v83, v91, v95
	v_cvt_pk_bf16_f32 v120, v130, v126
	ds_write2_b64 v146, v[116:117], v[82:83] offset0:34 offset1:50
	v_cvt_pk_bf16_f32 v82, v84, v88
	v_cvt_pk_bf16_f32 v83, v92, v96
	v_cvt_pk_bf16_f32 v119, v123, v119
	v_cvt_pk_bf16_f32 v123, v90, v94
	ds_write2_b64 v146, v[120:121], v[82:83] offset0:68 offset1:84
	v_cvt_pk_bf16_f32 v82, v85, v89
	v_cvt_pk_bf16_f32 v84, v113, v109
	v_cvt_pk_bf16_f32 v85, v105, v101
	v_cvt_pk_bf16_f32 v90, v66, v70
	v_add_u32_e32 v147, 0x1000, v146
	v_cvt_pk_bf16_f32 v66, v67, v71
	v_cvt_pk_bf16_f32 v67, v75, v79
	v_cvt_pk_bf16_f32 v118, v131, v127
	v_cvt_pk_bf16_f32 v83, v93, v97
	v_cvt_pk_bf16_f32 v86, v114, v110
	v_cvt_pk_bf16_f32 v87, v106, v102
	ds_write2_b64 v147, v[84:85], v[66:67] offset0:66 offset1:82
	v_cvt_pk_bf16_f32 v66, v68, v72
	v_cvt_pk_bf16_f32 v67, v76, v80
	v_cvt_pk_bf16_f32 v136, v128, v124
	ds_write2_b64 v146, v[118:119], v[82:83] offset0:102 offset1:118
	v_cvt_pk_bf16_f32 v82, v112, v108
	v_cvt_pk_bf16_f32 v83, v104, v100
	v_cvt_pk_bf16_f32 v88, v115, v111
	v_cvt_pk_bf16_f32 v89, v107, v103
	v_cvt_pk_bf16_f32 v91, v74, v78
	ds_write2_b64 v147, v[86:87], v[66:67] offset0:100 offset1:116
	v_cvt_pk_bf16_f32 v66, v69, v73
	v_cvt_pk_bf16_f32 v67, v77, v81
	ds_write2_b64 v146, v[136:137], v[122:123] offset1:16
	ds_write2_b64 v147, v[82:83], v[90:91] offset0:32 offset1:48
	ds_write2_b64 v147, v[88:89], v[66:67] offset0:134 offset1:150
	v_lshl_add_u64 v[134:135], v[150:151], 1, s[12:13]
	s_waitcnt lgkmcnt(0)
	v_lshlrev_b32_e32 v98, 10, v149
	v_lshl_add_u64 v[136:137], v[134:135], 0, v[98:99]
	global_load_dwordx4 v[78:81], v[136:137], off offset:256
	global_load_dwordx4 v[120:123], v[136:137], off offset:320
	global_load_dwordx4 v[66:69], v[136:137], off
	global_load_dwordx4 v[116:119], v[136:137], off offset:64
	global_load_dwordx4 v[86:89], v[136:137], off offset:512
	global_load_dwordx4 v[94:97], v[136:137], off offset:768
	v_and_b32_e32 v70, -16, v212
	v_add_u32_e32 v148, s20, v70
	s_movk_i32 s0, 0x110
	v_mad_u32_u24 v98, v149, s0, v148
	ds_read_b128 v[70:73], v98
	ds_read_b128 v[108:111], v98 offset:64
	ds_read_b128 v[100:103], v98 offset:4352
	ds_read_b128 v[124:127], v98 offset:4416
	ds_read_b128 v[138:141], v98 offset:4480
	s_add_i32 s0, s14, -1
	s_cmp_lt_u32 s0, 31
	s_cselect_b64 s[0:1], -1, 0
	s_lshl_b32 s10, s14, 12
	s_and_b64 vcc, exec, s[0:1]
	s_waitcnt vmcnt(5) lgkmcnt(4)
	v_mfma_f32_16x16x32_bf16 v[82:85], v[70:73], v[78:81], 0
	global_load_dwordx4 v[128:131], v[136:137], off offset:896
	global_load_dwordx4 v[162:165], v[136:137], off offset:960
	ds_read_b128 v[154:157], v98 offset:192
	s_waitcnt vmcnt(5)
	v_mfma_f32_16x16x32_bf16 v[74:77], v[70:73], v[66:69], 0
	global_load_dwordx4 v[158:161], v[136:137], off offset:704
	s_waitcnt vmcnt(4)
	v_mfma_f32_16x16x32_bf16 v[90:93], v[70:73], v[86:89], 0
	s_waitcnt vmcnt(3)
	v_mfma_f32_16x16x32_bf16 v[70:73], v[70:73], v[94:97], 0
	s_waitcnt lgkmcnt(3)
	v_mfma_f32_16x16x32_bf16 v[66:69], v[100:103], v[66:69], 0
	v_mfma_f32_16x16x32_bf16 v[78:81], v[100:103], v[78:81], 0
	v_mfma_f32_16x16x32_bf16 v[86:89], v[100:103], v[86:89], 0
	v_mfma_f32_16x16x32_bf16 v[94:97], v[100:103], v[94:97], 0
	v_mfma_f32_16x16x32_bf16 v[100:103], v[108:111], v[120:123], v[82:85]
	s_nop 2
	global_load_dwordx4 v[82:85], v[136:137], off offset:576
	s_waitcnt vmcnt(0)
	v_mfma_f32_16x16x32_bf16 v[112:115], v[108:111], v[82:85], v[90:93]
	s_nop 2
	global_load_dwordx4 v[90:93], v[136:137], off offset:832
	v_mfma_f32_16x16x32_bf16 v[104:107], v[108:111], v[116:119], v[74:77]
	s_waitcnt lgkmcnt(2)
	v_mfma_f32_16x16x32_bf16 v[74:77], v[124:127], v[116:119], v[66:69]
	v_mfma_f32_16x16x32_bf16 v[66:69], v[124:127], v[120:123], v[78:81]
	global_load_dwordx4 v[120:123], v[136:137], off offset:640
	s_waitcnt vmcnt(1)
	v_mfma_f32_16x16x32_bf16 v[78:81], v[124:127], v[90:93], v[94:97]
	s_nop 2
	global_load_dwordx4 v[94:97], v[136:137], off offset:384
	v_mfma_f32_16x16x32_bf16 v[108:111], v[108:111], v[90:93], v[70:73]
	v_mfma_f32_16x16x32_bf16 v[70:73], v[124:127], v[82:85], v[86:89]
	global_load_dwordx4 v[82:85], v[136:137], off offset:128
	s_nop 1
	ds_read_b128 v[86:89], v98 offset:128
	s_waitcnt vmcnt(1) lgkmcnt(0)
	v_mfma_f32_16x16x32_bf16 v[116:119], v[86:89], v[94:97], 0
	v_mfma_f32_16x16x32_bf16 v[142:145], v[138:141], v[94:97], 0
	global_load_dwordx4 v[94:97], v[136:137], off offset:192
	s_waitcnt vmcnt(1)
	v_mfma_f32_16x16x32_bf16 v[90:93], v[86:89], v[82:85], 0
	v_mfma_f32_16x16x32_bf16 v[124:127], v[86:89], v[120:123], 0
	v_mfma_f32_16x16x32_bf16 v[150:153], v[138:141], v[120:123], 0
	s_waitcnt vmcnt(0)
	v_mfma_f32_16x16x32_bf16 v[120:123], v[154:157], v[94:97], v[90:93]
	s_nop 3
	global_load_dwordx4 v[90:93], v[136:137], off offset:448
	v_mfma_f32_16x16x32_bf16 v[86:89], v[86:89], v[128:131], 0
	v_mfma_f32_16x16x32_bf16 v[82:85], v[138:141], v[82:85], 0
	v_mfma_f32_16x16x32_bf16 v[138:141], v[138:141], v[128:131], 0
	v_mfma_f32_16x16x32_bf16 v[128:131], v[154:157], v[158:161], v[124:127]
	v_mfma_f32_16x16x32_bf16 v[124:127], v[154:157], v[162:165], v[86:89]
	s_nop 3
	ds_read_b128 v[86:89], v98 offset:4544
	s_waitcnt vmcnt(0)
	v_mfma_f32_16x16x32_bf16 v[116:119], v[154:157], v[90:93], v[116:119]
	s_waitcnt lgkmcnt(0)
	v_lshlrev_b32_e32 v98, 2, v211
	s_waitcnt lgkmcnt(0)
	v_mfma_f32_16x16x32_bf16 v[94:97], v[86:89], v[94:97], v[82:85]
	v_mfma_f32_16x16x32_bf16 v[82:85], v[86:89], v[90:93], v[142:145]
	v_mfma_f32_16x16x32_bf16 v[90:93], v[86:89], v[158:161], v[150:153]
	s_nop 1
	v_mov_b32_e32 v142, v112
	v_mov_b32_e32 v143, v108
	v_mov_b32_e32 v144, v128
	v_mfma_f32_16x16x32_bf16 v[86:89], v[86:89], v[162:165], v[138:141]
	v_mov_b32_e32 v145, v124
	s_nop 1
	v_mov_b32_e32 v138, v104
	v_mov_b32_e32 v139, v100
	v_mov_b32_e32 v140, v120
	v_mov_b32_e32 v141, v116
	v_pk_add_f32 v[134:135], v[138:139], v[140:141]
	s_nop 0
	v_cvt_pk_bf16_f32 v150, v134, v135
	v_pk_add_f32 v[134:135], v[142:143], v[144:145]
	s_nop 0
	v_cvt_pk_bf16_f32 v151, v134, v135
	v_lshlrev_b32_e32 v134, 8, v211
	v_ashrrev_i32_e32 v135, 31, v134
	v_lshlrev_b64 v[152:153], 11, v[134:135]
	v_lshl_add_u64 v[152:153], v[132:133], 0, v[152:153]
	global_store_dwordx2 v[152:153], v[150:151], off sc1
	s_cbranch_vccz .LBB0_678
	v_pk_add_f32 v[138:139], v[138:139], v[140:141] neg_lo:[0,1] neg_hi:[0,1]
	v_pk_add_f32 v[140:141], v[142:143], v[144:145] neg_lo:[0,1] neg_hi:[0,1]
	v_cvt_pk_bf16_f32 v138, v138, v139
	v_cvt_pk_bf16_f32 v139, v140, v141
	v_sub_u32_e32 v140, 63, v98
	v_ashrrev_i32_e32 v141, 31, v140
	v_lshlrev_b64 v[140:141], 17, v[140:141]
	v_subrev_co_u32_e32 v140, vcc, s10, v140
	s_nop 1
	v_subbrev_co_u32_e32 v141, vcc, 0, v141, vcc
	v_lshl_add_u64 v[140:141], v[132:133], 0, v[140:141]
	v_add_co_u32_e32 v140, vcc, 0x20000, v140
	s_nop 1
	v_addc_co_u32_e32 v141, vcc, 0, v141, vcc
	global_store_dwordx2 v[140:141], v[138:139], off sc1
.LBB0_678:
	v_mov_b32_e32 v100, v105
	v_mov_b32_e32 v116, v121
	v_mov_b32_e32 v108, v113
	v_mov_b32_e32 v124, v129
	v_pk_add_f32 v[104:105], v[100:101], v[116:117]
	v_pk_add_f32 v[112:113], v[108:109], v[124:125]
	v_cvt_pk_bf16_f32 v104, v104, v105
	v_cvt_pk_bf16_f32 v105, v112, v113
	v_or_b32_e32 v112, 64, v134
	v_ashrrev_i32_e32 v113, 31, v112
	v_lshlrev_b64 v[112:113], 11, v[112:113]
	v_cndmask_b32_e64 v120, 0, 1, s[0:1]
	v_lshl_add_u64 v[112:113], v[132:133], 0, v[112:113]
	v_cmp_ne_u32_e64 s[36:37], 1, v120
	s_andn2_b64 vcc, exec, s[0:1]
	global_store_dwordx2 v[112:113], v[104:105], off sc1
	s_cbranch_vccnz .LBB0_680
	v_pk_add_f32 v[100:101], v[100:101], v[116:117] neg_lo:[0,1] neg_hi:[0,1]
	v_pk_add_f32 v[104:105], v[108:109], v[124:125] neg_lo:[0,1] neg_hi:[0,1]
	v_cvt_pk_bf16_f32 v100, v100, v101
	v_cvt_pk_bf16_f32 v101, v104, v105
	v_xor_b32_e32 v104, -2, v98
	v_ashrrev_i32_e32 v105, 31, v104
	v_lshlrev_b64 v[104:105], 17, v[104:105]
	v_subrev_co_u32_e32 v104, vcc, s10, v104
	s_nop 1
	v_subbrev_co_u32_e32 v105, vcc, 0, v105, vcc
	v_lshl_add_u64 v[104:105], v[132:133], 0, v[104:105]
	v_add_co_u32_e32 v104, vcc, 0x820000, v104
	s_nop 1
	v_addc_co_u32_e32 v105, vcc, 0, v105, vcc
	global_store_dwordx2 v[104:105], v[100:101], off sc1
.LBB0_680:
	v_mov_b32_e32 v100, v106
	v_mov_b32_e32 v101, v102
	v_mov_b32_e32 v104, v122
	v_mov_b32_e32 v105, v118
	v_pk_add_f32 v[108:109], v[100:101], v[104:105]
	v_mov_b32_e32 v112, v130
	v_cvt_pk_bf16_f32 v116, v108, v109
	v_mov_b32_e32 v108, v114
	v_mov_b32_e32 v109, v110
	v_mov_b32_e32 v113, v126
	v_pk_add_f32 v[120:121], v[108:109], v[112:113]
	s_and_b64 vcc, exec, s[36:37]
	v_cvt_pk_bf16_f32 v117, v120, v121
	v_or_b32_e32 v120, 0x80, v134
	v_ashrrev_i32_e32 v121, 31, v120
	v_lshlrev_b64 v[120:121], 11, v[120:121]
	v_lshl_add_u64 v[120:121], v[132:133], 0, v[120:121]
	global_store_dwordx2 v[120:121], v[116:117], off sc1
	s_cbranch_vccnz .LBB0_682
	v_pk_add_f32 v[100:101], v[100:101], v[104:105] neg_lo:[0,1] neg_hi:[0,1]
	v_pk_add_f32 v[104:105], v[108:109], v[112:113] neg_lo:[0,1] neg_hi:[0,1]
	v_cvt_pk_bf16_f32 v100, v100, v101
	v_cvt_pk_bf16_f32 v101, v104, v105
	v_xor_b32_e32 v104, -3, v98
	v_ashrrev_i32_e32 v105, 31, v104
	v_lshlrev_b64 v[104:105], 17, v[104:105]
	v_subrev_co_u32_e32 v104, vcc, s10, v104
	s_nop 1
	v_subbrev_co_u32_e32 v105, vcc, 0, v105, vcc
	v_lshl_add_u64 v[104:105], v[132:133], 0, v[104:105]
	v_add_co_u32_e32 v104, vcc, 0x820000, v104
	s_nop 1
	v_addc_co_u32_e32 v105, vcc, 0, v105, vcc
	global_store_dwordx2 v[104:105], v[100:101], off sc1
.LBB0_682:
	v_mov_b32_e32 v102, v107
	v_mov_b32_e32 v118, v123
	v_mov_b32_e32 v110, v115
	v_mov_b32_e32 v126, v131
	v_pk_add_f32 v[100:101], v[102:103], v[118:119]
	v_pk_add_f32 v[104:105], v[110:111], v[126:127]
	v_cvt_pk_bf16_f32 v100, v100, v101
	v_cvt_pk_bf16_f32 v101, v104, v105
	v_or_b32_e32 v104, 0xc0, v134
	v_ashrrev_i32_e32 v105, 31, v104
	v_lshlrev_b64 v[104:105], 11, v[104:105]
	v_lshl_add_u64 v[104:105], v[132:133], 0, v[104:105]
	s_and_b64 vcc, exec, s[36:37]
	global_store_dwordx2 v[104:105], v[100:101], off sc1
	s_cbranch_vccnz .LBB0_684
	v_pk_add_f32 v[100:101], v[102:103], v[118:119] neg_lo:[0,1] neg_hi:[0,1]
	v_pk_add_f32 v[102:103], v[110:111], v[126:127] neg_lo:[0,1] neg_hi:[0,1]
	v_cvt_pk_bf16_f32 v100, v100, v101
	v_cvt_pk_bf16_f32 v101, v102, v103
	v_xor_b32_e32 v102, -4, v98
	v_ashrrev_i32_e32 v103, 31, v102
	v_lshlrev_b64 v[102:103], 17, v[102:103]
	v_subrev_co_u32_e32 v102, vcc, s10, v102
	s_nop 1
	v_subbrev_co_u32_e32 v103, vcc, 0, v103, vcc
	v_lshl_add_u64 v[102:103], v[132:133], 0, v[102:103]
	v_add_co_u32_e32 v102, vcc, 0x820000, v102
	s_nop 1
	v_addc_co_u32_e32 v103, vcc, 0, v103, vcc
	global_store_dwordx2 v[102:103], v[100:101], off sc1
.LBB0_684:
	v_mov_b32_e32 v100, v74
	v_mov_b32_e32 v101, v66
	v_mov_b32_e32 v102, v94
	v_mov_b32_e32 v103, v82
	v_pk_add_f32 v[104:105], v[100:101], v[102:103]
	v_mov_b32_e32 v106, v90
	v_cvt_pk_bf16_f32 v108, v104, v105
	v_mov_b32_e32 v104, v70
	v_mov_b32_e32 v105, v78
	v_mov_b32_e32 v107, v86
	v_pk_add_f32 v[110:111], v[104:105], v[106:107]
	s_and_b64 vcc, exec, s[36:37]
	v_cvt_pk_bf16_f32 v109, v110, v111
	v_add_u32_e32 v110, 0x400, v134
	v_ashrrev_i32_e32 v111, 31, v110
	v_lshlrev_b64 v[110:111], 11, v[110:111]
	v_lshl_add_u64 v[110:111], v[132:133], 0, v[110:111]
	global_store_dwordx2 v[110:111], v[108:109], off sc1
	s_cbranch_vccnz .LBB0_686
	v_pk_add_f32 v[100:101], v[100:101], v[102:103] neg_lo:[0,1] neg_hi:[0,1]
	v_pk_add_f32 v[102:103], v[104:105], v[106:107] neg_lo:[0,1] neg_hi:[0,1]
	v_cvt_pk_bf16_f32 v100, v100, v101
	v_cvt_pk_bf16_f32 v101, v102, v103
	v_sub_u32_e32 v102, 47, v98
	v_ashrrev_i32_e32 v103, 31, v102
	v_lshlrev_b64 v[102:103], 17, v[102:103]
	v_subrev_co_u32_e32 v102, vcc, s10, v102
	s_nop 1
	v_subbrev_co_u32_e32 v103, vcc, 0, v103, vcc
	v_lshl_add_u64 v[102:103], v[132:133], 0, v[102:103]
	v_add_co_u32_e32 v102, vcc, 0x20000, v102
	s_nop 1
	v_addc_co_u32_e32 v103, vcc, 0, v103, vcc
	global_store_dwordx2 v[102:103], v[100:101], off sc1
.LBB0_686:
	v_mov_b32_e32 v66, v75
	v_mov_b32_e32 v82, v95
	v_pk_add_f32 v[74:75], v[66:67], v[82:83]
	v_mov_b32_e32 v78, v71
	v_mov_b32_e32 v86, v91
	v_cvt_pk_bf16_f32 v70, v74, v75
	v_pk_add_f32 v[74:75], v[78:79], v[86:87]
	s_and_b64 vcc, exec, s[36:37]
	v_cvt_pk_bf16_f32 v71, v74, v75
	v_add_u32_e32 v74, 0x440, v134
	v_ashrrev_i32_e32 v75, 31, v74
	v_lshlrev_b64 v[74:75], 11, v[74:75]
	v_lshl_add_u64 v[74:75], v[132:133], 0, v[74:75]
	global_store_dwordx2 v[74:75], v[70:71], off sc1
	s_cbranch_vccnz .LBB0_688
	v_pk_add_f32 v[66:67], v[66:67], v[82:83] neg_lo:[0,1] neg_hi:[0,1]
	v_pk_add_f32 v[70:71], v[78:79], v[86:87] neg_lo:[0,1] neg_hi:[0,1]
	v_cvt_pk_bf16_f32 v66, v66, v67
	v_cvt_pk_bf16_f32 v67, v70, v71
	v_sub_u32_e32 v70, 46, v98
	v_ashrrev_i32_e32 v71, 31, v70
	v_lshlrev_b64 v[70:71], 17, v[70:71]
	v_subrev_co_u32_e32 v70, vcc, s10, v70
	s_nop 1
	v_subbrev_co_u32_e32 v71, vcc, 0, v71, vcc
	v_lshl_add_u64 v[70:71], v[132:133], 0, v[70:71]
	v_add_co_u32_e32 v70, vcc, 0x20000, v70
	s_nop 1
	v_addc_co_u32_e32 v71, vcc, 0, v71, vcc
	global_store_dwordx2 v[70:71], v[66:67], off sc1
.LBB0_688:
	v_mov_b32_e32 v66, v76
	v_mov_b32_e32 v67, v68
	v_mov_b32_e32 v70, v96
	v_mov_b32_e32 v71, v84
	v_pk_add_f32 v[74:75], v[66:67], v[70:71]
	v_mov_b32_e32 v78, v92
	v_cvt_pk_bf16_f32 v82, v74, v75
	v_mov_b32_e32 v74, v72
	v_mov_b32_e32 v75, v80
	v_mov_b32_e32 v79, v88
	v_pk_add_f32 v[86:87], v[74:75], v[78:79]
	s_and_b64 vcc, exec, s[36:37]
	v_cvt_pk_bf16_f32 v83, v86, v87
	v_add_u32_e32 v86, 0x480, v134
	v_ashrrev_i32_e32 v87, 31, v86
	v_lshlrev_b64 v[86:87], 11, v[86:87]
	v_lshl_add_u64 v[86:87], v[132:133], 0, v[86:87]
	global_store_dwordx2 v[86:87], v[82:83], off sc1
	s_cbranch_vccnz .LBB0_690
	v_pk_add_f32 v[66:67], v[66:67], v[70:71] neg_lo:[0,1] neg_hi:[0,1]
	v_pk_add_f32 v[70:71], v[74:75], v[78:79] neg_lo:[0,1] neg_hi:[0,1]
	v_cvt_pk_bf16_f32 v66, v66, v67
	v_cvt_pk_bf16_f32 v67, v70, v71
	v_sub_u32_e32 v70, 45, v98
	v_ashrrev_i32_e32 v71, 31, v70
	v_lshlrev_b64 v[70:71], 17, v[70:71]
	v_subrev_co_u32_e32 v70, vcc, s10, v70
	s_nop 1
	v_subbrev_co_u32_e32 v71, vcc, 0, v71, vcc
	v_lshl_add_u64 v[70:71], v[132:133], 0, v[70:71]
	v_add_co_u32_e32 v70, vcc, 0x20000, v70
	s_nop 1
	v_addc_co_u32_e32 v71, vcc, 0, v71, vcc
	global_store_dwordx2 v[70:71], v[66:67], off sc1
.LBB0_690:
	v_mov_b32_e32 v68, v77
	v_mov_b32_e32 v84, v97
	v_mov_b32_e32 v80, v73
	v_mov_b32_e32 v88, v93
	v_pk_add_f32 v[66:67], v[68:69], v[84:85]
	v_pk_add_f32 v[70:71], v[80:81], v[88:89]
	v_cvt_pk_bf16_f32 v66, v66, v67
	v_cvt_pk_bf16_f32 v67, v70, v71
	v_add_u32_e32 v70, 0x4c0, v134
	v_ashrrev_i32_e32 v71, 31, v70
	v_lshlrev_b64 v[70:71], 11, v[70:71]
	v_lshl_add_u64 v[70:71], v[132:133], 0, v[70:71]
	s_and_b64 vcc, exec, s[36:37]
	global_store_dwordx2 v[70:71], v[66:67], off sc1
	s_cbranch_vccnz .LBB0_692
	v_pk_add_f32 v[66:67], v[68:69], v[84:85] neg_lo:[0,1] neg_hi:[0,1]
	v_pk_add_f32 v[68:69], v[80:81], v[88:89] neg_lo:[0,1] neg_hi:[0,1]
	v_cvt_pk_bf16_f32 v66, v66, v67
	v_cvt_pk_bf16_f32 v67, v68, v69
	v_sub_u32_e32 v68, 44, v98
	v_ashrrev_i32_e32 v69, 31, v68
	v_lshlrev_b64 v[68:69], 17, v[68:69]
	v_subrev_co_u32_e32 v68, vcc, s10, v68
	s_nop 1
	v_subbrev_co_u32_e32 v69, vcc, 0, v69, vcc
	v_lshl_add_u64 v[68:69], v[132:133], 0, v[68:69]
	v_add_co_u32_e32 v68, vcc, 0x20000, v68
	s_nop 1
	v_addc_co_u32_e32 v69, vcc, 0, v69, vcc
	global_store_dwordx2 v[68:69], v[66:67], off sc1
.LBB0_692:
	v_cvt_pk_bf16_f32 v66, v46, v54
	v_cvt_pk_bf16_f32 v46, v47, v55
	v_cvt_pk_bf16_f32 v47, v59, v63
	v_cvt_pk_bf16_f32 v54, v48, v56
	v_cvt_pk_bf16_f32 v56, v18, v22
	v_cvt_pk_bf16_f32 v18, v19, v23
	v_cvt_pk_bf16_f32 v19, v27, v31
	v_cvt_pk_bf16_f32 v55, v60, v64
	ds_write2_b64 v146, v[46:47], v[18:19] offset0:34 offset1:50
	v_cvt_pk_bf16_f32 v18, v20, v24
	v_cvt_pk_bf16_f32 v19, v28, v32
	ds_write2_b64 v146, v[54:55], v[18:19] offset0:68 offset1:84
	v_cvt_pk_bf16_f32 v18, v21, v25
	v_cvt_pk_bf16_f32 v20, v35, v39
	v_cvt_pk_bf16_f32 v21, v43, v51
	v_cvt_pk_bf16_f32 v27, v6, v2
	v_cvt_pk_bf16_f32 v2, v15, v11
	v_cvt_pk_bf16_f32 v3, v7, v3
	v_cvt_pk_bf16_f32 v48, v49, v57
	v_cvt_pk_bf16_f32 v49, v61, v65
	v_cvt_pk_bf16_f32 v19, v29, v33
	v_cvt_pk_bf16_f32 v22, v36, v40
	v_cvt_pk_bf16_f32 v23, v44, v52
	ds_write2_b64 v147, v[20:21], v[2:3] offset0:66 offset1:82
	v_cvt_pk_bf16_f32 v2, v16, v12
	v_cvt_pk_bf16_f32 v3, v8, v4
	v_cvt_pk_bf16_f32 v67, v58, v62
	v_cvt_pk_bf16_f32 v57, v26, v30
	ds_write2_b64 v146, v[48:49], v[18:19] offset0:102 offset1:118
	v_cvt_pk_bf16_f32 v18, v34, v38
	v_cvt_pk_bf16_f32 v19, v42, v50
	v_cvt_pk_bf16_f32 v24, v37, v41
	v_cvt_pk_bf16_f32 v25, v45, v53
	v_cvt_pk_bf16_f32 v26, v14, v10
	ds_write2_b64 v147, v[22:23], v[2:3] offset0:100 offset1:116
	v_cvt_pk_bf16_f32 v2, v17, v13
	v_cvt_pk_bf16_f32 v3, v9, v5
	ds_write2_b64 v146, v[66:67], v[56:57] offset1:16
	ds_write2_b64 v147, v[18:19], v[26:27] offset0:32 offset1:48
	ds_write2_b64 v147, v[24:25], v[2:3] offset0:134 offset1:150
	v_mul_u32_u24_e32 v68, 0x110, v149
	s_waitcnt lgkmcnt(0)
	v_add_u32_e32 v82, v148, v68
	ds_read_b128 v[2:5], v82
	ds_read_b128 v[6:9], v82 offset:4352
	global_load_dwordx4 v[10:13], v[136:137], off
	global_load_dwordx4 v[14:17], v[136:137], off offset:256
	global_load_dwordx4 v[18:21], v[136:137], off offset:512
	global_load_dwordx4 v[22:25], v[136:137], off offset:768
	s_and_b64 vcc, exec, s[36:37]
	s_waitcnt vmcnt(3) lgkmcnt(1)
	v_mfma_f32_16x16x32_bf16 v[26:29], v[2:5], v[10:13], 0
	s_waitcnt vmcnt(2)
	v_mfma_f32_16x16x32_bf16 v[34:37], v[2:5], v[14:17], 0
	s_waitcnt lgkmcnt(0)
	v_mfma_f32_16x16x32_bf16 v[42:45], v[6:9], v[14:17], 0
	ds_read_b128 v[14:17], v82 offset:64
	ds_read_b128 v[50:53], v82 offset:4416
	global_load_dwordx4 v[54:57], v[136:137], off offset:64
	global_load_dwordx4 v[58:61], v[136:137], off offset:320
	global_load_dwordx4 v[62:65], v[136:137], off offset:576
	global_load_dwordx4 v[66:69], v[136:137], off offset:832
	s_waitcnt vmcnt(5)
	v_mfma_f32_16x16x32_bf16 v[38:41], v[2:5], v[18:21], 0
	s_waitcnt vmcnt(4)
	v_mfma_f32_16x16x32_bf16 v[2:5], v[2:5], v[22:25], 0
	v_mfma_f32_16x16x32_bf16 v[10:13], v[6:9], v[10:13], 0
	v_mfma_f32_16x16x32_bf16 v[46:49], v[6:9], v[18:21], 0
	v_mfma_f32_16x16x32_bf16 v[6:9], v[6:9], v[22:25], 0
	s_waitcnt vmcnt(3) lgkmcnt(1)
	v_mfma_f32_16x16x32_bf16 v[30:33], v[14:17], v[54:57], v[26:29]
	s_waitcnt vmcnt(2)
	v_mfma_f32_16x16x32_bf16 v[18:21], v[14:17], v[58:61], v[34:37]
	s_waitcnt vmcnt(1)
	v_mfma_f32_16x16x32_bf16 v[26:29], v[14:17], v[62:65], v[38:41]
	s_nop 0
	ds_read_b128 v[34:37], v82 offset:128
	s_nop 0
	ds_read_b128 v[38:41], v82 offset:4480
	s_waitcnt vmcnt(0)
	v_mfma_f32_16x16x32_bf16 v[22:25], v[14:17], v[66:69], v[2:5]
	s_waitcnt lgkmcnt(2)
	v_mfma_f32_16x16x32_bf16 v[14:17], v[50:53], v[54:57], v[10:13]
	v_mfma_f32_16x16x32_bf16 v[2:5], v[50:53], v[58:61], v[42:45]
	v_mfma_f32_16x16x32_bf16 v[10:13], v[50:53], v[62:65], v[46:49]
	v_mfma_f32_16x16x32_bf16 v[6:9], v[50:53], v[66:69], v[6:9]
	s_nop 0
	global_load_dwordx4 v[42:45], v[136:137], off offset:128
	global_load_dwordx4 v[46:49], v[136:137], off offset:384
	global_load_dwordx4 v[50:53], v[136:137], off offset:640
	global_load_dwordx4 v[54:57], v[136:137], off offset:896
	s_waitcnt vmcnt(3) lgkmcnt(1)
	v_mfma_f32_16x16x32_bf16 v[58:61], v[34:37], v[42:45], 0
	s_waitcnt vmcnt(2)
	v_mfma_f32_16x16x32_bf16 v[66:69], v[34:37], v[46:49], 0
	s_waitcnt lgkmcnt(0)
	v_mfma_f32_16x16x32_bf16 v[74:77], v[38:41], v[46:49], 0
	ds_read_b128 v[46:49], v82 offset:192
	ds_read_b128 v[82:85], v82 offset:4544
	global_load_dwordx4 v[86:89], v[136:137], off offset:192
	global_load_dwordx4 v[90:93], v[136:137], off offset:448
	global_load_dwordx4 v[94:97], v[136:137], off offset:704
	global_load_dwordx4 v[100:103], v[136:137], off offset:960
	s_waitcnt lgkmcnt(0)
	s_waitcnt vmcnt(5)
	v_mfma_f32_16x16x32_bf16 v[70:73], v[34:37], v[50:53], 0
	s_waitcnt vmcnt(4)
	v_mfma_f32_16x16x32_bf16 v[34:37], v[34:37], v[54:57], 0
	v_mfma_f32_16x16x32_bf16 v[78:81], v[38:41], v[50:53], 0
	s_waitcnt vmcnt(3) lgkmcnt(1)
	v_mfma_f32_16x16x32_bf16 v[62:65], v[46:49], v[86:89], v[58:61]
	s_waitcnt vmcnt(2)
	v_mfma_f32_16x16x32_bf16 v[50:53], v[46:49], v[90:93], v[66:69]
	v_mfma_f32_16x16x32_bf16 v[42:45], v[38:41], v[42:45], 0
	s_nop 1
	v_mov_b32_e32 v66, v30
	v_mov_b32_e32 v67, v18
	s_nop 0
	v_mov_b32_e32 v68, v62
	v_mfma_f32_16x16x32_bf16 v[38:41], v[38:41], v[54:57], 0
	v_mov_b32_e32 v69, v50
	s_waitcnt vmcnt(1)
	v_mfma_f32_16x16x32_bf16 v[58:61], v[46:49], v[94:97], v[70:73]
	s_waitcnt vmcnt(0)
	v_mfma_f32_16x16x32_bf16 v[54:57], v[46:49], v[100:103], v[34:37]
	s_nop 0
	v_add_f32_e64 v70, v66, v68
	v_add_f32_e64 v71, v67, v69
	s_nop 2
	v_mov_b32_e32 v72, v58
	s_waitcnt lgkmcnt(0)
	v_mfma_f32_16x16x32_bf16 v[34:37], v[82:85], v[90:93], v[74:77]
	s_nop 2
	v_cvt_pk_bf16_f32 v74, v70, v71
	v_mov_b32_e32 v70, v26
	v_mov_b32_e32 v71, v22
	v_mov_b32_e32 v73, v54
	v_pk_add_f32 v[76:77], v[70:71], v[72:73]
	v_mfma_f32_16x16x32_bf16 v[46:49], v[82:85], v[86:89], v[42:45]
	v_cvt_pk_bf16_f32 v75, v76, v77
	v_add_u32_e32 v76, 0x800, v134
	v_ashrrev_i32_e32 v77, 31, v76
	v_mfma_f32_16x16x32_bf16 v[42:45], v[82:85], v[94:97], v[78:81]
	v_lshlrev_b64 v[76:77], 11, v[76:77]
	v_lshl_add_u64 v[76:77], v[132:133], 0, v[76:77]
	global_store_dwordx2 v[76:77], v[74:75], off sc1
	v_mfma_f32_16x16x32_bf16 v[38:41], v[82:85], v[100:103], v[38:41]
	s_cbranch_vccnz .LBB0_694
	v_pk_add_f32 v[66:67], v[66:67], v[68:69] neg_lo:[0,1] neg_hi:[0,1]
	v_pk_add_f32 v[68:69], v[70:71], v[72:73] neg_lo:[0,1] neg_hi:[0,1]
	v_cvt_pk_bf16_f32 v66, v66, v67
	v_cvt_pk_bf16_f32 v67, v68, v69
	v_sub_u32_e32 v68, 31, v98
	v_ashrrev_i32_e32 v69, 31, v68
	v_lshlrev_b64 v[68:69], 17, v[68:69]
	v_subrev_co_u32_e32 v68, vcc, s10, v68
	s_nop 1
	v_subbrev_co_u32_e32 v69, vcc, 0, v69, vcc
	v_lshl_add_u64 v[68:69], v[132:133], 0, v[68:69]
	v_add_co_u32_e32 v68, vcc, 0x20000, v68
	s_nop 1
	v_addc_co_u32_e32 v69, vcc, 0, v69, vcc
	global_store_dwordx2 v[68:69], v[66:67], off sc1
.LBB0_694:
	v_mov_b32_e32 v18, v31
	v_mov_b32_e32 v50, v63
	v_pk_add_f32 v[30:31], v[18:19], v[50:51]
	v_mov_b32_e32 v22, v27
	v_mov_b32_e32 v54, v59
	v_cvt_pk_bf16_f32 v26, v30, v31
	v_pk_add_f32 v[30:31], v[22:23], v[54:55]
	s_and_b64 vcc, exec, s[36:37]
	v_cvt_pk_bf16_f32 v27, v30, v31
	v_add_u32_e32 v30, 0x840, v134
	v_ashrrev_i32_e32 v31, 31, v30
	v_lshlrev_b64 v[30:31], 11, v[30:31]
	v_lshl_add_u64 v[30:31], v[132:133], 0, v[30:31]
	global_store_dwordx2 v[30:31], v[26:27], off sc1
	s_cbranch_vccnz .LBB0_696
	v_pk_add_f32 v[18:19], v[18:19], v[50:51] neg_lo:[0,1] neg_hi:[0,1]
	v_pk_add_f32 v[22:23], v[22:23], v[54:55] neg_lo:[0,1] neg_hi:[0,1]
	v_cvt_pk_bf16_f32 v18, v18, v19
	v_cvt_pk_bf16_f32 v19, v22, v23
	v_sub_u32_e32 v22, 30, v98
	v_ashrrev_i32_e32 v23, 31, v22
	v_lshlrev_b64 v[22:23], 17, v[22:23]
	v_subrev_co_u32_e32 v22, vcc, s10, v22
	s_nop 1
	v_subbrev_co_u32_e32 v23, vcc, 0, v23, vcc
	v_lshl_add_u64 v[22:23], v[132:133], 0, v[22:23]
	v_add_co_u32_e32 v22, vcc, 0x20000, v22
	s_nop 1
	v_addc_co_u32_e32 v23, vcc, 0, v23, vcc
	global_store_dwordx2 v[22:23], v[18:19], off sc1
.LBB0_696:
	v_mov_b32_e32 v18, v32
	v_mov_b32_e32 v19, v20
	v_mov_b32_e32 v22, v64
	v_mov_b32_e32 v23, v52
	v_pk_add_f32 v[26:27], v[18:19], v[22:23]
	v_mov_b32_e32 v30, v60
	v_cvt_pk_bf16_f32 v50, v26, v27
	v_mov_b32_e32 v26, v28
	v_mov_b32_e32 v27, v24
	v_mov_b32_e32 v31, v56
	v_pk_add_f32 v[54:55], v[26:27], v[30:31]
	s_and_b64 vcc, exec, s[36:37]
	v_cvt_pk_bf16_f32 v51, v54, v55
	v_add_u32_e32 v54, 0x880, v134
	v_ashrrev_i32_e32 v55, 31, v54
	v_lshlrev_b64 v[54:55], 11, v[54:55]
	v_lshl_add_u64 v[54:55], v[132:133], 0, v[54:55]
	global_store_dwordx2 v[54:55], v[50:51], off sc1
	s_cbranch_vccnz .LBB0_698
	v_pk_add_f32 v[18:19], v[18:19], v[22:23] neg_lo:[0,1] neg_hi:[0,1]
	v_pk_add_f32 v[22:23], v[26:27], v[30:31] neg_lo:[0,1] neg_hi:[0,1]
	v_cvt_pk_bf16_f32 v18, v18, v19
	v_cvt_pk_bf16_f32 v19, v22, v23
	v_sub_u32_e32 v22, 29, v98
	v_ashrrev_i32_e32 v23, 31, v22
	v_lshlrev_b64 v[22:23], 17, v[22:23]
	v_subrev_co_u32_e32 v22, vcc, s10, v22
	s_nop 1
	v_subbrev_co_u32_e32 v23, vcc, 0, v23, vcc
	v_lshl_add_u64 v[22:23], v[132:133], 0, v[22:23]
	v_add_co_u32_e32 v22, vcc, 0x20000, v22
	s_nop 1
	v_addc_co_u32_e32 v23, vcc, 0, v23, vcc
	global_store_dwordx2 v[22:23], v[18:19], off sc1
.LBB0_698:
	v_mov_b32_e32 v20, v33
	v_mov_b32_e32 v52, v65
	v_mov_b32_e32 v24, v29
	v_mov_b32_e32 v56, v61
	v_pk_add_f32 v[18:19], v[20:21], v[52:53]
	v_pk_add_f32 v[22:23], v[24:25], v[56:57]
	v_cvt_pk_bf16_f32 v18, v18, v19
	v_cvt_pk_bf16_f32 v19, v22, v23
	v_add_u32_e32 v22, 0x8c0, v134
	v_ashrrev_i32_e32 v23, 31, v22
	v_lshlrev_b64 v[22:23], 11, v[22:23]
	v_lshl_add_u64 v[22:23], v[132:133], 0, v[22:23]
	s_and_b64 vcc, exec, s[36:37]
	global_store_dwordx2 v[22:23], v[18:19], off sc1
	s_cbranch_vccnz .LBB0_700
	v_pk_add_f32 v[18:19], v[20:21], v[52:53] neg_lo:[0,1] neg_hi:[0,1]
	v_pk_add_f32 v[20:21], v[24:25], v[56:57] neg_lo:[0,1] neg_hi:[0,1]
	v_cvt_pk_bf16_f32 v18, v18, v19
	v_cvt_pk_bf16_f32 v19, v20, v21
	v_sub_u32_e32 v20, 28, v98
	v_ashrrev_i32_e32 v21, 31, v20
	v_lshlrev_b64 v[20:21], 17, v[20:21]
	v_subrev_co_u32_e32 v20, vcc, s10, v20
	s_nop 1
	v_subbrev_co_u32_e32 v21, vcc, 0, v21, vcc
	v_lshl_add_u64 v[20:21], v[132:133], 0, v[20:21]
	v_add_co_u32_e32 v20, vcc, 0x20000, v20
	s_nop 1
	v_addc_co_u32_e32 v21, vcc, 0, v21, vcc
	global_store_dwordx2 v[20:21], v[18:19], off sc1
.LBB0_700:
	v_mov_b32_e32 v18, v14
	v_mov_b32_e32 v19, v2
	v_mov_b32_e32 v20, v46
	v_mov_b32_e32 v21, v34
	v_pk_add_f32 v[22:23], v[18:19], v[20:21]
	v_mov_b32_e32 v24, v42
	v_cvt_pk_bf16_f32 v26, v22, v23
	v_mov_b32_e32 v22, v10
	v_mov_b32_e32 v23, v6
	v_mov_b32_e32 v25, v38
	v_pk_add_f32 v[28:29], v[22:23], v[24:25]
	s_and_b64 vcc, exec, s[36:37]
	v_cvt_pk_bf16_f32 v27, v28, v29
	v_add_u32_e32 v28, 0xc00, v134
	v_ashrrev_i32_e32 v29, 31, v28
	v_lshlrev_b64 v[28:29], 11, v[28:29]
	v_lshl_add_u64 v[28:29], v[132:133], 0, v[28:29]
	global_store_dwordx2 v[28:29], v[26:27], off sc1
	s_cbranch_vccnz .LBB0_702
	v_pk_add_f32 v[18:19], v[18:19], v[20:21] neg_lo:[0,1] neg_hi:[0,1]
	v_pk_add_f32 v[20:21], v[22:23], v[24:25] neg_lo:[0,1] neg_hi:[0,1]
	v_cvt_pk_bf16_f32 v18, v18, v19
	v_cvt_pk_bf16_f32 v19, v20, v21
	v_sub_u32_e32 v20, 15, v98
	v_ashrrev_i32_e32 v21, 31, v20
	v_lshlrev_b64 v[20:21], 17, v[20:21]
	v_subrev_co_u32_e32 v20, vcc, s10, v20
	s_nop 1
	v_subbrev_co_u32_e32 v21, vcc, 0, v21, vcc
	v_lshl_add_u64 v[20:21], v[132:133], 0, v[20:21]
	v_add_co_u32_e32 v20, vcc, 0x20000, v20
	s_nop 1
	v_addc_co_u32_e32 v21, vcc, 0, v21, vcc
	global_store_dwordx2 v[20:21], v[18:19], off sc1
.LBB0_702:
	v_mov_b32_e32 v2, v15
	v_mov_b32_e32 v34, v47
	v_pk_add_f32 v[14:15], v[2:3], v[34:35]
	v_mov_b32_e32 v6, v11
	v_mov_b32_e32 v38, v43
	v_cvt_pk_bf16_f32 v10, v14, v15
	v_pk_add_f32 v[14:15], v[6:7], v[38:39]
	s_and_b64 vcc, exec, s[36:37]
	v_cvt_pk_bf16_f32 v11, v14, v15
	v_add_u32_e32 v14, 0xc40, v134
	v_ashrrev_i32_e32 v15, 31, v14
	v_lshlrev_b64 v[14:15], 11, v[14:15]
	v_lshl_add_u64 v[14:15], v[132:133], 0, v[14:15]
	global_store_dwordx2 v[14:15], v[10:11], off sc1
	s_cbranch_vccnz .LBB0_704
	v_pk_add_f32 v[2:3], v[2:3], v[34:35] neg_lo:[0,1] neg_hi:[0,1]
	v_pk_add_f32 v[6:7], v[6:7], v[38:39] neg_lo:[0,1] neg_hi:[0,1]
	v_cvt_pk_bf16_f32 v2, v2, v3
	v_cvt_pk_bf16_f32 v3, v6, v7
	v_sub_u32_e32 v6, 14, v98
	v_ashrrev_i32_e32 v7, 31, v6
	v_lshlrev_b64 v[6:7], 17, v[6:7]
	v_subrev_co_u32_e32 v6, vcc, s10, v6
	s_nop 1
	v_subbrev_co_u32_e32 v7, vcc, 0, v7, vcc
	v_lshl_add_u64 v[6:7], v[132:133], 0, v[6:7]
	v_add_co_u32_e32 v6, vcc, 0x20000, v6
	s_nop 1
	v_addc_co_u32_e32 v7, vcc, 0, v7, vcc
	global_store_dwordx2 v[6:7], v[2:3], off sc1
.LBB0_704:
	v_mov_b32_e32 v2, v16
	v_mov_b32_e32 v3, v4
	v_mov_b32_e32 v6, v48
	v_mov_b32_e32 v7, v36
	v_pk_add_f32 v[10:11], v[2:3], v[6:7]
	v_mov_b32_e32 v14, v44
	v_cvt_pk_bf16_f32 v18, v10, v11
	v_mov_b32_e32 v10, v12
	v_mov_b32_e32 v11, v8
	v_mov_b32_e32 v15, v40
	v_pk_add_f32 v[20:21], v[10:11], v[14:15]
	s_and_b64 vcc, exec, s[36:37]
	v_cvt_pk_bf16_f32 v19, v20, v21
	v_add_u32_e32 v20, 0xc80, v134
	v_ashrrev_i32_e32 v21, 31, v20
	v_lshlrev_b64 v[20:21], 11, v[20:21]
	v_lshl_add_u64 v[20:21], v[132:133], 0, v[20:21]
	global_store_dwordx2 v[20:21], v[18:19], off sc1
	s_cbranch_vccnz .LBB0_706
	v_pk_add_f32 v[2:3], v[2:3], v[6:7] neg_lo:[0,1] neg_hi:[0,1]
	v_pk_add_f32 v[6:7], v[10:11], v[14:15] neg_lo:[0,1] neg_hi:[0,1]
	v_cvt_pk_bf16_f32 v2, v2, v3
	v_cvt_pk_bf16_f32 v3, v6, v7
	v_sub_u32_e32 v6, 13, v98
	v_ashrrev_i32_e32 v7, 31, v6
	v_lshlrev_b64 v[6:7], 17, v[6:7]
	v_subrev_co_u32_e32 v6, vcc, s10, v6
	s_nop 1
	v_subbrev_co_u32_e32 v7, vcc, 0, v7, vcc
	v_lshl_add_u64 v[6:7], v[132:133], 0, v[6:7]
	v_add_co_u32_e32 v6, vcc, 0x20000, v6
	s_nop 1
	v_addc_co_u32_e32 v7, vcc, 0, v7, vcc
	global_store_dwordx2 v[6:7], v[2:3], off sc1
.LBB0_706:
	v_mov_b32_e32 v4, v17
	v_mov_b32_e32 v36, v49
	v_mov_b32_e32 v8, v13
	v_mov_b32_e32 v40, v45
	v_pk_add_f32 v[2:3], v[4:5], v[36:37]
	v_pk_add_f32 v[6:7], v[8:9], v[40:41]
	v_cvt_pk_bf16_f32 v2, v2, v3
	v_cvt_pk_bf16_f32 v3, v6, v7
	v_add_u32_e32 v6, 0xcc0, v134
	v_ashrrev_i32_e32 v7, 31, v6
	v_lshlrev_b64 v[6:7], 11, v[6:7]
	v_lshl_add_u64 v[6:7], v[132:133], 0, v[6:7]
	s_and_b64 vcc, exec, s[36:37]
	global_store_dwordx2 v[6:7], v[2:3], off sc1
	s_cbranch_vccnz .LBB0_708
	v_pk_add_f32 v[2:3], v[4:5], v[36:37] neg_lo:[0,1] neg_hi:[0,1]
	v_pk_add_f32 v[4:5], v[8:9], v[40:41] neg_lo:[0,1] neg_hi:[0,1]
	v_cvt_pk_bf16_f32 v2, v2, v3
	v_cvt_pk_bf16_f32 v3, v4, v5
	v_sub_u32_e32 v4, 12, v98
	v_ashrrev_i32_e32 v5, 31, v4
	v_lshlrev_b64 v[4:5], 17, v[4:5]
	v_subrev_co_u32_e32 v4, vcc, s10, v4
	s_nop 1
	v_subbrev_co_u32_e32 v5, vcc, 0, v5, vcc
	v_lshl_add_u64 v[4:5], v[132:133], 0, v[4:5]
	v_add_co_u32_e32 v4, vcc, 0x20000, v4
	s_nop 1
	v_addc_co_u32_e32 v5, vcc, 0, v5, vcc
	global_store_dwordx2 v[4:5], v[2:3], off sc1

.LBB0_713:
	s_lshl_b32 s0, s30, 11
	s_add_u32 s0, s46, s0
	s_addc_u32 s1, s47, 0
	s_add_u32 s0, s0, s21
	s_addc_u32 s1, s1, 0
	v_lshlrev_b32_e32 v98, 1, v148
	v_lshl_add_u64 v[132:133], s[0:1], 0, v[98:99]
	s_movk_i32 s0, 0x440
	v_lshl_add_u32 v98, v149, 3, s20
	v_cvt_pk_bf16_f32 v137, v120, v116
	v_mul_lo_u32 v116, v211, s0
	v_add_u32_e32 v146, v98, v116
	v_cvt_pk_bf16_f32 v116, v129, v125
	v_cvt_pk_bf16_f32 v117, v121, v117
	v_cvt_pk_bf16_f32 v121, v122, v118
	v_cvt_pk_bf16_f32 v122, v82, v86
	v_cvt_pk_bf16_f32 v82, v83, v87
	v_cvt_pk_bf16_f32 v83, v91, v95
	v_cvt_pk_bf16_f32 v120, v130, v126
	ds_write2_b64 v146, v[116:117], v[82:83] offset0:34 offset1:50
	v_cvt_pk_bf16_f32 v82, v84, v88
	v_cvt_pk_bf16_f32 v83, v92, v96
	v_cvt_pk_bf16_f32 v119, v123, v119
	v_cvt_pk_bf16_f32 v123, v90, v94
	ds_write2_b64 v146, v[120:121], v[82:83] offset0:68 offset1:84
	v_cvt_pk_bf16_f32 v82, v85, v89
	v_cvt_pk_bf16_f32 v84, v113, v109
	v_cvt_pk_bf16_f32 v85, v105, v101
	v_cvt_pk_bf16_f32 v90, v66, v70
	v_add_u32_e32 v147, 0x1000, v146
	v_cvt_pk_bf16_f32 v66, v67, v71
	v_cvt_pk_bf16_f32 v67, v75, v79
	v_cvt_pk_bf16_f32 v118, v131, v127
	v_cvt_pk_bf16_f32 v83, v93, v97
	v_cvt_pk_bf16_f32 v86, v114, v110
	v_cvt_pk_bf16_f32 v87, v106, v102
	ds_write2_b64 v147, v[84:85], v[66:67] offset0:66 offset1:82
	v_cvt_pk_bf16_f32 v66, v68, v72
	v_cvt_pk_bf16_f32 v67, v76, v80
	v_cvt_pk_bf16_f32 v136, v128, v124
	ds_write2_b64 v146, v[118:119], v[82:83] offset0:102 offset1:118
	v_cvt_pk_bf16_f32 v82, v112, v108
	v_cvt_pk_bf16_f32 v83, v104, v100
	v_cvt_pk_bf16_f32 v88, v115, v111
	v_cvt_pk_bf16_f32 v89, v107, v103
	v_cvt_pk_bf16_f32 v91, v74, v78
	ds_write2_b64 v147, v[86:87], v[66:67] offset0:100 offset1:116
	v_cvt_pk_bf16_f32 v66, v69, v73
	v_cvt_pk_bf16_f32 v67, v77, v81
	ds_write2_b64 v146, v[136:137], v[122:123] offset1:16
	ds_write2_b64 v147, v[82:83], v[90:91] offset0:32 offset1:48
	ds_write2_b64 v147, v[88:89], v[66:67] offset0:134 offset1:150
	v_lshl_add_u64 v[134:135], v[150:151], 1, s[12:13]
	s_waitcnt lgkmcnt(0)
	v_lshlrev_b32_e32 v98, 10, v149
	v_lshl_add_u64 v[136:137], v[134:135], 0, v[98:99]
	global_load_dwordx4 v[78:81], v[136:137], off offset:256
	global_load_dwordx4 v[138:141], v[136:137], off offset:384
	v_and_b32_e32 v70, -16, v212
	v_add_u32_e32 v148, s20, v70
	s_movk_i32 s0, 0x110
	v_mad_u32_u24 v98, v149, s0, v148
	ds_read_b128 v[70:73], v98
	ds_read_b128 v[104:107], v98 offset:64
	ds_read_b128 v[100:103], v98 offset:4352
	ds_read_b128 v[128:131], v98 offset:128
	global_load_dwordx4 v[66:69], v[136:137], off
	global_load_dwordx4 v[82:85], v[136:137], off offset:512
	global_load_dwordx4 v[94:97], v[136:137], off offset:768
	global_load_dwordx4 v[124:127], v[136:137], off offset:128
	global_load_dwordx4 v[154:157], v[136:137], off offset:192
	s_mov_b64 s[0:1], 0x11800000
	v_lshl_add_u64 v[132:133], v[132:133], 0, s[0:1]
	s_add_i32 s0, s30, -1
	s_cmp_lt_u32 s0, 31
	s_cselect_b64 s[0:1], -1, 0
	s_lshl_b32 s30, s30, 12
	s_and_b64 vcc, exec, s[0:1]
	s_waitcnt vmcnt(6) lgkmcnt(3)
	v_mfma_f32_16x16x32_bf16 v[86:89], v[70:73], v[78:81], 0
	global_load_dwordx4 v[158:161], v[136:137], off offset:448
	global_load_dwordx4 v[166:169], v[136:137], off offset:960
	ds_read_b128 v[170:173], v98 offset:4544
	s_waitcnt lgkmcnt(2)
	v_mfma_f32_16x16x32_bf16 v[116:119], v[100:103], v[78:81], 0
	global_load_dwordx4 v[78:81], v[136:137], off offset:64
	s_waitcnt vmcnt(7)
	v_mfma_f32_16x16x32_bf16 v[74:77], v[70:73], v[66:69], 0
	s_waitcnt vmcnt(0)
	v_mfma_f32_16x16x32_bf16 v[108:111], v[104:107], v[78:81], v[74:77]
	s_nop 5
	global_load_dwordx4 v[74:77], v[136:137], off offset:320
	v_mfma_f32_16x16x32_bf16 v[90:93], v[70:73], v[82:85], 0
	v_mfma_f32_16x16x32_bf16 v[70:73], v[70:73], v[94:97], 0
	v_mfma_f32_16x16x32_bf16 v[66:69], v[100:103], v[66:69], 0
	v_mfma_f32_16x16x32_bf16 v[120:123], v[100:103], v[82:85], 0
	v_mfma_f32_16x16x32_bf16 v[100:103], v[100:103], v[94:97], 0
	s_waitcnt vmcnt(0)
	v_mfma_f32_16x16x32_bf16 v[94:97], v[104:107], v[74:77], v[86:89]
	s_nop 2
	global_load_dwordx4 v[86:89], v[136:137], off offset:576
	s_waitcnt vmcnt(0)
	v_mfma_f32_16x16x32_bf16 v[112:115], v[104:107], v[86:89], v[90:93]
	s_nop 2
	global_load_dwordx4 v[90:93], v[136:137], off offset:832
	s_waitcnt vmcnt(0)
	v_mfma_f32_16x16x32_bf16 v[104:107], v[104:107], v[90:93], v[70:73]
	s_nop 2
	ds_read_b128 v[70:73], v98 offset:4416
	s_waitcnt lgkmcnt(0)
	v_mfma_f32_16x16x32_bf16 v[78:81], v[70:73], v[78:81], v[66:69]
	v_mfma_f32_16x16x32_bf16 v[66:69], v[70:73], v[74:77], v[116:119]
	v_mfma_f32_16x16x32_bf16 v[74:77], v[70:73], v[86:89], v[120:123]
	global_load_dwordx4 v[86:89], v[136:137], off offset:640
	s_nop 0
	ds_read_b128 v[116:119], v98 offset:4480
	v_mfma_f32_16x16x32_bf16 v[70:73], v[70:73], v[90:93], v[100:103]
	s_nop 2
	global_load_dwordx4 v[100:103], v[136:137], off offset:896
	v_mfma_f32_16x16x32_bf16 v[142:145], v[128:131], v[124:127], 0
	v_mfma_f32_16x16x32_bf16 v[82:85], v[128:131], v[138:141], 0
	s_waitcnt vmcnt(1)
	v_mfma_f32_16x16x32_bf16 v[90:93], v[128:131], v[86:89], 0
	s_waitcnt vmcnt(0)
	v_mfma_f32_16x16x32_bf16 v[128:131], v[128:131], v[100:103], 0
	s_waitcnt lgkmcnt(0)
	v_mfma_f32_16x16x32_bf16 v[162:165], v[116:119], v[100:103], 0
	ds_read_b128 v[100:103], v98 offset:192
	v_lshlrev_b32_e32 v98, 2, v211
	v_mfma_f32_16x16x32_bf16 v[150:153], v[116:119], v[124:127], 0
	v_mfma_f32_16x16x32_bf16 v[138:141], v[116:119], v[138:141], 0
	v_mfma_f32_16x16x32_bf16 v[86:89], v[116:119], v[86:89], 0
	s_waitcnt lgkmcnt(0)
	v_mfma_f32_16x16x32_bf16 v[116:119], v[100:103], v[154:157], v[142:145]
	s_nop 2
	global_load_dwordx4 v[142:145], v[136:137], off offset:704
	v_mfma_f32_16x16x32_bf16 v[120:123], v[100:103], v[158:161], v[82:85]
	s_waitcnt lgkmcnt(0)
	s_waitcnt vmcnt(0)
	v_mfma_f32_16x16x32_bf16 v[124:127], v[100:103], v[142:145], v[90:93]
	v_mfma_f32_16x16x32_bf16 v[128:131], v[100:103], v[166:169], v[128:131]
	v_mfma_f32_16x16x32_bf16 v[82:85], v[170:173], v[158:161], v[138:141]
	s_nop 2
	v_mov_b32_e32 v138, v108
	v_mov_b32_e32 v139, v94
	v_mov_b32_e32 v140, v116
	v_mov_b32_e32 v141, v120
	v_mfma_f32_16x16x32_bf16 v[100:103], v[170:173], v[142:145], v[86:89]
	v_add_f32_e64 v134, v138, v140
	v_add_f32_e64 v135, v139, v141
	v_mov_b32_e32 v142, v112
	v_mov_b32_e32 v143, v104
	v_mov_b32_e32 v144, v124
	v_mov_b32_e32 v145, v128
	v_mfma_f32_16x16x32_bf16 v[90:93], v[170:173], v[154:157], v[150:153]
	s_nop 2
	v_cvt_pk_bf16_f32 v150, v134, v135
	v_pk_add_f32 v[134:135], v[142:143], v[144:145]
	v_mfma_f32_16x16x32_bf16 v[86:89], v[170:173], v[166:169], v[162:165]
	v_cvt_pk_bf16_f32 v151, v134, v135
	v_lshlrev_b32_e32 v134, 8, v211
	v_ashrrev_i32_e32 v135, 31, v134
	v_lshlrev_b64 v[152:153], 11, v[134:135]
	v_lshl_add_u64 v[152:153], v[132:133], 0, v[152:153]
	global_store_dwordx2 v[152:153], v[150:151], off sc1
	s_cbranch_vccz .LBB0_715
	v_pk_add_f32 v[138:139], v[138:139], v[140:141] neg_lo:[0,1] neg_hi:[0,1]
	v_pk_add_f32 v[140:141], v[142:143], v[144:145] neg_lo:[0,1] neg_hi:[0,1]
	v_cvt_pk_bf16_f32 v138, v138, v139
	v_cvt_pk_bf16_f32 v139, v140, v141
	v_sub_u32_e32 v140, 63, v98
	v_ashrrev_i32_e32 v141, 31, v140
	v_lshlrev_b64 v[140:141], 17, v[140:141]
	v_subrev_co_u32_e32 v140, vcc, s30, v140
	s_nop 1
	v_subbrev_co_u32_e32 v141, vcc, 0, v141, vcc
	v_lshl_add_u64 v[140:141], v[132:133], 0, v[140:141]
	v_add_co_u32_e32 v140, vcc, 0x20000, v140
	s_nop 1
	v_addc_co_u32_e32 v141, vcc, 0, v141, vcc
	global_store_dwordx2 v[140:141], v[138:139], off sc1
.LBB0_715:
	v_mov_b32_e32 v94, v109
	v_mov_b32_e32 v120, v117
	v_mov_b32_e32 v104, v113
	v_mov_b32_e32 v128, v125
	v_pk_add_f32 v[108:109], v[94:95], v[120:121]
	v_pk_add_f32 v[112:113], v[104:105], v[128:129]
	v_cvt_pk_bf16_f32 v108, v108, v109
	v_cvt_pk_bf16_f32 v109, v112, v113
	v_or_b32_e32 v112, 64, v134
	v_ashrrev_i32_e32 v113, 31, v112
	v_lshlrev_b64 v[112:113], 11, v[112:113]
	v_cndmask_b32_e64 v116, 0, 1, s[0:1]
	v_lshl_add_u64 v[112:113], v[132:133], 0, v[112:113]
	v_cmp_ne_u32_e64 s[36:37], 1, v116
	s_andn2_b64 vcc, exec, s[0:1]
	global_store_dwordx2 v[112:113], v[108:109], off sc1
	s_cbranch_vccnz .LBB0_717
	v_pk_add_f32 v[94:95], v[94:95], v[120:121] neg_lo:[0,1] neg_hi:[0,1]
	v_pk_add_f32 v[104:105], v[104:105], v[128:129] neg_lo:[0,1] neg_hi:[0,1]
	v_cvt_pk_bf16_f32 v94, v94, v95
	v_cvt_pk_bf16_f32 v95, v104, v105
	v_xor_b32_e32 v104, -2, v98
	v_ashrrev_i32_e32 v105, 31, v104
	v_lshlrev_b64 v[104:105], 17, v[104:105]
	v_subrev_co_u32_e32 v104, vcc, s30, v104
	s_nop 1
	v_subbrev_co_u32_e32 v105, vcc, 0, v105, vcc
	v_lshl_add_u64 v[104:105], v[132:133], 0, v[104:105]
	v_add_co_u32_e32 v104, vcc, 0x820000, v104
	s_nop 1
	v_addc_co_u32_e32 v105, vcc, 0, v105, vcc
	global_store_dwordx2 v[104:105], v[94:95], off sc1
.LBB0_717:
	v_mov_b32_e32 v94, v110
	v_mov_b32_e32 v95, v96
	v_mov_b32_e32 v104, v118
	v_mov_b32_e32 v105, v122
	v_pk_add_f32 v[108:109], v[94:95], v[104:105]
	v_mov_b32_e32 v112, v126
	v_cvt_pk_bf16_f32 v116, v108, v109
	v_mov_b32_e32 v108, v114
	v_mov_b32_e32 v109, v106
	v_mov_b32_e32 v113, v130
	v_pk_add_f32 v[120:121], v[108:109], v[112:113]
	s_and_b64 vcc, exec, s[36:37]
	v_cvt_pk_bf16_f32 v117, v120, v121
	v_or_b32_e32 v120, 0x80, v134
	v_ashrrev_i32_e32 v121, 31, v120
	v_lshlrev_b64 v[120:121], 11, v[120:121]
	v_lshl_add_u64 v[120:121], v[132:133], 0, v[120:121]
	global_store_dwordx2 v[120:121], v[116:117], off sc1
	s_cbranch_vccnz .LBB0_719
	v_pk_add_f32 v[94:95], v[94:95], v[104:105] neg_lo:[0,1] neg_hi:[0,1]
	v_pk_add_f32 v[104:105], v[108:109], v[112:113] neg_lo:[0,1] neg_hi:[0,1]
	v_cvt_pk_bf16_f32 v94, v94, v95
	v_cvt_pk_bf16_f32 v95, v104, v105
	v_xor_b32_e32 v104, -3, v98
	v_ashrrev_i32_e32 v105, 31, v104
	v_lshlrev_b64 v[104:105], 17, v[104:105]
	v_subrev_co_u32_e32 v104, vcc, s30, v104
	s_nop 1
	v_subbrev_co_u32_e32 v105, vcc, 0, v105, vcc
	v_lshl_add_u64 v[104:105], v[132:133], 0, v[104:105]
	v_add_co_u32_e32 v104, vcc, 0x820000, v104
	s_nop 1
	v_addc_co_u32_e32 v105, vcc, 0, v105, vcc
	global_store_dwordx2 v[104:105], v[94:95], off sc1
.LBB0_719:
	v_mov_b32_e32 v96, v111
	v_mov_b32_e32 v122, v119
	v_mov_b32_e32 v106, v115
	v_mov_b32_e32 v130, v127
	v_pk_add_f32 v[94:95], v[96:97], v[122:123]
	v_pk_add_f32 v[104:105], v[106:107], v[130:131]
	v_cvt_pk_bf16_f32 v94, v94, v95
	v_cvt_pk_bf16_f32 v95, v104, v105
	v_or_b32_e32 v104, 0xc0, v134
	v_ashrrev_i32_e32 v105, 31, v104
	v_lshlrev_b64 v[104:105], 11, v[104:105]
	v_lshl_add_u64 v[104:105], v[132:133], 0, v[104:105]
	s_and_b64 vcc, exec, s[36:37]
	global_store_dwordx2 v[104:105], v[94:95], off sc1
	s_cbranch_vccnz .LBB0_721
	v_pk_add_f32 v[94:95], v[96:97], v[122:123] neg_lo:[0,1] neg_hi:[0,1]
	v_pk_add_f32 v[96:97], v[106:107], v[130:131] neg_lo:[0,1] neg_hi:[0,1]
	v_cvt_pk_bf16_f32 v94, v94, v95
	v_cvt_pk_bf16_f32 v95, v96, v97
	v_xor_b32_e32 v96, -4, v98
	v_ashrrev_i32_e32 v97, 31, v96
	v_lshlrev_b64 v[96:97], 17, v[96:97]
	v_subrev_co_u32_e32 v96, vcc, s30, v96
	s_nop 1
	v_subbrev_co_u32_e32 v97, vcc, 0, v97, vcc
	v_lshl_add_u64 v[96:97], v[132:133], 0, v[96:97]
	v_add_co_u32_e32 v96, vcc, 0x820000, v96
	s_nop 1
	v_addc_co_u32_e32 v97, vcc, 0, v97, vcc
	global_store_dwordx2 v[96:97], v[94:95], off sc1
.LBB0_721:
	v_mov_b32_e32 v94, v78
	v_mov_b32_e32 v95, v66
	v_mov_b32_e32 v96, v90
	v_mov_b32_e32 v97, v82
	v_pk_add_f32 v[104:105], v[94:95], v[96:97]
	v_mov_b32_e32 v106, v100
	v_cvt_pk_bf16_f32 v108, v104, v105
	v_mov_b32_e32 v104, v74
	v_mov_b32_e32 v105, v70
	v_mov_b32_e32 v107, v86
	v_pk_add_f32 v[110:111], v[104:105], v[106:107]
	s_and_b64 vcc, exec, s[36:37]
	v_cvt_pk_bf16_f32 v109, v110, v111
	v_add_u32_e32 v110, 0x400, v134
	v_ashrrev_i32_e32 v111, 31, v110
	v_lshlrev_b64 v[110:111], 11, v[110:111]
	v_lshl_add_u64 v[110:111], v[132:133], 0, v[110:111]
	global_store_dwordx2 v[110:111], v[108:109], off sc1
	s_cbranch_vccnz .LBB0_723
	v_pk_add_f32 v[94:95], v[94:95], v[96:97] neg_lo:[0,1] neg_hi:[0,1]
	v_pk_add_f32 v[96:97], v[104:105], v[106:107] neg_lo:[0,1] neg_hi:[0,1]
	v_cvt_pk_bf16_f32 v94, v94, v95
	v_cvt_pk_bf16_f32 v95, v96, v97
	v_sub_u32_e32 v96, 47, v98
	v_ashrrev_i32_e32 v97, 31, v96
	v_lshlrev_b64 v[96:97], 17, v[96:97]
	v_subrev_co_u32_e32 v96, vcc, s30, v96
	s_nop 1
	v_subbrev_co_u32_e32 v97, vcc, 0, v97, vcc
	v_lshl_add_u64 v[96:97], v[132:133], 0, v[96:97]
	v_add_co_u32_e32 v96, vcc, 0x20000, v96
	s_nop 1
	v_addc_co_u32_e32 v97, vcc, 0, v97, vcc
	global_store_dwordx2 v[96:97], v[94:95], off sc1
.LBB0_723:
	v_mov_b32_e32 v66, v79
	v_mov_b32_e32 v82, v91
	v_pk_add_f32 v[78:79], v[66:67], v[82:83]
	v_mov_b32_e32 v70, v75
	v_mov_b32_e32 v86, v101
	v_cvt_pk_bf16_f32 v74, v78, v79
	v_pk_add_f32 v[78:79], v[70:71], v[86:87]
	s_and_b64 vcc, exec, s[36:37]
	v_cvt_pk_bf16_f32 v75, v78, v79
	v_add_u32_e32 v78, 0x440, v134
	v_ashrrev_i32_e32 v79, 31, v78
	v_lshlrev_b64 v[78:79], 11, v[78:79]
	v_lshl_add_u64 v[78:79], v[132:133], 0, v[78:79]
	global_store_dwordx2 v[78:79], v[74:75], off sc1
	s_cbranch_vccnz .LBB0_725
	v_pk_add_f32 v[66:67], v[66:67], v[82:83] neg_lo:[0,1] neg_hi:[0,1]
	v_pk_add_f32 v[70:71], v[70:71], v[86:87] neg_lo:[0,1] neg_hi:[0,1]
	v_cvt_pk_bf16_f32 v66, v66, v67
	v_cvt_pk_bf16_f32 v67, v70, v71
	v_sub_u32_e32 v70, 46, v98
	v_ashrrev_i32_e32 v71, 31, v70
	v_lshlrev_b64 v[70:71], 17, v[70:71]
	v_subrev_co_u32_e32 v70, vcc, s30, v70
	s_nop 1
	v_subbrev_co_u32_e32 v71, vcc, 0, v71, vcc
	v_lshl_add_u64 v[70:71], v[132:133], 0, v[70:71]
	v_add_co_u32_e32 v70, vcc, 0x20000, v70
	s_nop 1
	v_addc_co_u32_e32 v71, vcc, 0, v71, vcc
	global_store_dwordx2 v[70:71], v[66:67], off sc1
.LBB0_725:
	v_mov_b32_e32 v66, v80
	v_mov_b32_e32 v67, v68
	v_mov_b32_e32 v70, v92
	v_mov_b32_e32 v71, v84
	v_pk_add_f32 v[74:75], v[66:67], v[70:71]
	v_mov_b32_e32 v78, v102
	v_cvt_pk_bf16_f32 v82, v74, v75
	v_mov_b32_e32 v74, v76
	v_mov_b32_e32 v75, v72
	v_mov_b32_e32 v79, v88
	v_pk_add_f32 v[86:87], v[74:75], v[78:79]
	s_and_b64 vcc, exec, s[36:37]
	v_cvt_pk_bf16_f32 v83, v86, v87
	v_add_u32_e32 v86, 0x480, v134
	v_ashrrev_i32_e32 v87, 31, v86
	v_lshlrev_b64 v[86:87], 11, v[86:87]
	v_lshl_add_u64 v[86:87], v[132:133], 0, v[86:87]
	global_store_dwordx2 v[86:87], v[82:83], off sc1
	s_cbranch_vccnz .LBB0_727
	v_pk_add_f32 v[66:67], v[66:67], v[70:71] neg_lo:[0,1] neg_hi:[0,1]
	v_pk_add_f32 v[70:71], v[74:75], v[78:79] neg_lo:[0,1] neg_hi:[0,1]
	v_cvt_pk_bf16_f32 v66, v66, v67
	v_cvt_pk_bf16_f32 v67, v70, v71
	v_sub_u32_e32 v70, 45, v98
	v_ashrrev_i32_e32 v71, 31, v70
	v_lshlrev_b64 v[70:71], 17, v[70:71]
	v_subrev_co_u32_e32 v70, vcc, s30, v70
	s_nop 1
	v_subbrev_co_u32_e32 v71, vcc, 0, v71, vcc
	v_lshl_add_u64 v[70:71], v[132:133], 0, v[70:71]
	v_add_co_u32_e32 v70, vcc, 0x20000, v70
	s_nop 1
	v_addc_co_u32_e32 v71, vcc, 0, v71, vcc
	global_store_dwordx2 v[70:71], v[66:67], off sc1
.LBB0_727:
	v_mov_b32_e32 v68, v81
	v_mov_b32_e32 v84, v93
	v_mov_b32_e32 v72, v77
	v_mov_b32_e32 v88, v103
	v_pk_add_f32 v[66:67], v[68:69], v[84:85]
	v_pk_add_f32 v[70:71], v[72:73], v[88:89]
	v_cvt_pk_bf16_f32 v66, v66, v67
	v_cvt_pk_bf16_f32 v67, v70, v71
	v_add_u32_e32 v70, 0x4c0, v134
	v_ashrrev_i32_e32 v71, 31, v70
	v_lshlrev_b64 v[70:71], 11, v[70:71]
	v_lshl_add_u64 v[70:71], v[132:133], 0, v[70:71]
	s_and_b64 vcc, exec, s[36:37]
	global_store_dwordx2 v[70:71], v[66:67], off sc1
	s_cbranch_vccnz .LBB0_729
	v_pk_add_f32 v[66:67], v[68:69], v[84:85] neg_lo:[0,1] neg_hi:[0,1]
	v_pk_add_f32 v[68:69], v[72:73], v[88:89] neg_lo:[0,1] neg_hi:[0,1]
	v_cvt_pk_bf16_f32 v66, v66, v67
	v_cvt_pk_bf16_f32 v67, v68, v69
	v_sub_u32_e32 v68, 44, v98
	v_ashrrev_i32_e32 v69, 31, v68
	v_lshlrev_b64 v[68:69], 17, v[68:69]
	v_subrev_co_u32_e32 v68, vcc, s30, v68
	s_nop 1
	v_subbrev_co_u32_e32 v69, vcc, 0, v69, vcc
	v_lshl_add_u64 v[68:69], v[132:133], 0, v[68:69]
	v_add_co_u32_e32 v68, vcc, 0x20000, v68
	s_nop 1
	v_addc_co_u32_e32 v69, vcc, 0, v69, vcc
	global_store_dwordx2 v[68:69], v[66:67], off sc1
.LBB0_729:
	v_cvt_pk_bf16_f32 v66, v46, v54
	v_cvt_pk_bf16_f32 v46, v47, v55
	v_cvt_pk_bf16_f32 v47, v59, v63
	v_cvt_pk_bf16_f32 v54, v48, v56
	v_cvt_pk_bf16_f32 v56, v18, v22
	v_cvt_pk_bf16_f32 v18, v19, v23
	v_cvt_pk_bf16_f32 v19, v27, v31
	v_cvt_pk_bf16_f32 v55, v60, v64
	ds_write2_b64 v146, v[46:47], v[18:19] offset0:34 offset1:50
	v_cvt_pk_bf16_f32 v18, v20, v24
	v_cvt_pk_bf16_f32 v19, v28, v32
	ds_write2_b64 v146, v[54:55], v[18:19] offset0:68 offset1:84
	v_cvt_pk_bf16_f32 v18, v21, v25
	v_cvt_pk_bf16_f32 v20, v35, v39
	v_cvt_pk_bf16_f32 v21, v43, v51
	v_cvt_pk_bf16_f32 v27, v6, v2
	v_cvt_pk_bf16_f32 v2, v15, v11
	v_cvt_pk_bf16_f32 v3, v7, v3
	v_cvt_pk_bf16_f32 v48, v49, v57
	v_cvt_pk_bf16_f32 v49, v61, v65
	v_cvt_pk_bf16_f32 v19, v29, v33
	v_cvt_pk_bf16_f32 v22, v36, v40
	v_cvt_pk_bf16_f32 v23, v44, v52
	ds_write2_b64 v147, v[20:21], v[2:3] offset0:66 offset1:82
	v_cvt_pk_bf16_f32 v2, v16, v12
	v_cvt_pk_bf16_f32 v3, v8, v4
	v_cvt_pk_bf16_f32 v67, v58, v62
	v_cvt_pk_bf16_f32 v57, v26, v30
	ds_write2_b64 v146, v[48:49], v[18:19] offset0:102 offset1:118
	v_cvt_pk_bf16_f32 v18, v34, v38
	v_cvt_pk_bf16_f32 v19, v42, v50
	v_cvt_pk_bf16_f32 v24, v37, v41
	v_cvt_pk_bf16_f32 v25, v45, v53
	v_cvt_pk_bf16_f32 v26, v14, v10
	ds_write2_b64 v147, v[22:23], v[2:3] offset0:100 offset1:116
	v_cvt_pk_bf16_f32 v2, v17, v13
	v_cvt_pk_bf16_f32 v3, v9, v5
	ds_write2_b64 v146, v[66:67], v[56:57] offset1:16
	ds_write2_b64 v147, v[18:19], v[26:27] offset0:32 offset1:48
	ds_write2_b64 v147, v[24:25], v[2:3] offset0:134 offset1:150
	v_mul_u32_u24_e32 v68, 0x110, v149
	s_waitcnt lgkmcnt(0)
	v_add_u32_e32 v82, v148, v68
	ds_read_b128 v[2:5], v82
	ds_read_b128 v[6:9], v82 offset:4352
	global_load_dwordx4 v[10:13], v[136:137], off
	global_load_dwordx4 v[14:17], v[136:137], off offset:256
	global_load_dwordx4 v[18:21], v[136:137], off offset:512
	global_load_dwordx4 v[22:25], v[136:137], off offset:768
	s_and_b64 vcc, exec, s[36:37]
	s_waitcnt vmcnt(3) lgkmcnt(1)
	v_mfma_f32_16x16x32_bf16 v[26:29], v[2:5], v[10:13], 0
	s_waitcnt vmcnt(2)
	v_mfma_f32_16x16x32_bf16 v[30:33], v[2:5], v[14:17], 0
	s_waitcnt lgkmcnt(0)
	v_mfma_f32_16x16x32_bf16 v[42:45], v[6:9], v[14:17], 0
	ds_read_b128 v[14:17], v82 offset:64
	ds_read_b128 v[50:53], v82 offset:4416
	global_load_dwordx4 v[54:57], v[136:137], off offset:64
	global_load_dwordx4 v[58:61], v[136:137], off offset:320
	global_load_dwordx4 v[62:65], v[136:137], off offset:576
	global_load_dwordx4 v[66:69], v[136:137], off offset:832
	s_waitcnt vmcnt(5)
	v_mfma_f32_16x16x32_bf16 v[34:37], v[2:5], v[18:21], 0
	s_waitcnt vmcnt(4)
	v_mfma_f32_16x16x32_bf16 v[2:5], v[2:5], v[22:25], 0
	v_mfma_f32_16x16x32_bf16 v[10:13], v[6:9], v[10:13], 0
	v_mfma_f32_16x16x32_bf16 v[46:49], v[6:9], v[18:21], 0
	v_mfma_f32_16x16x32_bf16 v[6:9], v[6:9], v[22:25], 0
	s_waitcnt vmcnt(3) lgkmcnt(1)
	v_mfma_f32_16x16x32_bf16 v[38:41], v[14:17], v[54:57], v[26:29]
	s_waitcnt vmcnt(2)
	v_mfma_f32_16x16x32_bf16 v[18:21], v[14:17], v[58:61], v[30:33]
	s_waitcnt vmcnt(1)
	v_mfma_f32_16x16x32_bf16 v[26:29], v[14:17], v[62:65], v[34:37]
	s_nop 0
	ds_read_b128 v[30:33], v82 offset:128
	s_nop 0
	ds_read_b128 v[34:37], v82 offset:4480
	s_waitcnt vmcnt(0)
	v_mfma_f32_16x16x32_bf16 v[22:25], v[14:17], v[66:69], v[2:5]
	s_waitcnt lgkmcnt(2)
	v_mfma_f32_16x16x32_bf16 v[14:17], v[50:53], v[54:57], v[10:13]
	v_mfma_f32_16x16x32_bf16 v[2:5], v[50:53], v[58:61], v[42:45]
	v_mfma_f32_16x16x32_bf16 v[10:13], v[50:53], v[62:65], v[46:49]
	v_mfma_f32_16x16x32_bf16 v[6:9], v[50:53], v[66:69], v[6:9]
	s_nop 0
	global_load_dwordx4 v[42:45], v[136:137], off offset:128
	global_load_dwordx4 v[46:49], v[136:137], off offset:384
	global_load_dwordx4 v[50:53], v[136:137], off offset:640
	global_load_dwordx4 v[54:57], v[136:137], off offset:896
	s_waitcnt vmcnt(3) lgkmcnt(1)
	v_mfma_f32_16x16x32_bf16 v[58:61], v[30:33], v[42:45], 0
	s_waitcnt vmcnt(2)
	v_mfma_f32_16x16x32_bf16 v[66:69], v[30:33], v[46:49], 0
	s_waitcnt lgkmcnt(0)
	v_mfma_f32_16x16x32_bf16 v[74:77], v[34:37], v[46:49], 0
	ds_read_b128 v[46:49], v82 offset:192
	ds_read_b128 v[82:85], v82 offset:4544
	global_load_dwordx4 v[86:89], v[136:137], off offset:192
	global_load_dwordx4 v[90:93], v[136:137], off offset:448
	global_load_dwordx4 v[94:97], v[136:137], off offset:704
	global_load_dwordx4 v[100:103], v[136:137], off offset:960
	s_waitcnt lgkmcnt(0)
	s_waitcnt vmcnt(5)
	v_mfma_f32_16x16x32_bf16 v[70:73], v[30:33], v[50:53], 0
	s_waitcnt vmcnt(4)
	v_mfma_f32_16x16x32_bf16 v[30:33], v[30:33], v[54:57], 0
	v_mfma_f32_16x16x32_bf16 v[78:81], v[34:37], v[50:53], 0
	s_waitcnt vmcnt(3) lgkmcnt(1)
	v_mfma_f32_16x16x32_bf16 v[62:65], v[46:49], v[86:89], v[58:61]
	s_waitcnt vmcnt(2)
	v_mfma_f32_16x16x32_bf16 v[50:53], v[46:49], v[90:93], v[66:69]
	v_mfma_f32_16x16x32_bf16 v[42:45], v[34:37], v[42:45], 0
	s_nop 1
	v_mov_b32_e32 v66, v38
	v_mov_b32_e32 v67, v18
	s_nop 0
	v_mov_b32_e32 v68, v62
	v_mfma_f32_16x16x32_bf16 v[34:37], v[34:37], v[54:57], 0
	v_mov_b32_e32 v69, v50
	s_waitcnt vmcnt(1)
	v_mfma_f32_16x16x32_bf16 v[58:61], v[46:49], v[94:97], v[70:73]
	s_waitcnt vmcnt(0)
	v_mfma_f32_16x16x32_bf16 v[54:57], v[46:49], v[100:103], v[30:33]
	s_nop 0
	v_add_f32_e64 v70, v66, v68
	v_add_f32_e64 v71, v67, v69
	s_nop 2
	v_mov_b32_e32 v72, v58
	s_waitcnt lgkmcnt(0)
	v_mfma_f32_16x16x32_bf16 v[30:33], v[82:85], v[90:93], v[74:77]
	s_nop 2
	v_cvt_pk_bf16_f32 v74, v70, v71
	v_mov_b32_e32 v70, v26
	v_mov_b32_e32 v71, v22
	v_mov_b32_e32 v73, v54
	v_pk_add_f32 v[76:77], v[70:71], v[72:73]
	v_mfma_f32_16x16x32_bf16 v[46:49], v[82:85], v[86:89], v[42:45]
	v_cvt_pk_bf16_f32 v75, v76, v77
	v_add_u32_e32 v76, 0x800, v134
	v_ashrrev_i32_e32 v77, 31, v76
	v_mfma_f32_16x16x32_bf16 v[42:45], v[82:85], v[94:97], v[78:81]
	v_lshlrev_b64 v[76:77], 11, v[76:77]
	v_lshl_add_u64 v[76:77], v[132:133], 0, v[76:77]
	global_store_dwordx2 v[76:77], v[74:75], off sc1
	v_mfma_f32_16x16x32_bf16 v[34:37], v[82:85], v[100:103], v[34:37]
	s_cbranch_vccnz .LBB0_731
	v_pk_add_f32 v[66:67], v[66:67], v[68:69] neg_lo:[0,1] neg_hi:[0,1]
	v_pk_add_f32 v[68:69], v[70:71], v[72:73] neg_lo:[0,1] neg_hi:[0,1]
	v_cvt_pk_bf16_f32 v66, v66, v67
	v_cvt_pk_bf16_f32 v67, v68, v69
	v_sub_u32_e32 v68, 31, v98
	v_ashrrev_i32_e32 v69, 31, v68
	v_lshlrev_b64 v[68:69], 17, v[68:69]
	v_subrev_co_u32_e32 v68, vcc, s30, v68
	s_nop 1
	v_subbrev_co_u32_e32 v69, vcc, 0, v69, vcc
	v_lshl_add_u64 v[68:69], v[132:133], 0, v[68:69]
	v_add_co_u32_e32 v68, vcc, 0x20000, v68
	s_nop 1
	v_addc_co_u32_e32 v69, vcc, 0, v69, vcc
	global_store_dwordx2 v[68:69], v[66:67], off sc1
.LBB0_731:
	v_mov_b32_e32 v18, v39
	v_mov_b32_e32 v50, v63
	v_pk_add_f32 v[38:39], v[18:19], v[50:51]
	v_mov_b32_e32 v22, v27
	v_mov_b32_e32 v54, v59
	v_cvt_pk_bf16_f32 v26, v38, v39
	v_pk_add_f32 v[38:39], v[22:23], v[54:55]
	s_and_b64 vcc, exec, s[36:37]
	v_cvt_pk_bf16_f32 v27, v38, v39
	v_add_u32_e32 v38, 0x840, v134
	v_ashrrev_i32_e32 v39, 31, v38
	v_lshlrev_b64 v[38:39], 11, v[38:39]
	v_lshl_add_u64 v[38:39], v[132:133], 0, v[38:39]
	global_store_dwordx2 v[38:39], v[26:27], off sc1
	s_cbranch_vccnz .LBB0_733
	v_pk_add_f32 v[18:19], v[18:19], v[50:51] neg_lo:[0,1] neg_hi:[0,1]
	v_pk_add_f32 v[22:23], v[22:23], v[54:55] neg_lo:[0,1] neg_hi:[0,1]
	v_cvt_pk_bf16_f32 v18, v18, v19
	v_cvt_pk_bf16_f32 v19, v22, v23
	v_sub_u32_e32 v22, 30, v98
	v_ashrrev_i32_e32 v23, 31, v22
	v_lshlrev_b64 v[22:23], 17, v[22:23]
	v_subrev_co_u32_e32 v22, vcc, s30, v22
	s_nop 1
	v_subbrev_co_u32_e32 v23, vcc, 0, v23, vcc
	v_lshl_add_u64 v[22:23], v[132:133], 0, v[22:23]
	v_add_co_u32_e32 v22, vcc, 0x20000, v22
	s_nop 1
	v_addc_co_u32_e32 v23, vcc, 0, v23, vcc
	global_store_dwordx2 v[22:23], v[18:19], off sc1
.LBB0_733:
	v_mov_b32_e32 v18, v40
	v_mov_b32_e32 v19, v20
	v_mov_b32_e32 v22, v64
	v_mov_b32_e32 v23, v52
	v_pk_add_f32 v[26:27], v[18:19], v[22:23]
	v_mov_b32_e32 v38, v60
	v_cvt_pk_bf16_f32 v50, v26, v27
	v_mov_b32_e32 v26, v28
	v_mov_b32_e32 v27, v24
	v_mov_b32_e32 v39, v56
	v_pk_add_f32 v[54:55], v[26:27], v[38:39]
	s_and_b64 vcc, exec, s[36:37]
	v_cvt_pk_bf16_f32 v51, v54, v55
	v_add_u32_e32 v54, 0x880, v134
	v_ashrrev_i32_e32 v55, 31, v54
	v_lshlrev_b64 v[54:55], 11, v[54:55]
	v_lshl_add_u64 v[54:55], v[132:133], 0, v[54:55]
	global_store_dwordx2 v[54:55], v[50:51], off sc1
	s_cbranch_vccnz .LBB0_735
	v_pk_add_f32 v[18:19], v[18:19], v[22:23] neg_lo:[0,1] neg_hi:[0,1]
	v_pk_add_f32 v[22:23], v[26:27], v[38:39] neg_lo:[0,1] neg_hi:[0,1]
	v_cvt_pk_bf16_f32 v18, v18, v19
	v_cvt_pk_bf16_f32 v19, v22, v23
	v_sub_u32_e32 v22, 29, v98
	v_ashrrev_i32_e32 v23, 31, v22
	v_lshlrev_b64 v[22:23], 17, v[22:23]
	v_subrev_co_u32_e32 v22, vcc, s30, v22
	s_nop 1
	v_subbrev_co_u32_e32 v23, vcc, 0, v23, vcc
	v_lshl_add_u64 v[22:23], v[132:133], 0, v[22:23]
	v_add_co_u32_e32 v22, vcc, 0x20000, v22
	s_nop 1
	v_addc_co_u32_e32 v23, vcc, 0, v23, vcc
	global_store_dwordx2 v[22:23], v[18:19], off sc1
.LBB0_735:
	v_mov_b32_e32 v20, v41
	v_mov_b32_e32 v52, v65
	v_mov_b32_e32 v24, v29
	v_mov_b32_e32 v56, v61
	v_pk_add_f32 v[18:19], v[20:21], v[52:53]
	v_pk_add_f32 v[22:23], v[24:25], v[56:57]
	v_cvt_pk_bf16_f32 v18, v18, v19
	v_cvt_pk_bf16_f32 v19, v22, v23
	v_add_u32_e32 v22, 0x8c0, v134
	v_ashrrev_i32_e32 v23, 31, v22
	v_lshlrev_b64 v[22:23], 11, v[22:23]
	v_lshl_add_u64 v[22:23], v[132:133], 0, v[22:23]
	s_and_b64 vcc, exec, s[36:37]
	global_store_dwordx2 v[22:23], v[18:19], off sc1
	s_cbranch_vccnz .LBB0_737
	v_pk_add_f32 v[18:19], v[20:21], v[52:53] neg_lo:[0,1] neg_hi:[0,1]
	v_pk_add_f32 v[20:21], v[24:25], v[56:57] neg_lo:[0,1] neg_hi:[0,1]
	v_cvt_pk_bf16_f32 v18, v18, v19
	v_cvt_pk_bf16_f32 v19, v20, v21
	v_sub_u32_e32 v20, 28, v98
	v_ashrrev_i32_e32 v21, 31, v20
	v_lshlrev_b64 v[20:21], 17, v[20:21]
	v_subrev_co_u32_e32 v20, vcc, s30, v20
	s_nop 1
	v_subbrev_co_u32_e32 v21, vcc, 0, v21, vcc
	v_lshl_add_u64 v[20:21], v[132:133], 0, v[20:21]
	v_add_co_u32_e32 v20, vcc, 0x20000, v20
	s_nop 1
	v_addc_co_u32_e32 v21, vcc, 0, v21, vcc
	global_store_dwordx2 v[20:21], v[18:19], off sc1
.LBB0_737:
	v_mov_b32_e32 v18, v14
	v_mov_b32_e32 v19, v2
	v_mov_b32_e32 v20, v46
	v_mov_b32_e32 v21, v30
	v_pk_add_f32 v[22:23], v[18:19], v[20:21]
	v_mov_b32_e32 v24, v42
	v_cvt_pk_bf16_f32 v26, v22, v23
	v_mov_b32_e32 v22, v10
	v_mov_b32_e32 v23, v6
	v_mov_b32_e32 v25, v34
	v_pk_add_f32 v[28:29], v[22:23], v[24:25]
	s_and_b64 vcc, exec, s[36:37]
	v_cvt_pk_bf16_f32 v27, v28, v29
	v_add_u32_e32 v28, 0xc00, v134
	v_ashrrev_i32_e32 v29, 31, v28
	v_lshlrev_b64 v[28:29], 11, v[28:29]
	v_lshl_add_u64 v[28:29], v[132:133], 0, v[28:29]
	global_store_dwordx2 v[28:29], v[26:27], off sc1
	s_cbranch_vccnz .LBB0_739
	v_pk_add_f32 v[18:19], v[18:19], v[20:21] neg_lo:[0,1] neg_hi:[0,1]
	v_pk_add_f32 v[20:21], v[22:23], v[24:25] neg_lo:[0,1] neg_hi:[0,1]
	v_cvt_pk_bf16_f32 v18, v18, v19
	v_cvt_pk_bf16_f32 v19, v20, v21
	v_sub_u32_e32 v20, 15, v98
	v_ashrrev_i32_e32 v21, 31, v20
	v_lshlrev_b64 v[20:21], 17, v[20:21]
	v_subrev_co_u32_e32 v20, vcc, s30, v20
	s_nop 1
	v_subbrev_co_u32_e32 v21, vcc, 0, v21, vcc
	v_lshl_add_u64 v[20:21], v[132:133], 0, v[20:21]
	v_add_co_u32_e32 v20, vcc, 0x20000, v20
	s_nop 1
	v_addc_co_u32_e32 v21, vcc, 0, v21, vcc
	global_store_dwordx2 v[20:21], v[18:19], off sc1
.LBB0_739:
	v_mov_b32_e32 v2, v15
	v_mov_b32_e32 v30, v47
	v_pk_add_f32 v[14:15], v[2:3], v[30:31]
	v_mov_b32_e32 v6, v11
	v_mov_b32_e32 v34, v43
	v_cvt_pk_bf16_f32 v10, v14, v15
	v_pk_add_f32 v[14:15], v[6:7], v[34:35]
	s_and_b64 vcc, exec, s[36:37]
	v_cvt_pk_bf16_f32 v11, v14, v15
	v_add_u32_e32 v14, 0xc40, v134
	v_ashrrev_i32_e32 v15, 31, v14
	v_lshlrev_b64 v[14:15], 11, v[14:15]
	v_lshl_add_u64 v[14:15], v[132:133], 0, v[14:15]
	global_store_dwordx2 v[14:15], v[10:11], off sc1
	s_cbranch_vccnz .LBB0_741
	v_pk_add_f32 v[2:3], v[2:3], v[30:31] neg_lo:[0,1] neg_hi:[0,1]
	v_pk_add_f32 v[6:7], v[6:7], v[34:35] neg_lo:[0,1] neg_hi:[0,1]
	v_cvt_pk_bf16_f32 v2, v2, v3
	v_cvt_pk_bf16_f32 v3, v6, v7
	v_sub_u32_e32 v6, 14, v98
	v_ashrrev_i32_e32 v7, 31, v6
	v_lshlrev_b64 v[6:7], 17, v[6:7]
	v_subrev_co_u32_e32 v6, vcc, s30, v6
	s_nop 1
	v_subbrev_co_u32_e32 v7, vcc, 0, v7, vcc
	v_lshl_add_u64 v[6:7], v[132:133], 0, v[6:7]
	v_add_co_u32_e32 v6, vcc, 0x20000, v6
	s_nop 1
	v_addc_co_u32_e32 v7, vcc, 0, v7, vcc
	global_store_dwordx2 v[6:7], v[2:3], off sc1
.LBB0_741:
	v_mov_b32_e32 v2, v16
	v_mov_b32_e32 v3, v4
	v_mov_b32_e32 v6, v48
	v_mov_b32_e32 v7, v32
	v_pk_add_f32 v[10:11], v[2:3], v[6:7]
	v_mov_b32_e32 v14, v44
	v_cvt_pk_bf16_f32 v18, v10, v11
	v_mov_b32_e32 v10, v12
	v_mov_b32_e32 v11, v8
	v_mov_b32_e32 v15, v36
	v_pk_add_f32 v[20:21], v[10:11], v[14:15]
	s_and_b64 vcc, exec, s[36:37]
	v_cvt_pk_bf16_f32 v19, v20, v21
	v_add_u32_e32 v20, 0xc80, v134
	v_ashrrev_i32_e32 v21, 31, v20
	v_lshlrev_b64 v[20:21], 11, v[20:21]
	v_lshl_add_u64 v[20:21], v[132:133], 0, v[20:21]
	global_store_dwordx2 v[20:21], v[18:19], off sc1
	s_cbranch_vccnz .LBB0_743
	v_pk_add_f32 v[2:3], v[2:3], v[6:7] neg_lo:[0,1] neg_hi:[0,1]
	v_pk_add_f32 v[6:7], v[10:11], v[14:15] neg_lo:[0,1] neg_hi:[0,1]
	v_cvt_pk_bf16_f32 v2, v2, v3
	v_cvt_pk_bf16_f32 v3, v6, v7
	v_sub_u32_e32 v6, 13, v98
	v_ashrrev_i32_e32 v7, 31, v6
	v_lshlrev_b64 v[6:7], 17, v[6:7]
	v_subrev_co_u32_e32 v6, vcc, s30, v6
	s_nop 1
	v_subbrev_co_u32_e32 v7, vcc, 0, v7, vcc
	v_lshl_add_u64 v[6:7], v[132:133], 0, v[6:7]
	v_add_co_u32_e32 v6, vcc, 0x20000, v6
	s_nop 1
	v_addc_co_u32_e32 v7, vcc, 0, v7, vcc
	global_store_dwordx2 v[6:7], v[2:3], off sc1
.LBB0_743:
	v_mov_b32_e32 v4, v17
	v_mov_b32_e32 v32, v49
	v_mov_b32_e32 v8, v13
	v_mov_b32_e32 v36, v45
	v_pk_add_f32 v[2:3], v[4:5], v[32:33]
	v_pk_add_f32 v[6:7], v[8:9], v[36:37]
	v_cvt_pk_bf16_f32 v2, v2, v3
	v_cvt_pk_bf16_f32 v3, v6, v7
	v_add_u32_e32 v6, 0xcc0, v134
	v_ashrrev_i32_e32 v7, 31, v6
	v_lshlrev_b64 v[6:7], 11, v[6:7]
	v_lshl_add_u64 v[6:7], v[132:133], 0, v[6:7]
	s_and_b64 vcc, exec, s[36:37]
	s_mov_b64 s[14:15], 0
	global_store_dwordx2 v[6:7], v[2:3], off sc1
	s_cbranch_vccnz .LBB0_745
	v_pk_add_f32 v[2:3], v[4:5], v[32:33] neg_lo:[0,1] neg_hi:[0,1]
	v_pk_add_f32 v[4:5], v[8:9], v[36:37] neg_lo:[0,1] neg_hi:[0,1]
	v_cvt_pk_bf16_f32 v2, v2, v3
	v_cvt_pk_bf16_f32 v3, v4, v5
	v_sub_u32_e32 v6, 12, v98
	s_mov_b64 s[14:15], -1

.LBB0_750:
	s_lshl_b32 s5, s18, 14
	s_add_i32 s4, s41, 0
	s_or_b32 s5, s5, s27
	v_readlane_b32 s6, v254, 21
	s_add_u32 s12, s6, s5
	v_readlane_b32 s5, v254, 22
	s_addc_u32 s13, s5, 0
	s_add_i32 s20, s10, s0
	s_ashr_i32 s21, s20, 31
	s_lshl_b64 s[20:21], s[20:21], 11
	v_readlane_b32 s5, v254, 23
	s_add_u32 s5, s5, s20
	v_readlane_b32 s6, v254, 24
	s_addc_u32 s18, s6, s21
	s_lshl_b32 s10, s11, 1
	s_add_u32 s10, s5, s10
	s_addc_u32 s11, s18, 0
	v_lshlrev_b32_e32 v98, 1, v148
	s_movk_i32 s5, 0x440
	v_lshl_add_u64 v[132:133], s[10:11], 0, v[98:99]
	v_lshl_add_u32 v98, v149, 3, s4
	v_cvt_pk_bf16_f32 v137, v120, v116
	v_mul_lo_u32 v116, v186, s5
	v_add_u32_e32 v146, v98, v116
	v_cvt_pk_bf16_f32 v116, v129, v125
	v_cvt_pk_bf16_f32 v117, v121, v117
	v_cvt_pk_bf16_f32 v121, v122, v118
	v_cvt_pk_bf16_f32 v122, v82, v86
	v_cvt_pk_bf16_f32 v82, v83, v87
	v_cvt_pk_bf16_f32 v83, v91, v95
	v_cvt_pk_bf16_f32 v120, v130, v126
	ds_write2_b64 v146, v[116:117], v[82:83] offset0:34 offset1:50
	v_cvt_pk_bf16_f32 v82, v84, v88
	v_cvt_pk_bf16_f32 v83, v92, v96
	v_cvt_pk_bf16_f32 v119, v123, v119
	v_cvt_pk_bf16_f32 v123, v90, v94
	ds_write2_b64 v146, v[120:121], v[82:83] offset0:68 offset1:84
	v_cvt_pk_bf16_f32 v82, v85, v89
	v_cvt_pk_bf16_f32 v84, v113, v109
	v_cvt_pk_bf16_f32 v85, v105, v101
	v_cvt_pk_bf16_f32 v90, v66, v70
	v_add_u32_e32 v147, 0x1000, v146
	v_cvt_pk_bf16_f32 v66, v67, v71
	v_cvt_pk_bf16_f32 v67, v75, v79
	v_cvt_pk_bf16_f32 v118, v131, v127
	v_cvt_pk_bf16_f32 v83, v93, v97
	v_cvt_pk_bf16_f32 v86, v114, v110
	v_cvt_pk_bf16_f32 v87, v106, v102
	ds_write2_b64 v147, v[84:85], v[66:67] offset0:66 offset1:82
	v_cvt_pk_bf16_f32 v66, v68, v72
	v_cvt_pk_bf16_f32 v67, v76, v80
	v_cvt_pk_bf16_f32 v136, v128, v124
	ds_write2_b64 v146, v[118:119], v[82:83] offset0:102 offset1:118
	v_cvt_pk_bf16_f32 v82, v112, v108
	v_cvt_pk_bf16_f32 v83, v104, v100
	v_cvt_pk_bf16_f32 v88, v115, v111
	v_cvt_pk_bf16_f32 v89, v107, v103
	v_cvt_pk_bf16_f32 v91, v74, v78
	ds_write2_b64 v147, v[86:87], v[66:67] offset0:100 offset1:116
	v_cvt_pk_bf16_f32 v66, v69, v73
	v_cvt_pk_bf16_f32 v67, v77, v81
	ds_write2_b64 v146, v[136:137], v[122:123] offset1:16
	ds_write2_b64 v147, v[82:83], v[90:91] offset0:32 offset1:48
	ds_write2_b64 v147, v[88:89], v[66:67] offset0:134 offset1:150
	v_lshl_add_u64 v[134:135], v[150:151], 1, s[12:13]
	s_waitcnt lgkmcnt(0)
	v_lshlrev_b32_e32 v98, 10, v149
	v_lshl_add_u64 v[136:137], v[134:135], 0, v[98:99]
	global_load_dwordx4 v[78:81], v[136:137], off offset:256
	global_load_dwordx4 v[120:123], v[136:137], off offset:320
	global_load_dwordx4 v[66:69], v[136:137], off
	global_load_dwordx4 v[116:119], v[136:137], off offset:64
	global_load_dwordx4 v[86:89], v[136:137], off offset:512
	global_load_dwordx4 v[94:97], v[136:137], off offset:768
	v_and_b32_e32 v70, -16, v210
	v_add_u32_e32 v148, s4, v70
	s_movk_i32 s4, 0x110
	v_mad_u32_u24 v98, v149, s4, v148
	ds_read_b128 v[70:73], v98
	ds_read_b128 v[108:111], v98 offset:64
	ds_read_b128 v[100:103], v98 offset:4352
	ds_read_b128 v[124:127], v98 offset:4416
	ds_read_b128 v[138:141], v98 offset:4480
	s_add_i32 s4, s0, -1
	s_cmp_lt_u32 s4, 31
	s_cselect_b64 s[10:11], -1, 0
	s_lshl_b32 s30, s0, 12
	s_and_b64 vcc, exec, s[10:11]
	s_waitcnt vmcnt(5) lgkmcnt(4)
	v_mfma_f32_16x16x32_bf16 v[82:85], v[70:73], v[78:81], 0
	global_load_dwordx4 v[128:131], v[136:137], off offset:896
	global_load_dwordx4 v[162:165], v[136:137], off offset:960
	ds_read_b128 v[154:157], v98 offset:192
	s_waitcnt vmcnt(5)
	v_mfma_f32_16x16x32_bf16 v[74:77], v[70:73], v[66:69], 0
	global_load_dwordx4 v[158:161], v[136:137], off offset:704
	s_waitcnt vmcnt(4)
	v_mfma_f32_16x16x32_bf16 v[90:93], v[70:73], v[86:89], 0
	s_waitcnt vmcnt(3)
	v_mfma_f32_16x16x32_bf16 v[70:73], v[70:73], v[94:97], 0
	s_waitcnt lgkmcnt(3)
	v_mfma_f32_16x16x32_bf16 v[66:69], v[100:103], v[66:69], 0
	v_mfma_f32_16x16x32_bf16 v[78:81], v[100:103], v[78:81], 0
	v_mfma_f32_16x16x32_bf16 v[86:89], v[100:103], v[86:89], 0
	v_mfma_f32_16x16x32_bf16 v[94:97], v[100:103], v[94:97], 0
	v_mfma_f32_16x16x32_bf16 v[100:103], v[108:111], v[120:123], v[82:85]
	s_nop 2
	global_load_dwordx4 v[82:85], v[136:137], off offset:576
	s_waitcnt vmcnt(0)
	v_mfma_f32_16x16x32_bf16 v[112:115], v[108:111], v[82:85], v[90:93]
	s_nop 2
	global_load_dwordx4 v[90:93], v[136:137], off offset:832
	v_mfma_f32_16x16x32_bf16 v[104:107], v[108:111], v[116:119], v[74:77]
	s_waitcnt lgkmcnt(2)
	v_mfma_f32_16x16x32_bf16 v[74:77], v[124:127], v[116:119], v[66:69]
	v_mfma_f32_16x16x32_bf16 v[66:69], v[124:127], v[120:123], v[78:81]
	global_load_dwordx4 v[120:123], v[136:137], off offset:640
	s_waitcnt vmcnt(1)
	v_mfma_f32_16x16x32_bf16 v[78:81], v[124:127], v[90:93], v[94:97]
	s_nop 2
	global_load_dwordx4 v[94:97], v[136:137], off offset:384
	v_mfma_f32_16x16x32_bf16 v[108:111], v[108:111], v[90:93], v[70:73]
	v_mfma_f32_16x16x32_bf16 v[70:73], v[124:127], v[82:85], v[86:89]
	global_load_dwordx4 v[82:85], v[136:137], off offset:128
	s_nop 1
	ds_read_b128 v[86:89], v98 offset:128
	s_waitcnt vmcnt(1) lgkmcnt(0)
	v_mfma_f32_16x16x32_bf16 v[116:119], v[86:89], v[94:97], 0
	v_mfma_f32_16x16x32_bf16 v[142:145], v[138:141], v[94:97], 0
	global_load_dwordx4 v[94:97], v[136:137], off offset:192
	s_waitcnt vmcnt(1)
	v_mfma_f32_16x16x32_bf16 v[90:93], v[86:89], v[82:85], 0
	v_mfma_f32_16x16x32_bf16 v[124:127], v[86:89], v[120:123], 0
	v_mfma_f32_16x16x32_bf16 v[150:153], v[138:141], v[120:123], 0
	s_waitcnt vmcnt(0)
	v_mfma_f32_16x16x32_bf16 v[120:123], v[154:157], v[94:97], v[90:93]
	s_nop 3
	global_load_dwordx4 v[90:93], v[136:137], off offset:448
	v_mfma_f32_16x16x32_bf16 v[86:89], v[86:89], v[128:131], 0
	v_mfma_f32_16x16x32_bf16 v[82:85], v[138:141], v[82:85], 0
	v_mfma_f32_16x16x32_bf16 v[138:141], v[138:141], v[128:131], 0
	v_mfma_f32_16x16x32_bf16 v[128:131], v[154:157], v[158:161], v[124:127]
	v_mfma_f32_16x16x32_bf16 v[124:127], v[154:157], v[162:165], v[86:89]
	s_nop 3
	ds_read_b128 v[86:89], v98 offset:4544
	s_waitcnt vmcnt(0)
	v_mfma_f32_16x16x32_bf16 v[116:119], v[154:157], v[90:93], v[116:119]
	v_lshl_add_u32 v98, v186, 2, s1
	s_waitcnt lgkmcnt(0)
	s_waitcnt lgkmcnt(0)
	v_mfma_f32_16x16x32_bf16 v[94:97], v[86:89], v[94:97], v[82:85]
	v_mfma_f32_16x16x32_bf16 v[82:85], v[86:89], v[90:93], v[142:145]
	v_mfma_f32_16x16x32_bf16 v[90:93], v[86:89], v[158:161], v[150:153]
	s_nop 1
	v_mov_b32_e32 v142, v112
	v_mov_b32_e32 v143, v108
	v_mov_b32_e32 v144, v128
	v_mfma_f32_16x16x32_bf16 v[86:89], v[86:89], v[162:165], v[138:141]
	v_mov_b32_e32 v145, v124
	s_nop 1
	v_mov_b32_e32 v138, v104
	v_mov_b32_e32 v139, v100
	v_mov_b32_e32 v140, v120
	v_mov_b32_e32 v141, v116
	v_pk_add_f32 v[134:135], v[138:139], v[140:141]
	s_nop 0
	v_cvt_pk_bf16_f32 v150, v134, v135
	v_pk_add_f32 v[134:135], v[142:143], v[144:145]
	s_nop 0
	v_cvt_pk_bf16_f32 v151, v134, v135
	v_lshlrev_b32_e32 v134, 6, v98
	v_ashrrev_i32_e32 v135, 31, v134
	v_lshlrev_b64 v[152:153], 11, v[134:135]
	v_lshl_add_u64 v[152:153], v[132:133], 0, v[152:153]
	global_store_dwordx2 v[152:153], v[150:151], off sc1
	s_cbranch_vccz .LBB0_752
	v_pk_add_f32 v[138:139], v[138:139], v[140:141] neg_lo:[0,1] neg_hi:[0,1]
	v_pk_add_f32 v[140:141], v[142:143], v[144:145] neg_lo:[0,1] neg_hi:[0,1]
	v_cvt_pk_bf16_f32 v138, v138, v139
	v_cvt_pk_bf16_f32 v139, v140, v141
	v_sub_u32_e32 v140, 0x7f, v98
	v_ashrrev_i32_e32 v141, 31, v140
	v_lshlrev_b64 v[140:141], 17, v[140:141]
	v_subrev_co_u32_e32 v140, vcc, s30, v140
	s_nop 1
	v_subbrev_co_u32_e32 v141, vcc, 0, v141, vcc
	v_lshl_add_u64 v[140:141], v[132:133], 0, v[140:141]
	v_add_co_u32_e32 v140, vcc, 0x20000, v140
	s_nop 1
	v_addc_co_u32_e32 v141, vcc, 0, v141, vcc
	global_store_dwordx2 v[140:141], v[138:139], off sc1
.LBB0_752:
	v_mov_b32_e32 v100, v105
	v_mov_b32_e32 v116, v121
	v_mov_b32_e32 v108, v113
	v_mov_b32_e32 v124, v129
	v_pk_add_f32 v[104:105], v[100:101], v[116:117]
	v_pk_add_f32 v[112:113], v[108:109], v[124:125]
	v_cvt_pk_bf16_f32 v104, v104, v105
	v_cvt_pk_bf16_f32 v105, v112, v113
	v_or_b32_e32 v112, 64, v134
	v_ashrrev_i32_e32 v113, 31, v112
	v_lshlrev_b64 v[112:113], 11, v[112:113]
	v_cndmask_b32_e64 v120, 0, 1, s[10:11]
	v_lshl_add_u64 v[112:113], v[132:133], 0, v[112:113]
	v_cmp_ne_u32_e64 s[36:37], 1, v120
	s_andn2_b64 vcc, exec, s[10:11]
	global_store_dwordx2 v[112:113], v[104:105], off sc1
	s_cbranch_vccnz .LBB0_754
	v_pk_add_f32 v[100:101], v[100:101], v[116:117] neg_lo:[0,1] neg_hi:[0,1]
	v_pk_add_f32 v[104:105], v[108:109], v[124:125] neg_lo:[0,1] neg_hi:[0,1]
	v_cvt_pk_bf16_f32 v100, v100, v101
	v_cvt_pk_bf16_f32 v101, v104, v105
	v_xor_b32_e32 v104, -2, v98
	v_ashrrev_i32_e32 v105, 31, v104
	v_lshlrev_b64 v[104:105], 17, v[104:105]
	v_subrev_co_u32_e32 v104, vcc, s30, v104
	s_nop 1
	v_subbrev_co_u32_e32 v105, vcc, 0, v105, vcc
	v_lshl_add_u64 v[104:105], v[132:133], 0, v[104:105]
	v_add_co_u32_e32 v104, vcc, 0x1020000, v104
	s_nop 1
	v_addc_co_u32_e32 v105, vcc, 0, v105, vcc
	global_store_dwordx2 v[104:105], v[100:101], off sc1
.LBB0_754:
	v_mov_b32_e32 v100, v106
	v_mov_b32_e32 v101, v102
	v_mov_b32_e32 v104, v122
	v_mov_b32_e32 v105, v118
	v_pk_add_f32 v[108:109], v[100:101], v[104:105]
	v_mov_b32_e32 v112, v130
	v_cvt_pk_bf16_f32 v116, v108, v109
	v_mov_b32_e32 v108, v114
	v_mov_b32_e32 v109, v110
	v_mov_b32_e32 v113, v126
	v_pk_add_f32 v[120:121], v[108:109], v[112:113]
	s_and_b64 vcc, exec, s[36:37]
	v_cvt_pk_bf16_f32 v117, v120, v121
	v_or_b32_e32 v120, 0x80, v134
	v_ashrrev_i32_e32 v121, 31, v120
	v_lshlrev_b64 v[120:121], 11, v[120:121]
	v_lshl_add_u64 v[120:121], v[132:133], 0, v[120:121]
	global_store_dwordx2 v[120:121], v[116:117], off sc1
	s_cbranch_vccnz .LBB0_756
	v_pk_add_f32 v[100:101], v[100:101], v[104:105] neg_lo:[0,1] neg_hi:[0,1]
	v_pk_add_f32 v[104:105], v[108:109], v[112:113] neg_lo:[0,1] neg_hi:[0,1]
	v_cvt_pk_bf16_f32 v100, v100, v101
	v_cvt_pk_bf16_f32 v101, v104, v105
	v_xor_b32_e32 v104, -3, v98
	v_ashrrev_i32_e32 v105, 31, v104
	v_lshlrev_b64 v[104:105], 17, v[104:105]
	v_subrev_co_u32_e32 v104, vcc, s30, v104
	s_nop 1
	v_subbrev_co_u32_e32 v105, vcc, 0, v105, vcc
	v_lshl_add_u64 v[104:105], v[132:133], 0, v[104:105]
	v_add_co_u32_e32 v104, vcc, 0x1020000, v104
	s_nop 1
	v_addc_co_u32_e32 v105, vcc, 0, v105, vcc
	global_store_dwordx2 v[104:105], v[100:101], off sc1
.LBB0_756:
	v_mov_b32_e32 v102, v107
	v_mov_b32_e32 v118, v123
	v_mov_b32_e32 v110, v115
	v_mov_b32_e32 v126, v131
	v_pk_add_f32 v[100:101], v[102:103], v[118:119]
	v_pk_add_f32 v[104:105], v[110:111], v[126:127]
	v_cvt_pk_bf16_f32 v100, v100, v101
	v_cvt_pk_bf16_f32 v101, v104, v105
	v_or_b32_e32 v104, 0xc0, v134
	v_ashrrev_i32_e32 v105, 31, v104
	v_lshlrev_b64 v[104:105], 11, v[104:105]
	v_lshl_add_u64 v[104:105], v[132:133], 0, v[104:105]
	s_and_b64 vcc, exec, s[36:37]
	global_store_dwordx2 v[104:105], v[100:101], off sc1
	s_cbranch_vccnz .LBB0_758
	v_pk_add_f32 v[100:101], v[102:103], v[118:119] neg_lo:[0,1] neg_hi:[0,1]
	v_pk_add_f32 v[102:103], v[110:111], v[126:127] neg_lo:[0,1] neg_hi:[0,1]
	v_cvt_pk_bf16_f32 v100, v100, v101
	v_cvt_pk_bf16_f32 v101, v102, v103
	v_xor_b32_e32 v102, -4, v98
	v_ashrrev_i32_e32 v103, 31, v102
	v_lshlrev_b64 v[102:103], 17, v[102:103]
	v_subrev_co_u32_e32 v102, vcc, s30, v102
	s_nop 1
	v_subbrev_co_u32_e32 v103, vcc, 0, v103, vcc
	v_lshl_add_u64 v[102:103], v[132:133], 0, v[102:103]
	v_add_co_u32_e32 v102, vcc, 0x1020000, v102
	s_nop 1
	v_addc_co_u32_e32 v103, vcc, 0, v103, vcc
	global_store_dwordx2 v[102:103], v[100:101], off sc1
.LBB0_758:
	v_mov_b32_e32 v100, v74
	v_mov_b32_e32 v101, v66
	v_mov_b32_e32 v102, v94
	v_mov_b32_e32 v103, v82
	v_pk_add_f32 v[104:105], v[100:101], v[102:103]
	v_mov_b32_e32 v106, v90
	v_cvt_pk_bf16_f32 v108, v104, v105
	v_mov_b32_e32 v104, v70
	v_mov_b32_e32 v105, v78
	v_mov_b32_e32 v107, v86
	v_pk_add_f32 v[110:111], v[104:105], v[106:107]
	s_and_b64 vcc, exec, s[36:37]
	v_cvt_pk_bf16_f32 v109, v110, v111
	v_add_u32_e32 v110, 0x400, v134
	v_ashrrev_i32_e32 v111, 31, v110
	v_lshlrev_b64 v[110:111], 11, v[110:111]
	v_lshl_add_u64 v[110:111], v[132:133], 0, v[110:111]
	global_store_dwordx2 v[110:111], v[108:109], off sc1
	s_cbranch_vccnz .LBB0_760
	v_pk_add_f32 v[100:101], v[100:101], v[102:103] neg_lo:[0,1] neg_hi:[0,1]
	v_pk_add_f32 v[102:103], v[104:105], v[106:107] neg_lo:[0,1] neg_hi:[0,1]
	v_cvt_pk_bf16_f32 v100, v100, v101
	v_cvt_pk_bf16_f32 v101, v102, v103
	v_sub_u32_e32 v102, 0x6f, v98
	v_ashrrev_i32_e32 v103, 31, v102
	v_lshlrev_b64 v[102:103], 17, v[102:103]
	v_subrev_co_u32_e32 v102, vcc, s30, v102
	s_nop 1
	v_subbrev_co_u32_e32 v103, vcc, 0, v103, vcc
	v_lshl_add_u64 v[102:103], v[132:133], 0, v[102:103]
	v_add_co_u32_e32 v102, vcc, 0x20000, v102
	s_nop 1
	v_addc_co_u32_e32 v103, vcc, 0, v103, vcc
	global_store_dwordx2 v[102:103], v[100:101], off sc1
.LBB0_760:
	v_mov_b32_e32 v66, v75
	v_mov_b32_e32 v82, v95
	v_pk_add_f32 v[74:75], v[66:67], v[82:83]
	v_mov_b32_e32 v78, v71
	v_mov_b32_e32 v86, v91
	v_cvt_pk_bf16_f32 v70, v74, v75
	v_pk_add_f32 v[74:75], v[78:79], v[86:87]
	s_and_b64 vcc, exec, s[36:37]
	v_cvt_pk_bf16_f32 v71, v74, v75
	v_add_u32_e32 v74, 0x440, v134
	v_ashrrev_i32_e32 v75, 31, v74
	v_lshlrev_b64 v[74:75], 11, v[74:75]
	v_lshl_add_u64 v[74:75], v[132:133], 0, v[74:75]
	global_store_dwordx2 v[74:75], v[70:71], off sc1
	s_cbranch_vccnz .LBB0_762
	v_pk_add_f32 v[66:67], v[66:67], v[82:83] neg_lo:[0,1] neg_hi:[0,1]
	v_pk_add_f32 v[70:71], v[78:79], v[86:87] neg_lo:[0,1] neg_hi:[0,1]
	v_cvt_pk_bf16_f32 v66, v66, v67
	v_cvt_pk_bf16_f32 v67, v70, v71
	v_sub_u32_e32 v70, 0x6e, v98
	v_ashrrev_i32_e32 v71, 31, v70
	v_lshlrev_b64 v[70:71], 17, v[70:71]
	v_subrev_co_u32_e32 v70, vcc, s30, v70
	s_nop 1
	v_subbrev_co_u32_e32 v71, vcc, 0, v71, vcc
	v_lshl_add_u64 v[70:71], v[132:133], 0, v[70:71]
	v_add_co_u32_e32 v70, vcc, 0x20000, v70
	s_nop 1
	v_addc_co_u32_e32 v71, vcc, 0, v71, vcc
	global_store_dwordx2 v[70:71], v[66:67], off sc1
.LBB0_762:
	v_mov_b32_e32 v66, v76
	v_mov_b32_e32 v67, v68
	v_mov_b32_e32 v70, v96
	v_mov_b32_e32 v71, v84
	v_pk_add_f32 v[74:75], v[66:67], v[70:71]
	v_mov_b32_e32 v78, v92
	v_cvt_pk_bf16_f32 v82, v74, v75
	v_mov_b32_e32 v74, v72
	v_mov_b32_e32 v75, v80
	v_mov_b32_e32 v79, v88
	v_pk_add_f32 v[86:87], v[74:75], v[78:79]
	s_and_b64 vcc, exec, s[36:37]
	v_cvt_pk_bf16_f32 v83, v86, v87
	v_add_u32_e32 v86, 0x480, v134
	v_ashrrev_i32_e32 v87, 31, v86
	v_lshlrev_b64 v[86:87], 11, v[86:87]
	v_lshl_add_u64 v[86:87], v[132:133], 0, v[86:87]
	global_store_dwordx2 v[86:87], v[82:83], off sc1
	s_cbranch_vccnz .LBB0_764
	v_pk_add_f32 v[66:67], v[66:67], v[70:71] neg_lo:[0,1] neg_hi:[0,1]
	v_pk_add_f32 v[70:71], v[74:75], v[78:79] neg_lo:[0,1] neg_hi:[0,1]
	v_cvt_pk_bf16_f32 v66, v66, v67
	v_cvt_pk_bf16_f32 v67, v70, v71
	v_sub_u32_e32 v70, 0x6d, v98
	v_ashrrev_i32_e32 v71, 31, v70
	v_lshlrev_b64 v[70:71], 17, v[70:71]
	v_subrev_co_u32_e32 v70, vcc, s30, v70
	s_nop 1
	v_subbrev_co_u32_e32 v71, vcc, 0, v71, vcc
	v_lshl_add_u64 v[70:71], v[132:133], 0, v[70:71]
	v_add_co_u32_e32 v70, vcc, 0x20000, v70
	s_nop 1
	v_addc_co_u32_e32 v71, vcc, 0, v71, vcc
	global_store_dwordx2 v[70:71], v[66:67], off sc1
.LBB0_764:
	v_mov_b32_e32 v68, v77
	v_mov_b32_e32 v84, v97
	v_mov_b32_e32 v80, v73
	v_mov_b32_e32 v88, v93
	v_pk_add_f32 v[66:67], v[68:69], v[84:85]
	v_pk_add_f32 v[70:71], v[80:81], v[88:89]
	v_cvt_pk_bf16_f32 v66, v66, v67
	v_cvt_pk_bf16_f32 v67, v70, v71
	v_add_u32_e32 v70, 0x4c0, v134
	v_ashrrev_i32_e32 v71, 31, v70
	v_lshlrev_b64 v[70:71], 11, v[70:71]
	v_lshl_add_u64 v[70:71], v[132:133], 0, v[70:71]
	s_and_b64 vcc, exec, s[36:37]
	global_store_dwordx2 v[70:71], v[66:67], off sc1
	s_cbranch_vccnz .LBB0_766
	v_pk_add_f32 v[66:67], v[68:69], v[84:85] neg_lo:[0,1] neg_hi:[0,1]
	v_pk_add_f32 v[68:69], v[80:81], v[88:89] neg_lo:[0,1] neg_hi:[0,1]
	v_cvt_pk_bf16_f32 v66, v66, v67
	v_cvt_pk_bf16_f32 v67, v68, v69
	v_sub_u32_e32 v68, 0x6c, v98
	v_ashrrev_i32_e32 v69, 31, v68
	v_lshlrev_b64 v[68:69], 17, v[68:69]
	v_subrev_co_u32_e32 v68, vcc, s30, v68
	s_nop 1
	v_subbrev_co_u32_e32 v69, vcc, 0, v69, vcc
	v_lshl_add_u64 v[68:69], v[132:133], 0, v[68:69]
	v_add_co_u32_e32 v68, vcc, 0x20000, v68
	s_nop 1
	v_addc_co_u32_e32 v69, vcc, 0, v69, vcc
	global_store_dwordx2 v[68:69], v[66:67], off sc1
.LBB0_766:
	v_cvt_pk_bf16_f32 v66, v34, v38
	v_cvt_pk_bf16_f32 v67, v42, v46
	v_cvt_pk_bf16_f32 v38, v36, v40
	v_cvt_pk_bf16_f32 v36, v37, v41
	v_cvt_pk_bf16_f32 v40, v50, v54
	v_cvt_pk_bf16_f32 v41, v58, v62
	v_cvt_pk_bf16_f32 v34, v35, v39
	v_cvt_pk_bf16_f32 v35, v43, v47
	ds_write2_b64 v146, v[66:67], v[40:41] offset1:16
	v_cvt_pk_bf16_f32 v40, v51, v55
	v_cvt_pk_bf16_f32 v41, v59, v63
	v_cvt_pk_bf16_f32 v39, v44, v48
	ds_write2_b64 v146, v[34:35], v[40:41] offset0:34 offset1:50
	v_cvt_pk_bf16_f32 v34, v52, v56
	v_cvt_pk_bf16_f32 v35, v60, v64
	v_cvt_pk_bf16_f32 v37, v45, v49
	ds_write2_b64 v146, v[38:39], v[34:35] offset0:68 offset1:84
	v_cvt_pk_bf16_f32 v34, v53, v57
	v_cvt_pk_bf16_f32 v35, v61, v65
	ds_write2_b64 v146, v[36:37], v[34:35] offset0:102 offset1:118
	v_cvt_pk_bf16_f32 v34, v18, v22
	v_cvt_pk_bf16_f32 v18, v19, v23
	v_cvt_pk_bf16_f32 v19, v27, v31
	v_cvt_pk_bf16_f32 v22, v20, v24
	v_cvt_pk_bf16_f32 v24, v14, v2
	v_cvt_pk_bf16_f32 v2, v15, v3
	v_cvt_pk_bf16_f32 v3, v7, v11
	v_cvt_pk_bf16_f32 v23, v28, v32
	ds_write2_b64 v147, v[18:19], v[2:3] offset0:66 offset1:82
	v_cvt_pk_bf16_f32 v2, v16, v4
	v_cvt_pk_bf16_f32 v3, v8, v12
	v_cvt_pk_bf16_f32 v35, v26, v30
	v_cvt_pk_bf16_f32 v20, v21, v25
	v_cvt_pk_bf16_f32 v21, v29, v33
	v_cvt_pk_bf16_f32 v25, v6, v10
	ds_write2_b64 v147, v[22:23], v[2:3] offset0:100 offset1:116
	v_cvt_pk_bf16_f32 v2, v17, v5
	v_cvt_pk_bf16_f32 v3, v9, v13
	ds_write2_b64 v147, v[34:35], v[24:25] offset0:32 offset1:48
	ds_write2_b64 v147, v[20:21], v[2:3] offset0:134 offset1:150
	v_mul_u32_u24_e32 v68, 0x110, v149
	s_waitcnt lgkmcnt(0)
	v_add_u32_e32 v82, v148, v68
	ds_read_b128 v[2:5], v82
	ds_read_b128 v[6:9], v82 offset:4352
	global_load_dwordx4 v[10:13], v[136:137], off
	global_load_dwordx4 v[14:17], v[136:137], off offset:256
	global_load_dwordx4 v[18:21], v[136:137], off offset:512
	global_load_dwordx4 v[22:25], v[136:137], off offset:768
	s_and_b64 vcc, exec, s[36:37]
	s_waitcnt vmcnt(3) lgkmcnt(1)
	v_mfma_f32_16x16x32_bf16 v[26:29], v[2:5], v[10:13], 0
	s_waitcnt vmcnt(2)
	v_mfma_f32_16x16x32_bf16 v[30:33], v[2:5], v[14:17], 0
	s_waitcnt lgkmcnt(0)
	v_mfma_f32_16x16x32_bf16 v[42:45], v[6:9], v[14:17], 0
	ds_read_b128 v[14:17], v82 offset:64
	ds_read_b128 v[50:53], v82 offset:4416
	global_load_dwordx4 v[54:57], v[136:137], off offset:64
	global_load_dwordx4 v[58:61], v[136:137], off offset:320
	global_load_dwordx4 v[62:65], v[136:137], off offset:576
	global_load_dwordx4 v[66:69], v[136:137], off offset:832
	s_waitcnt vmcnt(5)
	v_mfma_f32_16x16x32_bf16 v[34:37], v[2:5], v[18:21], 0
	s_waitcnt vmcnt(4)
	v_mfma_f32_16x16x32_bf16 v[2:5], v[2:5], v[22:25], 0
	v_mfma_f32_16x16x32_bf16 v[10:13], v[6:9], v[10:13], 0
	v_mfma_f32_16x16x32_bf16 v[46:49], v[6:9], v[18:21], 0
	v_mfma_f32_16x16x32_bf16 v[6:9], v[6:9], v[22:25], 0
	s_waitcnt vmcnt(3) lgkmcnt(1)
	v_mfma_f32_16x16x32_bf16 v[38:41], v[14:17], v[54:57], v[26:29]
	s_waitcnt vmcnt(2)
	v_mfma_f32_16x16x32_bf16 v[18:21], v[14:17], v[58:61], v[30:33]
	s_waitcnt vmcnt(1)
	v_mfma_f32_16x16x32_bf16 v[26:29], v[14:17], v[62:65], v[34:37]
	s_nop 0
	ds_read_b128 v[30:33], v82 offset:128
	s_nop 0
	ds_read_b128 v[34:37], v82 offset:4480
	s_waitcnt vmcnt(0)
	v_mfma_f32_16x16x32_bf16 v[22:25], v[14:17], v[66:69], v[2:5]
	s_waitcnt lgkmcnt(2)
	v_mfma_f32_16x16x32_bf16 v[14:17], v[50:53], v[54:57], v[10:13]
	v_mfma_f32_16x16x32_bf16 v[2:5], v[50:53], v[58:61], v[42:45]
	v_mfma_f32_16x16x32_bf16 v[10:13], v[50:53], v[62:65], v[46:49]
	v_mfma_f32_16x16x32_bf16 v[6:9], v[50:53], v[66:69], v[6:9]
	s_nop 0
	global_load_dwordx4 v[42:45], v[136:137], off offset:128
	global_load_dwordx4 v[46:49], v[136:137], off offset:384
	global_load_dwordx4 v[50:53], v[136:137], off offset:640
	global_load_dwordx4 v[54:57], v[136:137], off offset:896
	s_waitcnt vmcnt(3) lgkmcnt(1)
	v_mfma_f32_16x16x32_bf16 v[58:61], v[30:33], v[42:45], 0
	s_waitcnt vmcnt(2)
	v_mfma_f32_16x16x32_bf16 v[66:69], v[30:33], v[46:49], 0
	s_waitcnt lgkmcnt(0)
	v_mfma_f32_16x16x32_bf16 v[74:77], v[34:37], v[46:49], 0
	ds_read_b128 v[46:49], v82 offset:192
	ds_read_b128 v[82:85], v82 offset:4544
	global_load_dwordx4 v[86:89], v[136:137], off offset:192
	global_load_dwordx4 v[90:93], v[136:137], off offset:448
	global_load_dwordx4 v[94:97], v[136:137], off offset:704
	global_load_dwordx4 v[100:103], v[136:137], off offset:960
	s_waitcnt lgkmcnt(0)
	s_waitcnt vmcnt(5)
	v_mfma_f32_16x16x32_bf16 v[70:73], v[30:33], v[50:53], 0
	s_waitcnt vmcnt(4)
	v_mfma_f32_16x16x32_bf16 v[30:33], v[30:33], v[54:57], 0
	v_mfma_f32_16x16x32_bf16 v[78:81], v[34:37], v[50:53], 0
	s_waitcnt vmcnt(3) lgkmcnt(1)
	v_mfma_f32_16x16x32_bf16 v[62:65], v[46:49], v[86:89], v[58:61]
	s_waitcnt vmcnt(2)
	v_mfma_f32_16x16x32_bf16 v[50:53], v[46:49], v[90:93], v[66:69]
	v_mfma_f32_16x16x32_bf16 v[42:45], v[34:37], v[42:45], 0
	s_nop 1
	v_mov_b32_e32 v66, v38
	v_mov_b32_e32 v67, v18
	s_nop 0
	v_mov_b32_e32 v68, v62
	v_mfma_f32_16x16x32_bf16 v[34:37], v[34:37], v[54:57], 0
	v_mov_b32_e32 v69, v50
	s_waitcnt vmcnt(1)
	v_mfma_f32_16x16x32_bf16 v[58:61], v[46:49], v[94:97], v[70:73]
	s_waitcnt vmcnt(0)
	v_mfma_f32_16x16x32_bf16 v[54:57], v[46:49], v[100:103], v[30:33]
	s_nop 0
	v_add_f32_e64 v70, v66, v68
	v_add_f32_e64 v71, v67, v69
	s_nop 2
	v_mov_b32_e32 v72, v58
	s_waitcnt lgkmcnt(0)
	v_mfma_f32_16x16x32_bf16 v[30:33], v[82:85], v[90:93], v[74:77]
	s_nop 2
	v_cvt_pk_bf16_f32 v74, v70, v71
	v_mov_b32_e32 v70, v26
	v_mov_b32_e32 v71, v22
	v_mov_b32_e32 v73, v54
	v_pk_add_f32 v[76:77], v[70:71], v[72:73]
	v_mfma_f32_16x16x32_bf16 v[46:49], v[82:85], v[86:89], v[42:45]
	v_cvt_pk_bf16_f32 v75, v76, v77
	v_add_u32_e32 v76, 0x800, v134
	v_ashrrev_i32_e32 v77, 31, v76
	v_mfma_f32_16x16x32_bf16 v[42:45], v[82:85], v[94:97], v[78:81]
	v_lshlrev_b64 v[76:77], 11, v[76:77]
	v_lshl_add_u64 v[76:77], v[132:133], 0, v[76:77]
	global_store_dwordx2 v[76:77], v[74:75], off sc1
	v_mfma_f32_16x16x32_bf16 v[34:37], v[82:85], v[100:103], v[34:37]
	s_cbranch_vccnz .LBB0_768
	v_pk_add_f32 v[66:67], v[66:67], v[68:69] neg_lo:[0,1] neg_hi:[0,1]
	v_pk_add_f32 v[68:69], v[70:71], v[72:73] neg_lo:[0,1] neg_hi:[0,1]
	v_cvt_pk_bf16_f32 v66, v66, v67
	v_cvt_pk_bf16_f32 v67, v68, v69
	v_sub_u32_e32 v68, 0x5f, v98
	v_ashrrev_i32_e32 v69, 31, v68
	v_lshlrev_b64 v[68:69], 17, v[68:69]
	v_subrev_co_u32_e32 v68, vcc, s30, v68
	s_nop 1
	v_subbrev_co_u32_e32 v69, vcc, 0, v69, vcc
	v_lshl_add_u64 v[68:69], v[132:133], 0, v[68:69]
	v_add_co_u32_e32 v68, vcc, 0x20000, v68
	s_nop 1
	v_addc_co_u32_e32 v69, vcc, 0, v69, vcc
	global_store_dwordx2 v[68:69], v[66:67], off sc1
.LBB0_768:
	v_mov_b32_e32 v18, v39
	v_mov_b32_e32 v50, v63
	v_pk_add_f32 v[38:39], v[18:19], v[50:51]
	v_mov_b32_e32 v22, v27
	v_mov_b32_e32 v54, v59
	v_cvt_pk_bf16_f32 v26, v38, v39
	v_pk_add_f32 v[38:39], v[22:23], v[54:55]
	s_and_b64 vcc, exec, s[36:37]
	v_cvt_pk_bf16_f32 v27, v38, v39
	v_add_u32_e32 v38, 0x840, v134
	v_ashrrev_i32_e32 v39, 31, v38
	v_lshlrev_b64 v[38:39], 11, v[38:39]
	v_lshl_add_u64 v[38:39], v[132:133], 0, v[38:39]
	global_store_dwordx2 v[38:39], v[26:27], off sc1
	s_cbranch_vccnz .LBB0_770
	v_pk_add_f32 v[18:19], v[18:19], v[50:51] neg_lo:[0,1] neg_hi:[0,1]
	v_pk_add_f32 v[22:23], v[22:23], v[54:55] neg_lo:[0,1] neg_hi:[0,1]
	v_cvt_pk_bf16_f32 v18, v18, v19
	v_cvt_pk_bf16_f32 v19, v22, v23
	v_sub_u32_e32 v22, 0x5e, v98
	v_ashrrev_i32_e32 v23, 31, v22
	v_lshlrev_b64 v[22:23], 17, v[22:23]
	v_subrev_co_u32_e32 v22, vcc, s30, v22
	s_nop 1
	v_subbrev_co_u32_e32 v23, vcc, 0, v23, vcc
	v_lshl_add_u64 v[22:23], v[132:133], 0, v[22:23]
	v_add_co_u32_e32 v22, vcc, 0x20000, v22
	s_nop 1
	v_addc_co_u32_e32 v23, vcc, 0, v23, vcc
	global_store_dwordx2 v[22:23], v[18:19], off sc1
.LBB0_770:
	v_mov_b32_e32 v18, v40
	v_mov_b32_e32 v19, v20
	v_mov_b32_e32 v22, v64
	v_mov_b32_e32 v23, v52
	v_pk_add_f32 v[26:27], v[18:19], v[22:23]
	v_mov_b32_e32 v38, v60
	v_cvt_pk_bf16_f32 v50, v26, v27
	v_mov_b32_e32 v26, v28
	v_mov_b32_e32 v27, v24
	v_mov_b32_e32 v39, v56
	v_pk_add_f32 v[54:55], v[26:27], v[38:39]
	s_and_b64 vcc, exec, s[36:37]
	v_cvt_pk_bf16_f32 v51, v54, v55
	v_add_u32_e32 v54, 0x880, v134
	v_ashrrev_i32_e32 v55, 31, v54
	v_lshlrev_b64 v[54:55], 11, v[54:55]
	v_lshl_add_u64 v[54:55], v[132:133], 0, v[54:55]
	global_store_dwordx2 v[54:55], v[50:51], off sc1
	s_cbranch_vccnz .LBB0_772
	v_pk_add_f32 v[18:19], v[18:19], v[22:23] neg_lo:[0,1] neg_hi:[0,1]
	v_pk_add_f32 v[22:23], v[26:27], v[38:39] neg_lo:[0,1] neg_hi:[0,1]
	v_cvt_pk_bf16_f32 v18, v18, v19
	v_cvt_pk_bf16_f32 v19, v22, v23
	v_sub_u32_e32 v22, 0x5d, v98
	v_ashrrev_i32_e32 v23, 31, v22
	v_lshlrev_b64 v[22:23], 17, v[22:23]
	v_subrev_co_u32_e32 v22, vcc, s30, v22
	s_nop 1
	v_subbrev_co_u32_e32 v23, vcc, 0, v23, vcc
	v_lshl_add_u64 v[22:23], v[132:133], 0, v[22:23]
	v_add_co_u32_e32 v22, vcc, 0x20000, v22
	s_nop 1
	v_addc_co_u32_e32 v23, vcc, 0, v23, vcc
	global_store_dwordx2 v[22:23], v[18:19], off sc1
.LBB0_772:
	v_mov_b32_e32 v20, v41
	v_mov_b32_e32 v52, v65
	v_mov_b32_e32 v24, v29
	v_mov_b32_e32 v56, v61
	v_pk_add_f32 v[18:19], v[20:21], v[52:53]
	v_pk_add_f32 v[22:23], v[24:25], v[56:57]
	v_cvt_pk_bf16_f32 v18, v18, v19
	v_cvt_pk_bf16_f32 v19, v22, v23
	v_add_u32_e32 v22, 0x8c0, v134
	v_ashrrev_i32_e32 v23, 31, v22
	v_lshlrev_b64 v[22:23], 11, v[22:23]
	v_lshl_add_u64 v[22:23], v[132:133], 0, v[22:23]
	s_and_b64 vcc, exec, s[36:37]
	global_store_dwordx2 v[22:23], v[18:19], off sc1
	s_cbranch_vccnz .LBB0_774
	v_pk_add_f32 v[18:19], v[20:21], v[52:53] neg_lo:[0,1] neg_hi:[0,1]
	v_pk_add_f32 v[20:21], v[24:25], v[56:57] neg_lo:[0,1] neg_hi:[0,1]
	v_cvt_pk_bf16_f32 v18, v18, v19
	v_cvt_pk_bf16_f32 v19, v20, v21
	v_sub_u32_e32 v20, 0x5c, v98
	v_ashrrev_i32_e32 v21, 31, v20
	v_lshlrev_b64 v[20:21], 17, v[20:21]
	v_subrev_co_u32_e32 v20, vcc, s30, v20
	s_nop 1
	v_subbrev_co_u32_e32 v21, vcc, 0, v21, vcc
	v_lshl_add_u64 v[20:21], v[132:133], 0, v[20:21]
	v_add_co_u32_e32 v20, vcc, 0x20000, v20
	s_nop 1
	v_addc_co_u32_e32 v21, vcc, 0, v21, vcc
	global_store_dwordx2 v[20:21], v[18:19], off sc1
.LBB0_774:
	v_mov_b32_e32 v18, v14
	v_mov_b32_e32 v19, v2
	v_mov_b32_e32 v20, v46
	v_mov_b32_e32 v21, v30
	v_pk_add_f32 v[22:23], v[18:19], v[20:21]
	v_mov_b32_e32 v24, v42
	v_cvt_pk_bf16_f32 v26, v22, v23
	v_mov_b32_e32 v22, v10
	v_mov_b32_e32 v23, v6
	v_mov_b32_e32 v25, v34
	v_pk_add_f32 v[28:29], v[22:23], v[24:25]
	s_and_b64 vcc, exec, s[36:37]
	v_cvt_pk_bf16_f32 v27, v28, v29
	v_add_u32_e32 v28, 0xc00, v134
	v_ashrrev_i32_e32 v29, 31, v28
	v_lshlrev_b64 v[28:29], 11, v[28:29]
	v_lshl_add_u64 v[28:29], v[132:133], 0, v[28:29]
	global_store_dwordx2 v[28:29], v[26:27], off sc1
	s_cbranch_vccnz .LBB0_776
	v_pk_add_f32 v[18:19], v[18:19], v[20:21] neg_lo:[0,1] neg_hi:[0,1]
	v_pk_add_f32 v[20:21], v[22:23], v[24:25] neg_lo:[0,1] neg_hi:[0,1]
	v_cvt_pk_bf16_f32 v18, v18, v19
	v_cvt_pk_bf16_f32 v19, v20, v21
	v_sub_u32_e32 v20, 0x4f, v98
	v_ashrrev_i32_e32 v21, 31, v20
	v_lshlrev_b64 v[20:21], 17, v[20:21]
	v_subrev_co_u32_e32 v20, vcc, s30, v20
	s_nop 1
	v_subbrev_co_u32_e32 v21, vcc, 0, v21, vcc
	v_lshl_add_u64 v[20:21], v[132:133], 0, v[20:21]
	v_add_co_u32_e32 v20, vcc, 0x20000, v20
	s_nop 1
	v_addc_co_u32_e32 v21, vcc, 0, v21, vcc
	global_store_dwordx2 v[20:21], v[18:19], off sc1
.LBB0_776:
	v_mov_b32_e32 v2, v15
	v_mov_b32_e32 v30, v47
	v_pk_add_f32 v[14:15], v[2:3], v[30:31]
	v_mov_b32_e32 v6, v11
	v_mov_b32_e32 v34, v43
	v_cvt_pk_bf16_f32 v10, v14, v15
	v_pk_add_f32 v[14:15], v[6:7], v[34:35]
	s_and_b64 vcc, exec, s[36:37]
	v_cvt_pk_bf16_f32 v11, v14, v15
	v_add_u32_e32 v14, 0xc40, v134
	v_ashrrev_i32_e32 v15, 31, v14
	v_lshlrev_b64 v[14:15], 11, v[14:15]
	v_lshl_add_u64 v[14:15], v[132:133], 0, v[14:15]
	global_store_dwordx2 v[14:15], v[10:11], off sc1
	s_cbranch_vccnz .LBB0_778
	v_pk_add_f32 v[2:3], v[2:3], v[30:31] neg_lo:[0,1] neg_hi:[0,1]
	v_pk_add_f32 v[6:7], v[6:7], v[34:35] neg_lo:[0,1] neg_hi:[0,1]
	v_cvt_pk_bf16_f32 v2, v2, v3
	v_cvt_pk_bf16_f32 v3, v6, v7
	v_sub_u32_e32 v6, 0x4e, v98
	v_ashrrev_i32_e32 v7, 31, v6
	v_lshlrev_b64 v[6:7], 17, v[6:7]
	v_subrev_co_u32_e32 v6, vcc, s30, v6
	s_nop 1
	v_subbrev_co_u32_e32 v7, vcc, 0, v7, vcc
	v_lshl_add_u64 v[6:7], v[132:133], 0, v[6:7]
	v_add_co_u32_e32 v6, vcc, 0x20000, v6
	s_nop 1
	v_addc_co_u32_e32 v7, vcc, 0, v7, vcc
	global_store_dwordx2 v[6:7], v[2:3], off sc1
.LBB0_778:
	v_mov_b32_e32 v2, v16
	v_mov_b32_e32 v3, v4
	v_mov_b32_e32 v6, v48
	v_mov_b32_e32 v7, v32
	v_pk_add_f32 v[10:11], v[2:3], v[6:7]
	v_mov_b32_e32 v14, v44
	v_cvt_pk_bf16_f32 v18, v10, v11
	v_mov_b32_e32 v10, v12
	v_mov_b32_e32 v11, v8
	v_mov_b32_e32 v15, v36
	v_pk_add_f32 v[20:21], v[10:11], v[14:15]
	s_and_b64 vcc, exec, s[36:37]
	v_cvt_pk_bf16_f32 v19, v20, v21
	v_add_u32_e32 v20, 0xc80, v134
	v_ashrrev_i32_e32 v21, 31, v20
	v_lshlrev_b64 v[20:21], 11, v[20:21]
	v_lshl_add_u64 v[20:21], v[132:133], 0, v[20:21]
	global_store_dwordx2 v[20:21], v[18:19], off sc1
	s_cbranch_vccnz .LBB0_780
	v_pk_add_f32 v[2:3], v[2:3], v[6:7] neg_lo:[0,1] neg_hi:[0,1]
	v_pk_add_f32 v[6:7], v[10:11], v[14:15] neg_lo:[0,1] neg_hi:[0,1]
	v_cvt_pk_bf16_f32 v2, v2, v3
	v_cvt_pk_bf16_f32 v3, v6, v7
	v_sub_u32_e32 v6, 0x4d, v98
	v_ashrrev_i32_e32 v7, 31, v6
	v_lshlrev_b64 v[6:7], 17, v[6:7]
	v_subrev_co_u32_e32 v6, vcc, s30, v6
	s_nop 1
	v_subbrev_co_u32_e32 v7, vcc, 0, v7, vcc
	v_lshl_add_u64 v[6:7], v[132:133], 0, v[6:7]
	v_add_co_u32_e32 v6, vcc, 0x20000, v6
	s_nop 1
	v_addc_co_u32_e32 v7, vcc, 0, v7, vcc
	global_store_dwordx2 v[6:7], v[2:3], off sc1
.LBB0_780:
	v_mov_b32_e32 v4, v17
	v_mov_b32_e32 v32, v49
	v_mov_b32_e32 v8, v13
	v_mov_b32_e32 v36, v45
	v_pk_add_f32 v[2:3], v[4:5], v[32:33]
	v_pk_add_f32 v[6:7], v[8:9], v[36:37]
	v_cvt_pk_bf16_f32 v2, v2, v3
	v_cvt_pk_bf16_f32 v3, v6, v7
	v_add_u32_e32 v6, 0xcc0, v134
	v_ashrrev_i32_e32 v7, 31, v6
	v_lshlrev_b64 v[6:7], 11, v[6:7]
	v_lshl_add_u64 v[6:7], v[132:133], 0, v[6:7]
	s_and_b64 vcc, exec, s[36:37]
	global_store_dwordx2 v[6:7], v[2:3], off sc1
	s_cbranch_vccnz .LBB0_782
	v_pk_add_f32 v[2:3], v[4:5], v[32:33] neg_lo:[0,1] neg_hi:[0,1]
	v_pk_add_f32 v[4:5], v[8:9], v[36:37] neg_lo:[0,1] neg_hi:[0,1]
	v_cvt_pk_bf16_f32 v2, v2, v3
	v_cvt_pk_bf16_f32 v3, v4, v5
	v_sub_u32_e32 v6, 0x4c, v98
	s_mov_b64 s[14:15], -1
.LBB0_782:
	s_and_b64 vcc, exec, s[14:15]
	s_cbranch_vccz .LBB0_784
	s_waitcnt vmcnt(0)
	v_ashrrev_i32_e32 v7, 31, v6
	v_lshlrev_b64 v[4:5], 17, v[6:7]
	v_subrev_co_u32_e32 v4, vcc, s30, v4
	s_nop 1
	v_subbrev_co_u32_e32 v5, vcc, 0, v5, vcc
	v_lshl_add_u64 v[4:5], v[132:133], 0, v[4:5]
	v_add_co_u32_e32 v4, vcc, 0x20000, v4
	s_nop 1
	v_addc_co_u32_e32 v5, vcc, 0, v5, vcc
	global_store_dwordx2 v[4:5], v[2:3], off sc1
